# HGRN items: the 2x32 serialised two-byte row loads issued up front (both directions) instead of one round trip each; skip unused grid.sync protocol
# speedup vs baseline: 1.1698x; 1.0632x over previous
.LBB0_5:
	s_or_b64 exec, exec, s[2:3]
	v_lshrrev_b32_e32 v1, 20, v0
	v_lshrrev_b32_e32 v0, 10, v0
	v_or_b32_e32 v0, v0, v1
	s_movk_i32 s2, 0x3ff
	v_and_or_b32 v0, v0, s2, v222
	v_cmp_eq_u32_e32 vcc, 0, v0
	s_barrier
	s_and_saveexec_b64 s[2:3], vcc
	s_branch .LBB0_15
	buffer_wbl2 sc1
	s_waitcnt vmcnt(0)
	s_load_dwordx2 s[4:5], s[4:5], 0x58
	v_mov_b32_e32 v2, 0
	s_mov_b64 s[6:7], exec
	v_mbcnt_lo_u32_b32 v1, s6, 0
	v_mbcnt_hi_u32_b32 v1, s7, v1
	s_waitcnt lgkmcnt(0)
	global_load_dword v0, v2, s[4:5] offset:40
	v_cmp_eq_u32_e32 vcc, 0, v1
	s_and_saveexec_b64 s[8:9], vcc
	s_cbranch_execz .LBB0_8
	s_bcnt1_i32_b64 s6, s[6:7]
	v_mov_b32_e32 v3, s6
	global_atomic_add v3, v2, v3, s[4:5] offset:32 sc0

.LBB0_548:
	s_or_b64 exec, exec, s[0:1]
	s_waitcnt lgkmcnt(0)
	s_barrier
	ds_read_b32 v0, v3 offset:16
	s_movk_i32 s0, 0x10ff
	s_waitcnt lgkmcnt(0)
	v_cmp_lt_i32_e32 vcc, s0, v0
	v_readfirstlane_b32 s6, v0
	s_mov_b64 s[0:1], -1
	s_cbranch_vccnz .LBB0_543
	s_cmpk_gt_i32 s6, 0x43f
	s_cbranch_scc0 .LBB0_760
	s_cmpk_gt_u32 s6, 0x65f
	s_cbranch_scc0 .LBB0_719
	s_cmpk_gt_u32 s6, 0x87f
	s_cbranch_scc0 .LBB0_561
	s_add_i32 s0, s6, 0xf780
	s_and_b32 s1, s0, 0xffff
	s_mul_i32 s5, s1, 0xf0f1
	s_lshr_b32 s7, s5, 22
	s_mulk_i32 s7, 0x44
	s_sub_i32 s0, s0, s7
	s_lshr_b32 s4, s5, 24
	s_and_b32 s7, s0, 0xffff
	s_mul_i32 s1, s4, 0xee0000
	s_mul_i32 s0, s7, 0x38000
	s_add_i32 s22, s1, s0
	v_mov_b32_e32 v0, v222
	s_lshl_b64 s[0:1], s[22:23], 1
	s_add_u32 s0, s24, s0
	s_addc_u32 s1, s25, s1
	s_bfe_u32 s5, s5, 0x20016
	v_mov_b32_e32 v0, v222
	s_lshl_b32 s10, s5, 6
	v_and_b32_e32 v6, 63, v0
	v_ashrrev_i32_e32 v4, 6, v0
	v_or_b32_e32 v1, s10, v6
	v_lshlrev_b32_e32 v24, 4, v4
	v_lshlrev_b32_e32 v2, 1, v1
	v_lshl_add_u64 v[8:9], s[0:1], 0, v[2:3]
	v_or_b32_e32 v2, 2, v24
	v_or_b32_e32 v1, 1, v24
	v_mad_i64_i32 v[14:15], s[12:13], v2, s48, v[8:9]
	v_or_b32_e32 v2, 3, v24
	v_mad_i64_i32 v[10:11], s[12:13], v24, s48, v[8:9]
	v_mad_i64_i32 v[12:13], s[12:13], v1, s48, v[8:9]
	v_mad_i64_i32 v[16:17], s[12:13], v2, s48, v[8:9]
	s_barrier
	v_mad_i64_i32 v[128:129], s[12:13], v24, s48, v[8:9]
	global_load_ushort v96, v[128:129], off offset:1024
	global_load_ushort v80, v[128:129], off offset:2560
	v_or_b32_e32 v137, 1, v24
	v_mad_i64_i32 v[130:131], s[12:13], v137, s48, v[8:9]
	global_load_ushort v97, v[130:131], off offset:1024
	global_load_ushort v81, v[130:131], off offset:2560
	v_or_b32_e32 v138, 2, v24
	v_mad_i64_i32 v[132:133], s[12:13], v138, s48, v[8:9]
	global_load_ushort v98, v[132:133], off offset:1024
	global_load_ushort v82, v[132:133], off offset:2560
	v_or_b32_e32 v139, 3, v24
	v_mad_i64_i32 v[134:135], s[12:13], v139, s48, v[8:9]
	global_load_ushort v99, v[134:135], off offset:1024
	global_load_ushort v83, v[134:135], off offset:2560
	v_or_b32_e32 v136, 4, v24
	v_mad_i64_i32 v[128:129], s[12:13], v136, s48, v[8:9]
	global_load_ushort v100, v[128:129], off offset:1024
	global_load_ushort v84, v[128:129], off offset:2560
	v_or_b32_e32 v137, 5, v24
	v_mad_i64_i32 v[130:131], s[12:13], v137, s48, v[8:9]
	global_load_ushort v101, v[130:131], off offset:1024
	global_load_ushort v85, v[130:131], off offset:2560
	v_or_b32_e32 v138, 6, v24
	v_mad_i64_i32 v[132:133], s[12:13], v138, s48, v[8:9]
	global_load_ushort v102, v[132:133], off offset:1024
	global_load_ushort v86, v[132:133], off offset:2560
	v_or_b32_e32 v139, 7, v24
	v_mad_i64_i32 v[134:135], s[12:13], v139, s48, v[8:9]
	global_load_ushort v103, v[134:135], off offset:1024
	global_load_ushort v87, v[134:135], off offset:2560
	v_or_b32_e32 v136, 8, v24
	v_mad_i64_i32 v[128:129], s[12:13], v136, s48, v[8:9]
	global_load_ushort v104, v[128:129], off offset:1024
	global_load_ushort v88, v[128:129], off offset:2560
	v_or_b32_e32 v137, 9, v24
	v_mad_i64_i32 v[130:131], s[12:13], v137, s48, v[8:9]
	global_load_ushort v105, v[130:131], off offset:1024
	global_load_ushort v89, v[130:131], off offset:2560
	v_or_b32_e32 v138, 10, v24
	v_mad_i64_i32 v[132:133], s[12:13], v138, s48, v[8:9]
	global_load_ushort v106, v[132:133], off offset:1024
	global_load_ushort v90, v[132:133], off offset:2560
	v_or_b32_e32 v139, 11, v24
	v_mad_i64_i32 v[134:135], s[12:13], v139, s48, v[8:9]
	global_load_ushort v107, v[134:135], off offset:1024
	global_load_ushort v91, v[134:135], off offset:2560
	v_or_b32_e32 v136, 12, v24
	v_mad_i64_i32 v[128:129], s[12:13], v136, s48, v[8:9]
	global_load_ushort v108, v[128:129], off offset:1024
	global_load_ushort v92, v[128:129], off offset:2560
	v_or_b32_e32 v137, 13, v24
	v_mad_i64_i32 v[130:131], s[12:13], v137, s48, v[8:9]
	global_load_ushort v109, v[130:131], off offset:1024
	global_load_ushort v93, v[130:131], off offset:2560
	v_or_b32_e32 v138, 14, v24
	v_mad_i64_i32 v[132:133], s[12:13], v138, s48, v[8:9]
	global_load_ushort v110, v[132:133], off offset:1024
	global_load_ushort v94, v[132:133], off offset:2560
	v_or_b32_e32 v139, 15, v24
	v_mad_i64_i32 v[134:135], s[12:13], v139, s48, v[8:9]
	global_load_ushort v111, v[134:135], off offset:1024
	global_load_ushort v95, v[134:135], off offset:2560
	global_load_ushort v2, v[10:11], off offset:2048
	global_load_ushort v5, v[12:13], off offset:2048
	global_load_ushort v7, v[14:15], off offset:2048
	global_load_ushort v18, v[16:17], off offset:2048
	global_load_ushort v19, v[16:17], off offset:1024
	global_load_ushort v20, v[14:15], off offset:1024
	global_load_ushort v21, v[12:13], off offset:1024
	global_load_ushort v22, v[10:11], off offset:1024
	v_or_b32_e32 v10, 4, v24
	v_or_b32_e32 v12, 5, v24
	v_or_b32_e32 v14, 6, v24
	v_or_b32_e32 v16, 7, v24
	v_mad_i64_i32 v[10:11], s[12:13], v10, s48, v[8:9]
	v_mad_i64_i32 v[12:13], s[12:13], v12, s48, v[8:9]
	v_mad_i64_i32 v[14:15], s[12:13], v14, s48, v[8:9]
	v_mad_i64_i32 v[16:17], s[12:13], v16, s48, v[8:9]
	global_load_ushort v23, v[10:11], off offset:2048
	global_load_ushort v25, v[12:13], off offset:2048
	global_load_ushort v26, v[14:15], off offset:2048
	global_load_ushort v27, v[16:17], off offset:2048
	global_load_ushort v28, v[16:17], off offset:1024
	global_load_ushort v29, v[14:15], off offset:1024
	global_load_ushort v30, v[12:13], off offset:1024
	global_load_ushort v31, v[10:11], off offset:1024
	v_or_b32_e32 v10, 8, v24
	v_or_b32_e32 v12, 9, v24
	v_or_b32_e32 v14, 10, v24
	v_or_b32_e32 v16, 11, v24
	v_mad_i64_i32 v[10:11], s[12:13], v10, s48, v[8:9]
	v_mad_i64_i32 v[12:13], s[12:13], v12, s48, v[8:9]
	v_mad_i64_i32 v[14:15], s[12:13], v14, s48, v[8:9]
	v_mad_i64_i32 v[16:17], s[12:13], v16, s48, v[8:9]
	global_load_ushort v32, v[10:11], off offset:2048
	global_load_ushort v33, v[12:13], off offset:2048
	global_load_ushort v34, v[14:15], off offset:2048
	global_load_ushort v35, v[16:17], off offset:2048
	s_nop 0
	global_load_ushort v16, v[16:17], off offset:1024
	s_nop 0
	global_load_ushort v17, v[14:15], off offset:1024
	global_load_ushort v36, v[12:13], off offset:1024
	global_load_ushort v37, v[10:11], off offset:1024
	v_or_b32_e32 v10, 12, v24
	v_or_b32_e32 v12, 13, v24
	v_or_b32_e32 v14, 14, v24
	v_or_b32_e32 v38, 15, v24
	v_mad_i64_i32 v[10:11], s[12:13], v10, s48, v[8:9]
	v_mad_i64_i32 v[12:13], s[12:13], v12, s48, v[8:9]
	v_mad_i64_i32 v[14:15], s[12:13], v14, s48, v[8:9]
	v_mad_i64_i32 v[8:9], s[12:13], v38, s48, v[8:9]
	global_load_ushort v38, v[10:11], off offset:2048
	global_load_ushort v39, v[12:13], off offset:1024
	global_load_ushort v40, v[8:9], off offset:2048
	global_load_ushort v41, v[14:15], off offset:2048
	s_nop 0
	global_load_ushort v12, v[12:13], off offset:2048
	s_nop 0
	global_load_ushort v10, v[10:11], off offset:1024
	s_nop 0
	global_load_ushort v11, v[14:15], off offset:1024
	s_nop 0
	global_load_ushort v8, v[8:9], off offset:1024
	s_movk_i32 s8, 0x500
	s_waitcnt vmcnt(43)
	v_mul_lo_u32 v55, v4, s8
	v_or_b32_e32 v55, v55, v6
	s_movk_i32 s8, 0x50
	s_lshl_b32 s22, s5, 7
	s_lshl_b32 s4, s4, 3
	s_lshl_b32 s5, s5, 1
	s_or_b32 s11, s5, s4
	v_cmp_lt_i32_e32 vcc, 63, v0
	s_waitcnt vmcnt(31)
	v_lshlrev_b32_e32 v2, 16, v2
	s_waitcnt vmcnt(30)
	v_lshlrev_b32_e32 v5, 16, v5
	s_waitcnt vmcnt(29)
	v_lshlrev_b32_e32 v14, 16, v7
	v_add_f32_e32 v7, 0, v2
	s_waitcnt vmcnt(28)
	v_lshlrev_b32_e32 v18, 16, v18
	s_waitcnt vmcnt(26)
	v_lshlrev_b32_e32 v15, 16, v20
	s_waitcnt vmcnt(25)
	v_lshlrev_b32_e32 v13, 16, v21
	s_waitcnt vmcnt(24)
	v_lshlrev_b32_e32 v9, 16, v22
	v_mul_f32_e32 v2, 0x3fb8aa3b, v2
	v_mul_f32_e32 v54, 0x3fb8aa3b, v7
	v_exp_f32_e32 v2, v2
	v_exp_f32_e32 v54, v54
	v_lshlrev_b32_e32 v19, 16, v19
	s_waitcnt vmcnt(23)
	v_lshlrev_b32_e32 v20, 16, v23
	s_waitcnt vmcnt(22)
	v_lshlrev_b32_e32 v22, 16, v25
	s_waitcnt vmcnt(21)
	v_lshlrev_b32_e32 v25, 16, v26
	s_waitcnt vmcnt(20)
	v_lshlrev_b32_e32 v27, 16, v27
	v_sub_f32_e32 v2, 1.0, v2
	s_waitcnt vmcnt(18)
	v_lshlrev_b32_e32 v26, 16, v29
	s_waitcnt vmcnt(17)
	v_lshlrev_b32_e32 v23, 16, v30
	s_waitcnt vmcnt(16)
	v_lshlrev_b32_e32 v21, 16, v31
	v_mul_f32_e32 v9, v54, v9
	v_lshl_add_u32 v54, v55, 1, 32
	v_cvt_pk_bf16_f32 v9, v9, s0
	ds_write_b16 v54, v9
	v_lshlrev_b32_e32 v28, 16, v28
	s_waitcnt vmcnt(15)
	v_lshlrev_b32_e32 v29, 16, v32
	s_waitcnt vmcnt(14)
	v_lshlrev_b32_e32 v31, 16, v33
	s_waitcnt vmcnt(13)
	v_lshlrev_b32_e32 v33, 16, v34
	s_waitcnt vmcnt(12)
	v_lshlrev_b32_e32 v34, 16, v35
	s_waitcnt vmcnt(11)
	v_lshlrev_b32_e32 v16, 16, v16
	s_waitcnt vmcnt(10)
	v_lshlrev_b32_e32 v17, 16, v17
	s_waitcnt vmcnt(9)
	v_lshlrev_b32_e32 v32, 16, v36
	s_waitcnt vmcnt(8)
	v_lshlrev_b32_e32 v30, 16, v37
	s_waitcnt vmcnt(7)
	v_lshlrev_b32_e32 v35, 16, v38
	s_waitcnt vmcnt(6)
	v_lshlrev_b32_e32 v38, 16, v39
	s_waitcnt vmcnt(5)
	v_lshlrev_b32_e32 v40, 16, v40
	s_waitcnt vmcnt(4)
	v_lshlrev_b32_e32 v39, 16, v41
	s_waitcnt vmcnt(3)
	v_lshlrev_b32_e32 v37, 16, v12
	s_waitcnt vmcnt(2)
	v_lshlrev_b32_e32 v36, 16, v10
	s_waitcnt vmcnt(1)
	v_lshlrev_b32_e32 v41, 16, v11
	s_waitcnt vmcnt(0)
	v_lshlrev_b32_e32 v42, 16, v8
	v_add_f32_e32 v8, v7, v5
	v_add_f32_e32 v10, v8, v14
	v_add_f32_e32 v11, v10, v18
	v_add_f32_e32 v12, v11, v20
	v_add_f32_e32 v43, v12, v22
	v_add_f32_e32 v44, v43, v25
	v_add_f32_e32 v45, v44, v27
	v_add_f32_e32 v46, v45, v29
	v_add_f32_e32 v47, v46, v31
	v_add_f32_e32 v48, v47, v33
	v_add_f32_e32 v49, v48, v34
	v_add_f32_e32 v50, v49, v35
	v_add_f32_e32 v51, v50, v37
	v_add_f32_e32 v52, v51, v39
	v_add_f32_e32 v53, v52, v40
	v_sub_f32_e32 v7, v53, v7
	v_mul_f32_e32 v7, 0x3fb8aa3b, v7
	v_exp_f32_e32 v7, v7
	v_mul_f32_e32 v5, 0x3fb8aa3b, v5
	v_exp_f32_e32 v5, v5
	v_mul_f32_e32 v2, v2, v7
	v_cvt_pk_bf16_f32 v2, v2, s0
	ds_write_b16 v54, v2 offset:20480
	v_mul_f32_e32 v2, 0x3fb8aa3b, v8
	v_exp_f32_e32 v2, v2
	v_mad_u64_u32 v[6:7], s[12:13], v1, s8, v[6:7]
	v_sub_f32_e32 v5, 1.0, v5
	v_mul_f32_e32 v1, v2, v13
	v_sub_f32_e32 v2, v53, v8
	v_mul_f32_e32 v2, 0x3fb8aa3b, v2
	v_exp_f32_e32 v2, v2
	v_cvt_pk_bf16_f32 v1, v1, s0
	v_lshl_add_u32 v54, v6, 1, 32
	ds_write_b16 v54, v1
	v_mul_f32_e32 v1, v5, v2
	v_mul_f32_e32 v2, 0x3fb8aa3b, v14
	v_mul_f32_e32 v5, 0x3fb8aa3b, v10
	v_exp_f32_e32 v2, v2
	v_exp_f32_e32 v5, v5
	v_cvt_pk_bf16_f32 v1, v1, s0
	ds_write_b16 v54, v1 offset:20480
	v_sub_f32_e32 v1, 1.0, v2
	v_mul_f32_e32 v2, v5, v15
	v_sub_f32_e32 v5, v53, v10
	v_mul_f32_e32 v5, 0x3fb8aa3b, v5
	v_cvt_pk_bf16_f32 v2, v2, s0
	v_exp_f32_e32 v5, v5
	ds_write_b16 v54, v2 offset:160
	v_mul_f32_e32 v2, 0x3fb8aa3b, v18
	v_exp_f32_e32 v2, v2
	v_mul_f32_e32 v1, v1, v5
	v_cvt_pk_bf16_f32 v1, v1, s0
	ds_write_b16 v54, v1 offset:20640
	v_sub_f32_e32 v1, 1.0, v2
	v_mul_f32_e32 v2, 0x3fb8aa3b, v11
	v_exp_f32_e32 v2, v2
	v_sub_f32_e32 v5, v53, v11
	v_mul_f32_e32 v5, 0x3fb8aa3b, v5
	v_exp_f32_e32 v5, v5
	v_mul_f32_e32 v2, v2, v19
	v_cvt_pk_bf16_f32 v2, v2, s0
	ds_write_b16 v54, v2 offset:320
	v_mul_f32_e32 v1, v1, v5
	v_mul_f32_e32 v2, 0x3fb8aa3b, v20
	v_mul_f32_e32 v5, 0x3fb8aa3b, v12
	v_exp_f32_e32 v2, v2
	v_exp_f32_e32 v5, v5
	v_cvt_pk_bf16_f32 v1, v1, s0
	ds_write_b16 v54, v1 offset:20800
	v_sub_f32_e32 v1, 1.0, v2
	v_mul_f32_e32 v2, v5, v21
	v_sub_f32_e32 v5, v53, v12
	v_mul_f32_e32 v5, 0x3fb8aa3b, v5
	v_cvt_pk_bf16_f32 v2, v2, s0
	v_exp_f32_e32 v5, v5
	ds_write_b16 v54, v2 offset:480
	v_mul_f32_e32 v2, 0x3fb8aa3b, v22
	v_exp_f32_e32 v2, v2
	v_mul_f32_e32 v1, v1, v5
	v_cvt_pk_bf16_f32 v1, v1, s0
	ds_write_b16 v54, v1 offset:20960
	v_sub_f32_e32 v1, 1.0, v2
	v_mul_f32_e32 v2, 0x3fb8aa3b, v43
	v_exp_f32_e32 v2, v2
	v_sub_f32_e32 v5, v53, v43
	v_mul_f32_e32 v5, 0x3fb8aa3b, v5
	v_exp_f32_e32 v5, v5
	v_mul_f32_e32 v2, v2, v23
	v_cvt_pk_bf16_f32 v2, v2, s0
	ds_write_b16 v54, v2 offset:640
	v_mul_f32_e32 v1, v1, v5
	v_mul_f32_e32 v2, 0x3fb8aa3b, v25
	v_mul_f32_e32 v5, 0x3fb8aa3b, v44
	v_exp_f32_e32 v2, v2
	v_exp_f32_e32 v5, v5
	v_cvt_pk_bf16_f32 v1, v1, s0
	ds_write_b16 v54, v1 offset:21120
	v_sub_f32_e32 v1, 1.0, v2
	v_mul_f32_e32 v2, v5, v26
	v_sub_f32_e32 v5, v53, v44
	v_mul_f32_e32 v5, 0x3fb8aa3b, v5
	v_cvt_pk_bf16_f32 v2, v2, s0
	v_exp_f32_e32 v5, v5
	ds_write_b16 v54, v2 offset:800
	v_mul_f32_e32 v2, 0x3fb8aa3b, v27
	v_exp_f32_e32 v2, v2
	v_mul_f32_e32 v1, v1, v5
	v_cvt_pk_bf16_f32 v1, v1, s0
	ds_write_b16 v54, v1 offset:21280
	v_sub_f32_e32 v1, 1.0, v2
	v_mul_f32_e32 v2, 0x3fb8aa3b, v45
	v_exp_f32_e32 v2, v2
	v_sub_f32_e32 v5, v53, v45
	v_mul_f32_e32 v5, 0x3fb8aa3b, v5
	v_exp_f32_e32 v5, v5
	v_mul_f32_e32 v2, v2, v28
	v_cvt_pk_bf16_f32 v2, v2, s0
	ds_write_b16 v54, v2 offset:960
	v_mul_f32_e32 v1, v1, v5
	v_mul_f32_e32 v2, 0x3fb8aa3b, v29
	v_mul_f32_e32 v5, 0x3fb8aa3b, v46
	v_exp_f32_e32 v2, v2
	v_exp_f32_e32 v5, v5
	v_cvt_pk_bf16_f32 v1, v1, s0
	ds_write_b16 v54, v1 offset:21440
	v_sub_f32_e32 v1, 1.0, v2
	v_mul_f32_e32 v2, v5, v30
	v_sub_f32_e32 v5, v53, v46
	v_mul_f32_e32 v5, 0x3fb8aa3b, v5
	v_cvt_pk_bf16_f32 v2, v2, s0
	v_exp_f32_e32 v5, v5
	ds_write_b16 v54, v2 offset:1120
	v_mul_f32_e32 v2, 0x3fb8aa3b, v31
	v_exp_f32_e32 v2, v2
	v_mul_f32_e32 v1, v1, v5
	v_cvt_pk_bf16_f32 v1, v1, s0
	ds_write_b16 v54, v1 offset:21600
	v_sub_f32_e32 v1, 1.0, v2
	v_mul_f32_e32 v2, 0x3fb8aa3b, v47
	v_exp_f32_e32 v2, v2
	v_sub_f32_e32 v5, v53, v47
	v_mul_f32_e32 v5, 0x3fb8aa3b, v5
	v_exp_f32_e32 v5, v5
	v_mul_f32_e32 v2, v2, v32
	v_cvt_pk_bf16_f32 v2, v2, s0
	ds_write_b16 v54, v2 offset:1280
	v_mul_f32_e32 v1, v1, v5
	v_mul_f32_e32 v2, 0x3fb8aa3b, v33
	v_mul_f32_e32 v5, 0x3fb8aa3b, v48
	v_exp_f32_e32 v2, v2
	v_exp_f32_e32 v5, v5
	v_cvt_pk_bf16_f32 v1, v1, s0
	ds_write_b16 v54, v1 offset:21760
	v_sub_f32_e32 v1, 1.0, v2
	v_mul_f32_e32 v2, v5, v17
	v_cvt_pk_bf16_f32 v2, v2, s0
	ds_write_b16 v54, v2 offset:1440
	v_sub_f32_e32 v2, v53, v48
	v_mul_f32_e32 v2, 0x3fb8aa3b, v2
	v_exp_f32_e32 v5, v2
	v_mul_f32_e32 v2, 0x3fb8aa3b, v34
	v_ashrrev_i32_e32 v15, 3, v0
	v_mov_b64_e32 v[10:11], s[0:1]
	v_exp_f32_e32 v14, v2
	v_lshlrev_b32_e32 v2, 4, v0
	v_mad_i64_i32 v[6:7], s[12:13], v15, s48, v[10:11]
	v_add_u32_e32 v12, 0x100, v0
	v_and_b32_e32 v2, 0x70, v2
	v_lshl_add_u64 v[6:7], v[6:7], 0, s[22:23]
	v_ashrrev_i32_e32 v17, 3, v12
	v_lshl_add_u64 v[6:7], v[6:7], 0, v[2:3]
	v_mad_i64_i32 v[10:11], s[12:13], v17, s48, v[10:11]
	global_load_dwordx4 v[6:9], v[6:7], off offset:1536
	v_lshl_add_u64 v[10:11], v[10:11], 0, s[22:23]
	v_lshl_add_u64 v[10:11], v[10:11], 0, v[2:3]
	global_load_dwordx4 v[10:13], v[10:11], off offset:1536
	v_mul_f32_e32 v1, v1, v5
	v_cvt_pk_bf16_f32 v1, v1, s0
	v_mul_f32_e32 v5, 0x3fb8aa3b, v49
	ds_write_b16 v54, v1 offset:21920
	v_sub_f32_e32 v1, 1.0, v14
	v_exp_f32_e32 v5, v5
	v_sub_f32_e32 v14, v53, v49
	v_mul_f32_e32 v14, 0x3fb8aa3b, v14
	v_exp_f32_e32 v14, v14
	v_mul_f32_e32 v5, v5, v16
	v_cvt_pk_bf16_f32 v5, v5, s0
	ds_write_b16 v54, v5 offset:1600
	v_mul_f32_e32 v1, v1, v14
	v_mul_f32_e32 v5, 0x3fb8aa3b, v35
	v_mul_f32_e32 v14, 0x3fb8aa3b, v50
	v_exp_f32_e32 v5, v5
	v_exp_f32_e32 v14, v14
	v_cvt_pk_bf16_f32 v1, v1, s0
	ds_write_b16 v54, v1 offset:22080
	v_sub_f32_e32 v1, 1.0, v5
	v_mul_f32_e32 v5, v14, v36
	v_sub_f32_e32 v14, v53, v50
	v_mul_f32_e32 v14, 0x3fb8aa3b, v14
	v_cvt_pk_bf16_f32 v5, v5, s0
	v_exp_f32_e32 v14, v14
	ds_write_b16 v54, v5 offset:1760
	v_mul_f32_e32 v5, 0x3fb8aa3b, v37
	v_exp_f32_e32 v5, v5
	v_mul_f32_e32 v1, v1, v14
	v_cvt_pk_bf16_f32 v1, v1, s0
	ds_write_b16 v54, v1 offset:22240
	v_sub_f32_e32 v1, 1.0, v5
	v_mul_f32_e32 v5, 0x3fb8aa3b, v51
	v_exp_f32_e32 v5, v5
	v_sub_f32_e32 v14, v53, v51
	v_mul_f32_e32 v14, 0x3fb8aa3b, v14
	v_exp_f32_e32 v14, v14
	v_mul_f32_e32 v5, v5, v38
	v_cvt_pk_bf16_f32 v5, v5, s0
	ds_write_b16 v54, v5 offset:1920
	v_mul_f32_e32 v1, v1, v14
	v_mul_f32_e32 v5, 0x3fb8aa3b, v39
	v_mul_f32_e32 v14, 0x3fb8aa3b, v52
	v_exp_f32_e32 v5, v5
	v_exp_f32_e32 v14, v14
	v_cvt_pk_bf16_f32 v1, v1, s0
	ds_write_b16 v54, v1 offset:22400
	v_sub_f32_e32 v1, 1.0, v5
	v_mul_f32_e32 v5, v14, v41
	v_sub_f32_e32 v14, v53, v52
	v_mul_f32_e32 v14, 0x3fb8aa3b, v14
	v_cvt_pk_bf16_f32 v5, v5, s0
	v_exp_f32_e32 v14, v14
	ds_write_b16 v54, v5 offset:2080
	v_mul_f32_e32 v5, 0x3fb8aa3b, v40
	v_exp_f32_e32 v5, v5
	v_mul_f32_e32 v1, v1, v14
	v_cvt_pk_bf16_f32 v1, v1, s0
	ds_write_b16 v54, v1 offset:22560
	v_sub_f32_e32 v1, 1.0, v5
	v_mul_f32_e32 v5, 0x3fb8aa3b, v53
	v_exp_f32_e32 v14, v5
	v_sub_f32_e32 v5, v53, v53
	v_mul_f32_e32 v5, 0x3fb8aa3b, v5
	v_exp_f32_e32 v5, v5
	v_mul_f32_e32 v16, v14, v42
	v_add_u32_e32 v2, 32, v2
	s_movk_i32 s8, 0xa0
	v_mul_f32_e32 v1, v1, v5
	v_lshl_add_u32 v5, v0, 2, 32
	v_cvt_pk_bf16_f32 v16, v16, s0
	v_cvt_pk_bf16_f32 v1, v1, s0
	ds_write_b32 v5, v14 offset:40960
	v_mad_u64_u32 v[14:15], s[12:13], v15, s8, v[2:3]
	ds_write_b16 v54, v16 offset:2240
	ds_write_b16 v54, v1 offset:22720
	s_waitcnt vmcnt(1)
	ds_write_b128 v14, v[6:9] offset:30720
	v_mad_u64_u32 v[6:7], s[12:13], v17, s8, v[2:3]
	s_mul_i32 s12, s11, 0x44
	s_waitcnt vmcnt(0)
	ds_write_b128 v6, v[10:13] offset:30720
	s_waitcnt lgkmcnt(0)
	s_barrier
	s_and_saveexec_b64 s[4:5], vcc
	s_xor_b64 s[4:5], exec, s[4:5]
	s_add_i32 s13, s12, s7
	s_or_saveexec_b64 s[4:5], s[4:5]
	v_mov_b32_e32 v1, s13
	s_xor_b64 exec, exec, s[4:5]
	s_cbranch_execz .LBB0_556
	ds_read2st64_b32 v[6:7], v5 offset0:160 offset1:161
	s_add_i32 s22, s12, s7
	s_lshl_b32 s12, s22, 8
	v_readlane_b32 s8, v252, 9
	s_add_u32 s12, s8, s12
	s_waitcnt lgkmcnt(0)
	v_mul_f32_e32 v2, v6, v7
	ds_read2st64_b32 v[6:7], v5 offset0:162 offset1:163
	v_readlane_b32 s8, v252, 10
	v_ashrrev_i32_e32 v1, 31, v0
	s_addc_u32 s13, s8, 0
	s_waitcnt lgkmcnt(0)
	v_mul_f32_e32 v2, v2, v6
	v_mul_f32_e32 v2, v2, v7
	v_lshl_add_u64 v[6:7], v[0:1], 2, s[12:13]
	v_mov_b32_e32 v1, s22
	global_store_dword v[6:7], v2, off
.LBB0_556:
	s_or_b64 exec, exec, s[4:5]
	v_bfe_u32 v6, v0, 2, 4
	v_lshlrev_b32_e32 v5, 2, v0
	v_mul_u32_u24_e32 v6, 0x50, v6
	v_lshlrev_b32_e32 v2, 12, v1
	v_lshrrev_b32_e32 v1, 2, v0
	v_and_or_b32 v5, v5, 12, v6
	v_and_b32_e32 v1, 12, v1
	v_lshlrev_b32_e32 v4, 5, v4
	v_lshlrev_b32_e32 v6, 1, v5
	v_lshl_add_u32 v26, v1, 2, 32
	v_add3_u32 v8, 32, v4, v6
	ds_read_b64_tr_b16 v[4:5], v8 offset:30720
	ds_read_b128 v[10:13], v26 offset:40960
	v_add_u32_e32 v25, 32, v6
	v_mov_b32_e32 v16, v3
	v_mov_b32_e32 v17, v3
	ds_read_b64_tr_b16 v[14:15], v25 offset:20480
	ds_read_b64_tr_b16 v[18:19], v25 offset:20512
	v_mov_b32_e32 v6, v3
	v_mov_b32_e32 v7, v3
	s_waitcnt lgkmcnt(2)
	v_pk_mul_f32 v[12:13], v[12:13], 0 op_sel_hi:[1,0]
	v_pk_mul_f32 v[10:11], v[10:11], 0 op_sel_hi:[1,0]
	v_mov_b32_e32 v20, v3
	v_mov_b32_e32 v21, v3
	s_waitcnt lgkmcnt(1)
	v_mfma_f32_16x16x32_bf16 v[10:13], v[14:17], v[4:7], v[10:13]
	ds_read_b128 v[14:17], v26 offset:41024
	ds_read_b64_tr_b16 v[28:29], v25 offset:20544
	ds_read_b64_tr_b16 v[32:33], v25 offset:20576
	v_mov_b32_e32 v30, v3
	v_mov_b32_e32 v31, v3
	s_waitcnt lgkmcnt(2)
	v_pk_mul_f32 v[16:17], v[16:17], 0 op_sel_hi:[1,0]
	v_pk_mul_f32 v[14:15], v[14:15], 0 op_sel_hi:[1,0]
	v_mov_b32_e32 v34, v3
	v_mov_b32_e32 v35, v3
	v_mfma_f32_16x16x32_bf16 v[14:17], v[18:21], v[4:7], v[14:17]
	ds_read_b128 v[18:21], v26 offset:41088
	v_and_or_b32 v0, v0, 15, v24
	v_lshl_add_u32 v0, v1, 6, v0
	v_ashrrev_i32_e32 v1, 31, v0
	s_lshl_b32 s22, s10, 1
	s_waitcnt lgkmcnt(0)
	v_pk_mul_f32 v[20:21], v[20:21], 0 op_sel_hi:[1,0]
	v_pk_mul_f32 v[18:19], v[18:19], 0 op_sel_hi:[1,0]
	s_nop 1
	v_mfma_f32_16x16x32_bf16 v[18:21], v[28:31], v[4:7], v[18:21]
	ds_read_b128 v[28:31], v26 offset:41152
	s_waitcnt lgkmcnt(0)
	v_pk_mul_f32 v[30:31], v[30:31], 0 op_sel_hi:[1,0]
	v_pk_mul_f32 v[28:29], v[28:29], 0 op_sel_hi:[1,0]
	s_nop 1
	v_mfma_f32_16x16x32_bf16 v[4:7], v[32:35], v[4:7], v[28:31]
	ds_read_b128 v[32:35], v26 offset:41216
	s_waitcnt lgkmcnt(0)
	v_pk_mul_f32 v[10:11], v[10:11], v[32:33]
	ds_read_b64_tr_b16 v[28:29], v8 offset:33280
	ds_read_b64_tr_b16 v[32:33], v25 offset:23040
	v_pk_mul_f32 v[12:13], v[12:13], v[34:35]
	v_mov_b32_e32 v34, v3
	v_mov_b32_e32 v35, v3
	v_mov_b32_e32 v30, v3
	v_mov_b32_e32 v31, v3
	s_waitcnt lgkmcnt(0)
	s_nop 0
	v_mfma_f32_16x16x32_bf16 v[10:13], v[32:35], v[28:31], v[10:13]
	ds_read_b128 v[32:35], v26 offset:41280
	s_waitcnt lgkmcnt(0)
	v_pk_mul_f32 v[14:15], v[14:15], v[32:33]
	ds_read_b64_tr_b16 v[32:33], v25 offset:23072
	v_pk_mul_f32 v[16:17], v[16:17], v[34:35]
	v_mov_b32_e32 v34, v3
	v_mov_b32_e32 v35, v3
	s_waitcnt lgkmcnt(0)
	s_nop 0
	v_mfma_f32_16x16x32_bf16 v[14:17], v[32:35], v[28:31], v[14:17]
	ds_read_b128 v[32:35], v26 offset:41344
	s_waitcnt lgkmcnt(0)
	v_pk_mul_f32 v[18:19], v[18:19], v[32:33]
	ds_read_b64_tr_b16 v[32:33], v25 offset:23104
	v_pk_mul_f32 v[20:21], v[20:21], v[34:35]
	v_mov_b32_e32 v34, v3
	v_mov_b32_e32 v35, v3
	s_waitcnt lgkmcnt(0)
	s_nop 0
	v_mfma_f32_16x16x32_bf16 v[32:35], v[32:35], v[28:31], v[18:21]
	s_nop 2
	ds_read_b128 v[18:21], v26 offset:41408
	s_waitcnt lgkmcnt(0)
	v_pk_mul_f32 v[4:5], v[4:5], v[18:19]
	ds_read_b64_tr_b16 v[18:19], v25 offset:23136
	v_pk_mul_f32 v[6:7], v[6:7], v[20:21]
	v_mov_b32_e32 v20, v3
	v_mov_b32_e32 v21, v3
	s_waitcnt lgkmcnt(0)
	s_nop 0
	v_mfma_f32_16x16x32_bf16 v[4:7], v[18:21], v[28:31], v[4:7]
	ds_read_b64_tr_b16 v[28:29], v8 offset:35840
	ds_read_b128 v[18:21], v26 offset:41472
	ds_read_b64_tr_b16 v[8:9], v8 offset:38400
	s_waitcnt lgkmcnt(1)
	v_pk_mul_f32 v[10:11], v[10:11], v[18:19]
	ds_read_b64_tr_b16 v[18:19], v25 offset:25600
	v_pk_mul_f32 v[12:13], v[12:13], v[20:21]
	v_mov_b32_e32 v20, v3
	v_mov_b32_e32 v21, v3
	s_waitcnt lgkmcnt(0)
	s_nop 0
	v_mfma_f32_16x16x32_bf16 v[20:23], v[18:21], v[28:31], v[10:13]
	s_nop 2
	ds_read_b128 v[10:13], v26 offset:41536
	s_waitcnt lgkmcnt(0)
	v_pk_mul_f32 v[10:11], v[14:15], v[10:11]
	ds_read_b64_tr_b16 v[14:15], v25 offset:25632
	v_pk_mul_f32 v[12:13], v[16:17], v[12:13]
	v_mov_b32_e32 v16, v3
	v_mov_b32_e32 v17, v3
	s_waitcnt lgkmcnt(0)
	s_nop 0
	v_mfma_f32_16x16x32_bf16 v[16:19], v[14:17], v[28:31], v[10:13]
	s_nop 2
	ds_read_b128 v[10:13], v26 offset:41600
	s_waitcnt lgkmcnt(0)
	v_pk_mul_f32 v[10:11], v[32:33], v[10:11]
	ds_read_b64_tr_b16 v[32:33], v25 offset:25664
	v_pk_mul_f32 v[12:13], v[34:35], v[12:13]
	v_mov_b32_e32 v34, v3
	v_mov_b32_e32 v35, v3
	s_waitcnt lgkmcnt(0)
	s_nop 0
	v_mfma_f32_16x16x32_bf16 v[12:15], v[32:35], v[28:31], v[10:13]
	ds_read_b128 v[32:35], v26 offset:41664
	s_nop 1
	v_mov_b32_e32 v10, v3
	v_mov_b32_e32 v11, v3
	s_waitcnt lgkmcnt(0)
	v_pk_mul_f32 v[4:5], v[4:5], v[32:33]
	ds_read_b64_tr_b16 v[32:33], v25 offset:25696
	v_pk_mul_f32 v[6:7], v[6:7], v[34:35]
	v_mov_b32_e32 v34, v3
	v_mov_b32_e32 v35, v3
	s_waitcnt lgkmcnt(0)
	s_nop 0
	v_mfma_f32_16x16x32_bf16 v[4:7], v[32:35], v[28:31], v[4:7]
	ds_read_b128 v[28:31], v26 offset:41728
	s_waitcnt lgkmcnt(0)
	v_pk_mul_f32 v[20:21], v[20:21], v[28:29]
	ds_read_b64_tr_b16 v[28:29], v25 offset:28160
	v_pk_mul_f32 v[22:23], v[22:23], v[30:31]
	v_mov_b32_e32 v30, v3
	v_mov_b32_e32 v31, v3
	s_waitcnt lgkmcnt(0)
	s_nop 0
	v_mfma_f32_16x16x32_bf16 v[20:23], v[28:31], v[8:11], v[20:23]
	ds_read_b128 v[28:31], v26 offset:41792
	s_waitcnt lgkmcnt(0)
	v_pk_mul_f32 v[16:17], v[16:17], v[28:29]
	ds_read_b64_tr_b16 v[28:29], v25 offset:28192
	v_pk_mul_f32 v[18:19], v[18:19], v[30:31]
	v_mov_b32_e32 v30, v3
	v_mov_b32_e32 v31, v3
	s_waitcnt lgkmcnt(0)
	s_nop 0
	v_mfma_f32_16x16x32_bf16 v[16:19], v[28:31], v[8:11], v[16:19]
	ds_read_b128 v[28:31], v26 offset:41856
	s_waitcnt lgkmcnt(0)
	v_pk_mul_f32 v[12:13], v[12:13], v[28:29]
	ds_read_b64_tr_b16 v[28:29], v25 offset:28224
	v_pk_mul_f32 v[14:15], v[14:15], v[30:31]
	v_mov_b32_e32 v30, v3
	v_mov_b32_e32 v31, v3
	s_waitcnt lgkmcnt(0)
	s_nop 0
	v_mfma_f32_16x16x32_bf16 v[12:15], v[28:31], v[8:11], v[12:15]
	ds_read_b128 v[26:29], v26 offset:41920
	s_waitcnt lgkmcnt(0)
	v_pk_mul_f32 v[4:5], v[4:5], v[26:27]
	ds_read_b64_tr_b16 v[26:27], v25 offset:28256
	v_pk_mul_f32 v[6:7], v[6:7], v[28:29]
	v_mov_b32_e32 v28, v3
	v_mov_b32_e32 v29, v3
	s_waitcnt lgkmcnt(0)
	s_nop 0
	v_mfma_f32_16x16x32_bf16 v[4:7], v[26:29], v[8:11], v[4:7]
	v_lshl_add_u64 v[8:9], v[2:3], 2, s[2:3]
	v_lshl_add_u64 v[10:11], v[0:1], 2, v[8:9]
	global_store_dword v[10:11], v20, off
	global_store_dword v[10:11], v21, off offset:256
	global_store_dword v[10:11], v22, off offset:512
	global_store_dword v[10:11], v23, off offset:768
	v_add_u32_e32 v10, 0x400, v0
	v_ashrrev_i32_e32 v11, 31, v10
	v_lshl_add_u64 v[10:11], v[10:11], 2, v[8:9]
	global_store_dword v[10:11], v16, off
	v_add_u32_e32 v10, 0x440, v0
	v_ashrrev_i32_e32 v11, 31, v10
	v_lshl_add_u64 v[10:11], v[10:11], 2, v[8:9]
	global_store_dword v[10:11], v17, off
	v_add_u32_e32 v10, 0x480, v0
	v_ashrrev_i32_e32 v11, 31, v10
	v_lshl_add_u64 v[10:11], v[10:11], 2, v[8:9]
	global_store_dword v[10:11], v18, off
	v_add_u32_e32 v10, 0x4c0, v0
	v_ashrrev_i32_e32 v11, 31, v10
	v_lshl_add_u64 v[10:11], v[10:11], 2, v[8:9]
	global_store_dword v[10:11], v19, off
	v_add_u32_e32 v10, 0x800, v0
	v_ashrrev_i32_e32 v11, 31, v10
	v_lshl_add_u64 v[10:11], v[10:11], 2, v[8:9]
	global_store_dword v[10:11], v12, off
	v_add_u32_e32 v10, 0x840, v0
	v_ashrrev_i32_e32 v11, 31, v10
	v_lshl_add_u64 v[10:11], v[10:11], 2, v[8:9]
	global_store_dword v[10:11], v13, off
	v_add_u32_e32 v10, 0x880, v0
	v_ashrrev_i32_e32 v11, 31, v10
	v_lshl_add_u64 v[10:11], v[10:11], 2, v[8:9]
	global_store_dword v[10:11], v14, off
	v_add_u32_e32 v10, 0x8c0, v0
	v_ashrrev_i32_e32 v11, 31, v10
	v_lshl_add_u64 v[10:11], v[10:11], 2, v[8:9]
	global_store_dword v[10:11], v15, off
	v_add_u32_e32 v10, 0xc00, v0
	v_ashrrev_i32_e32 v11, 31, v10
	v_lshl_add_u64 v[10:11], v[10:11], 2, v[8:9]
	global_store_dword v[10:11], v4, off
	v_add_u32_e32 v10, 0xc40, v0
	v_ashrrev_i32_e32 v11, 31, v10
	v_add_u32_e32 v4, 0xc80, v0
	v_add_u32_e32 v0, 0xcc0, v0
	v_lshl_add_u64 v[10:11], v[10:11], 2, v[8:9]
	v_ashrrev_i32_e32 v1, 31, v0
	global_store_dword v[10:11], v5, off
	v_ashrrev_i32_e32 v5, 31, v4
	v_lshl_add_u64 v[0:1], v[0:1], 2, v[8:9]
	v_lshl_add_u64 v[4:5], v[4:5], 2, v[8:9]
	global_store_dword v[0:1], v7, off
	v_mov_b32_e32 v0, v222
	global_store_dword v[4:5], v6, off
	s_nop 0
	v_and_b32_e32 v4, 63, v0
	v_or_b32_e32 v1, s10, v4
	v_ashrrev_i32_e32 v10, 6, v0
	v_lshlrev_b32_e32 v2, 1, v1
	v_lshlrev_b32_e32 v24, 4, v10
	v_lshl_add_u64 v[6:7], s[0:1], 0, v[2:3]
	v_mad_i64_i32 v[8:9], s[4:5], v24, s48, v[6:7]
	s_barrier
	v_mov_b32_e32 v1, v80
	v_or_b32_e32 v42, 1, v24
	v_or_b32_e32 v2, 11, v24
	v_or_b32_e32 v11, 13, v24
	v_or_b32_e32 v27, 15, v24
	v_cmp_lt_i32_e32 vcc, 63, v0
	s_waitcnt vmcnt(0)
	v_lshlrev_b32_e32 v33, 16, v1
	v_mov_b32_e32 v1, v96
	v_mad_i64_i32 v[8:9], s[4:5], v42, s48, v[6:7]
	s_waitcnt vmcnt(0)
	v_lshlrev_b32_e32 v45, 16, v1
	v_mov_b32_e32 v1, v81
	s_waitcnt vmcnt(0)
	v_lshlrev_b32_e32 v43, 16, v1
	v_mov_b32_e32 v1, v97
	s_waitcnt vmcnt(0)
	v_lshlrev_b32_e32 v41, 16, v1
	v_or_b32_e32 v1, 2, v24
	v_mad_i64_i32 v[8:9], s[4:5], v1, s48, v[6:7]
	v_mov_b32_e32 v1, v82
	s_waitcnt vmcnt(0)
	v_lshlrev_b32_e32 v39, 16, v1
	v_mov_b32_e32 v1, v98
	s_waitcnt vmcnt(0)
	v_lshlrev_b32_e32 v38, 16, v1
	v_or_b32_e32 v1, 3, v24
	v_mad_i64_i32 v[8:9], s[4:5], v1, s48, v[6:7]
	v_mov_b32_e32 v1, v83
	s_waitcnt vmcnt(0)
	v_lshlrev_b32_e32 v37, 16, v1
	v_mov_b32_e32 v1, v99
	s_waitcnt vmcnt(0)
	v_lshlrev_b32_e32 v35, 16, v1
	v_or_b32_e32 v1, 4, v24
	v_mad_i64_i32 v[8:9], s[4:5], v1, s48, v[6:7]
	v_mov_b32_e32 v1, v84
	s_waitcnt vmcnt(0)
	v_lshlrev_b32_e32 v32, 16, v1
	v_mov_b32_e32 v1, v100
	s_waitcnt vmcnt(0)
	v_lshlrev_b32_e32 v28, 16, v1
	v_or_b32_e32 v1, 5, v24
	v_mad_i64_i32 v[8:9], s[4:5], v1, s48, v[6:7]
	v_mov_b32_e32 v1, v85
	s_waitcnt vmcnt(0)
	v_lshlrev_b32_e32 v26, 16, v1
	v_mov_b32_e32 v1, v101
	s_waitcnt vmcnt(0)
	v_lshlrev_b32_e32 v25, 16, v1
	v_or_b32_e32 v1, 6, v24
	v_mad_i64_i32 v[8:9], s[4:5], v1, s48, v[6:7]
	v_mov_b32_e32 v1, v86
	s_waitcnt vmcnt(0)
	v_lshlrev_b32_e32 v23, 16, v1
	v_mov_b32_e32 v1, v102
	s_waitcnt vmcnt(0)
	v_lshlrev_b32_e32 v22, 16, v1
	v_or_b32_e32 v1, 7, v24
	v_mad_i64_i32 v[8:9], s[4:5], v1, s48, v[6:7]
	v_mov_b32_e32 v1, v87
	s_waitcnt vmcnt(0)
	v_lshlrev_b32_e32 v21, 16, v1
	v_mov_b32_e32 v1, v103
	s_waitcnt vmcnt(0)
	v_lshlrev_b32_e32 v20, 16, v1
	v_or_b32_e32 v1, 8, v24
	v_mad_i64_i32 v[8:9], s[4:5], v1, s48, v[6:7]
	v_mov_b32_e32 v1, v88
	s_waitcnt vmcnt(0)
	v_lshlrev_b32_e32 v19, 16, v1
	v_mov_b32_e32 v1, v104
	s_waitcnt vmcnt(0)
	v_lshlrev_b32_e32 v18, 16, v1
	v_or_b32_e32 v1, 9, v24
	v_mad_i64_i32 v[8:9], s[4:5], v1, s48, v[6:7]
	v_mov_b32_e32 v1, v89
	s_waitcnt vmcnt(0)
	v_lshlrev_b32_e32 v17, 16, v1
	v_mov_b32_e32 v1, v105
	s_waitcnt vmcnt(0)
	v_lshlrev_b32_e32 v16, 16, v1
	v_or_b32_e32 v1, 10, v24
	v_mad_i64_i32 v[8:9], s[4:5], v1, s48, v[6:7]
	v_mov_b32_e32 v1, v90
	s_waitcnt vmcnt(0)
	v_lshlrev_b32_e32 v12, 16, v1
	v_mov_b32_e32 v1, v106
	v_mad_i64_i32 v[8:9], s[4:5], v2, s48, v[6:7]
	v_mov_b32_e32 v2, v91
	v_mov_b32_e32 v5, v107
	v_or_b32_e32 v8, 12, v24
	v_mad_i64_i32 v[14:15], s[4:5], v8, s48, v[6:7]
	v_mov_b32_e32 v8, v92
	s_waitcnt vmcnt(3)
	v_lshlrev_b32_e32 v1, 16, v1
	s_waitcnt vmcnt(2)
	v_lshlrev_b32_e32 v2, 16, v2
	s_waitcnt vmcnt(1)
	v_lshlrev_b32_e32 v5, 16, v5
	s_waitcnt vmcnt(0)
	v_lshlrev_b32_e32 v9, 16, v8
	v_mov_b32_e32 v8, v108
	v_mad_i64_i32 v[14:15], s[4:5], v11, s48, v[6:7]
	v_mov_b32_e32 v11, v93
	s_waitcnt vmcnt(1)
	v_lshlrev_b32_e32 v8, 16, v8
	s_waitcnt vmcnt(0)
	v_lshlrev_b32_e32 v13, 16, v11
	v_mov_b32_e32 v11, v109
	v_or_b32_e32 v14, 14, v24
	v_mad_i64_i32 v[30:31], s[4:5], v14, s48, v[6:7]
	v_mov_b32_e32 v14, v94
	s_waitcnt vmcnt(1)
	v_lshlrev_b32_e32 v11, 16, v11
	s_waitcnt vmcnt(0)
	v_lshlrev_b32_e32 v15, 16, v14
	v_mov_b32_e32 v14, v110
	v_mad_i64_i32 v[30:31], s[4:5], v27, s48, v[6:7]
	v_mov_b32_e32 v6, v95
	v_mov_b32_e32 v7, v111
	s_movk_i32 s4, 0x500
	s_waitcnt vmcnt(2)
	v_lshlrev_b32_e32 v14, 16, v14
	s_waitcnt vmcnt(1)
	v_lshlrev_b32_e32 v6, 16, v6
	s_waitcnt vmcnt(0)
	v_lshlrev_b32_e32 v27, 16, v7
	v_add_f32_e32 v7, 0, v6
	v_add_f32_e32 v29, v7, v15
	v_add_f32_e32 v31, v29, v13
	v_add_f32_e32 v34, v31, v9
	v_add_f32_e32 v36, v34, v2
	v_add_f32_e32 v40, v36, v12
	v_add_f32_e32 v44, v40, v17
	v_add_f32_e32 v46, v44, v19
	v_add_f32_e32 v47, v46, v21
	v_add_f32_e32 v48, v47, v23
	v_add_f32_e32 v49, v48, v26
	v_add_f32_e32 v50, v49, v32
	v_add_f32_e32 v51, v50, v37
	v_add_f32_e32 v52, v51, v39
	v_add_f32_e32 v53, v52, v43
	v_add_f32_e32 v30, v53, v33
	v_mul_f32_e32 v33, 0x3fb8aa3b, v33
	v_exp_f32_e32 v33, v33
	v_mul_f32_e32 v43, 0x3fb8aa3b, v43
	v_exp_f32_e32 v43, v43
	v_mul_f32_e32 v39, 0x3fb8aa3b, v39
	v_sub_f32_e32 v54, 1.0, v33
	v_mul_lo_u32 v33, v10, s4
	v_or_b32_e32 v55, v33, v4
	v_mul_f32_e32 v33, 0x3fb8aa3b, v30
	v_exp_f32_e32 v33, v33
	v_lshl_add_u32 v55, v55, 1, 32
	s_movk_i32 s4, 0x50
	v_exp_f32_e32 v39, v39
	v_mul_f32_e32 v45, v33, v45
	v_cvt_pk_bf16_f32 v45, v45, s0
	ds_write_b16 v55, v45
	v_sub_f32_e32 v45, v30, v30
	v_mul_f32_e32 v45, 0x3fb8aa3b, v45
	v_exp_f32_e32 v45, v45
	v_sub_f32_e32 v39, 1.0, v39
	v_mul_f32_e32 v37, 0x3fb8aa3b, v37
	v_exp_f32_e32 v37, v37
	v_mul_f32_e32 v45, v54, v45
	v_cvt_pk_bf16_f32 v45, v45, s0
	ds_write_b16 v55, v45 offset:20480
	v_sub_f32_e32 v45, 1.0, v43
	v_mad_u64_u32 v[42:43], s[4:5], v42, s4, v[4:5]
	v_mul_f32_e32 v4, 0x3fb8aa3b, v53
	v_exp_f32_e32 v4, v4
	v_sub_f32_e32 v37, 1.0, v37
	v_mul_f32_e32 v32, 0x3fb8aa3b, v32
	v_exp_f32_e32 v32, v32
	v_mul_f32_e32 v4, v4, v41
	v_cvt_pk_bf16_f32 v41, v4, s0
	v_lshl_add_u32 v4, v42, 1, 32
	ds_write_b16 v4, v41
	v_sub_f32_e32 v41, v30, v53
	v_mul_f32_e32 v41, 0x3fb8aa3b, v41
	v_exp_f32_e32 v41, v41
	v_sub_f32_e32 v32, 1.0, v32
	v_mul_f32_e32 v26, 0x3fb8aa3b, v26
	v_exp_f32_e32 v26, v26
	v_mul_f32_e32 v41, v45, v41
	v_cvt_pk_bf16_f32 v41, v41, s0
	ds_write_b16 v4, v41 offset:20480
	v_mul_f32_e32 v41, 0x3fb8aa3b, v52
	v_exp_f32_e32 v41, v41
	v_sub_f32_e32 v26, 1.0, v26
	v_mul_f32_e32 v23, 0x3fb8aa3b, v23
	v_exp_f32_e32 v23, v23
	v_mul_f32_e32 v38, v41, v38
	v_cvt_pk_bf16_f32 v38, v38, s0
	ds_write_b16 v4, v38 offset:160
	v_sub_f32_e32 v38, v30, v52
	v_mul_f32_e32 v38, 0x3fb8aa3b, v38
	v_exp_f32_e32 v38, v38
	v_sub_f32_e32 v23, 1.0, v23
	v_mul_f32_e32 v21, 0x3fb8aa3b, v21
	v_exp_f32_e32 v21, v21
	v_mul_f32_e32 v38, v39, v38
	v_cvt_pk_bf16_f32 v38, v38, s0
	ds_write_b16 v4, v38 offset:20640
	v_mul_f32_e32 v38, 0x3fb8aa3b, v51
	v_exp_f32_e32 v38, v38
	v_sub_f32_e32 v21, 1.0, v21
	v_mul_f32_e32 v19, 0x3fb8aa3b, v19
	v_exp_f32_e32 v19, v19
	v_mul_f32_e32 v35, v38, v35
	v_cvt_pk_bf16_f32 v35, v35, s0
	ds_write_b16 v4, v35 offset:320
	v_sub_f32_e32 v35, v30, v51
	v_mul_f32_e32 v35, 0x3fb8aa3b, v35
	v_exp_f32_e32 v35, v35
	v_sub_f32_e32 v19, 1.0, v19
	v_mul_f32_e32 v17, 0x3fb8aa3b, v17
	v_exp_f32_e32 v17, v17
	v_mul_f32_e32 v35, v37, v35
	v_cvt_pk_bf16_f32 v35, v35, s0
	ds_write_b16 v4, v35 offset:20800
	v_mul_f32_e32 v35, 0x3fb8aa3b, v50
	v_exp_f32_e32 v35, v35
	v_sub_f32_e32 v17, 1.0, v17
	v_mul_f32_e32 v12, 0x3fb8aa3b, v12
	v_exp_f32_e32 v12, v12
	v_mul_f32_e32 v28, v35, v28
	v_cvt_pk_bf16_f32 v28, v28, s0
	ds_write_b16 v4, v28 offset:480
	v_sub_f32_e32 v28, v30, v50
	v_mul_f32_e32 v28, 0x3fb8aa3b, v28
	v_exp_f32_e32 v28, v28
	v_sub_f32_e32 v12, 1.0, v12
	s_movk_i32 s4, 0xa0
	v_mul_f32_e32 v28, v32, v28
	v_cvt_pk_bf16_f32 v28, v28, s0
	ds_write_b16 v4, v28 offset:20960
	v_mul_f32_e32 v28, 0x3fb8aa3b, v49
	v_exp_f32_e32 v28, v28
	s_nop 0
	v_mul_f32_e32 v25, v28, v25
	v_cvt_pk_bf16_f32 v25, v25, s0
	ds_write_b16 v4, v25 offset:640
	v_sub_f32_e32 v25, v30, v49
	v_mul_f32_e32 v25, 0x3fb8aa3b, v25
	v_exp_f32_e32 v25, v25
	s_nop 0
	v_mul_f32_e32 v25, v26, v25
	v_cvt_pk_bf16_f32 v25, v25, s0
	ds_write_b16 v4, v25 offset:21120
	v_mul_f32_e32 v25, 0x3fb8aa3b, v48
	v_exp_f32_e32 v25, v25
	s_nop 0
	v_mul_f32_e32 v22, v25, v22
	v_cvt_pk_bf16_f32 v22, v22, s0
	ds_write_b16 v4, v22 offset:800
	v_sub_f32_e32 v22, v30, v48
	v_mul_f32_e32 v22, 0x3fb8aa3b, v22
	v_exp_f32_e32 v22, v22
	s_nop 0
	v_mul_f32_e32 v22, v23, v22
	v_cvt_pk_bf16_f32 v22, v22, s0
	ds_write_b16 v4, v22 offset:21280
	v_mul_f32_e32 v22, 0x3fb8aa3b, v47
	v_exp_f32_e32 v22, v22
	s_nop 0
	v_mul_f32_e32 v20, v22, v20
	v_cvt_pk_bf16_f32 v20, v20, s0
	ds_write_b16 v4, v20 offset:960
	v_sub_f32_e32 v20, v30, v47
	v_mul_f32_e32 v20, 0x3fb8aa3b, v20
	v_exp_f32_e32 v20, v20
	s_nop 0
	v_mul_f32_e32 v20, v21, v20
	v_cvt_pk_bf16_f32 v20, v20, s0
	ds_write_b16 v4, v20 offset:21440
	v_mul_f32_e32 v20, 0x3fb8aa3b, v46
	v_exp_f32_e32 v20, v20
	s_nop 0
	v_mul_f32_e32 v18, v20, v18
	v_cvt_pk_bf16_f32 v18, v18, s0
	ds_write_b16 v4, v18 offset:1120
	v_sub_f32_e32 v18, v30, v46
	v_mul_f32_e32 v18, 0x3fb8aa3b, v18
	v_exp_f32_e32 v18, v18
	s_nop 0
	v_mul_f32_e32 v18, v19, v18
	v_cvt_pk_bf16_f32 v18, v18, s0
	ds_write_b16 v4, v18 offset:21600
	v_mul_f32_e32 v18, 0x3fb8aa3b, v44
	v_exp_f32_e32 v18, v18
	s_nop 0
	v_mul_f32_e32 v16, v18, v16
	v_cvt_pk_bf16_f32 v16, v16, s0
	ds_write_b16 v4, v16 offset:1280
	v_sub_f32_e32 v16, v30, v44
	v_mul_f32_e32 v16, 0x3fb8aa3b, v16
	v_exp_f32_e32 v16, v16
	s_nop 0
	v_mul_f32_e32 v16, v17, v16
	v_cvt_pk_bf16_f32 v16, v16, s0
	ds_write_b16 v4, v16 offset:21760
	v_mul_f32_e32 v16, 0x3fb8aa3b, v40
	v_exp_f32_e32 v16, v16
	s_nop 0
	v_mul_f32_e32 v1, v16, v1
	v_cvt_pk_bf16_f32 v1, v1, s0
	ds_write_b16 v4, v1 offset:1440
	v_sub_f32_e32 v1, v30, v40
	v_mul_f32_e32 v1, 0x3fb8aa3b, v1
	v_exp_f32_e32 v1, v1
	s_nop 0
	v_mul_f32_e32 v1, v12, v1
	v_cvt_pk_bf16_f32 v1, v1, s0
	ds_write_b16 v4, v1 offset:21920
	v_mul_f32_e32 v1, 0x3fb8aa3b, v2
	v_mul_f32_e32 v2, 0x3fb8aa3b, v36
	v_exp_f32_e32 v2, v2
	v_exp_f32_e32 v1, v1
	v_mul_f32_e32 v2, v2, v5
	v_cvt_pk_bf16_f32 v2, v2, s0
	ds_write_b16 v4, v2 offset:1600
	v_sub_f32_e32 v2, v30, v36
	v_mul_f32_e32 v2, 0x3fb8aa3b, v2
	v_exp_f32_e32 v2, v2
	v_sub_f32_e32 v1, 1.0, v1
	v_mul_f32_e32 v1, v1, v2
	v_mul_f32_e32 v2, 0x3fb8aa3b, v34
	v_exp_f32_e32 v2, v2
	v_cvt_pk_bf16_f32 v1, v1, s0
	ds_write_b16 v4, v1 offset:22080
	v_mul_f32_e32 v1, 0x3fb8aa3b, v9
	v_mul_f32_e32 v2, v2, v8
	v_cvt_pk_bf16_f32 v2, v2, s0
	ds_write_b16 v4, v2 offset:1760
	v_sub_f32_e32 v2, v30, v34
	v_exp_f32_e32 v1, v1
	v_mul_f32_e32 v2, 0x3fb8aa3b, v2
	v_exp_f32_e32 v2, v2
	v_sub_f32_e32 v1, 1.0, v1
	v_mul_f32_e32 v1, v1, v2
	v_mul_f32_e32 v2, 0x3fb8aa3b, v31
	v_exp_f32_e32 v2, v2
	v_cvt_pk_bf16_f32 v1, v1, s0
	ds_write_b16 v4, v1 offset:22240
	v_mul_f32_e32 v1, 0x3fb8aa3b, v13
	v_mul_f32_e32 v2, v2, v11
	v_cvt_pk_bf16_f32 v2, v2, s0
	ds_write_b16 v4, v2 offset:1920
	v_sub_f32_e32 v2, v30, v31
	v_exp_f32_e32 v1, v1
	v_mul_f32_e32 v2, 0x3fb8aa3b, v2
	v_exp_f32_e32 v2, v2
	v_mov_b64_e32 v[12:13], s[0:1]
	v_sub_f32_e32 v1, 1.0, v1
	v_lshl_add_u32 v11, v0, 2, 32
	v_mul_f32_e32 v1, v1, v2
	v_mul_f32_e32 v2, 0x3fb8aa3b, v29
	v_exp_f32_e32 v2, v2
	v_cvt_pk_bf16_f32 v1, v1, s0
	ds_write_b16 v4, v1 offset:22400
	v_mul_f32_e32 v1, 0x3fb8aa3b, v15
	v_mul_f32_e32 v2, v2, v14
	v_cvt_pk_bf16_f32 v2, v2, s0
	ds_write_b16 v4, v2 offset:2080
	v_sub_f32_e32 v2, v30, v29
	v_exp_f32_e32 v1, v1
	v_mul_f32_e32 v2, 0x3fb8aa3b, v2
	v_exp_f32_e32 v2, v2
	ds_write_b32 v11, v33 offset:40960
	v_sub_f32_e32 v1, 1.0, v1
	v_mul_f32_e32 v1, v1, v2
	v_mul_f32_e32 v2, 0x3fb8aa3b, v7
	v_exp_f32_e32 v2, v2
	v_cvt_pk_bf16_f32 v1, v1, s0
	ds_write_b16 v4, v1 offset:22560
	v_mul_f32_e32 v1, 0x3fb8aa3b, v6
	v_mul_f32_e32 v2, v2, v27
	v_cvt_pk_bf16_f32 v2, v2, s0
	ds_write_b16 v4, v2 offset:2240
	v_sub_f32_e32 v2, v30, v7
	v_exp_f32_e32 v1, v1
	v_mul_f32_e32 v2, 0x3fb8aa3b, v2
	v_exp_f32_e32 v2, v2
	v_sub_f32_e32 v1, 1.0, v1
	v_mul_f32_e32 v1, v1, v2
	v_cvt_pk_bf16_f32 v1, v1, s0
	ds_write_b16 v4, v1 offset:22720
	v_lshlrev_b32_e32 v1, 4, v0
	v_and_b32_e32 v2, 0x70, v1
	v_ashrrev_i32_e32 v1, 3, v0
	v_mad_i64_i32 v[4:5], s[0:1], v1, s48, v[12:13]
	v_lshl_add_u64 v[4:5], v[4:5], 0, s[22:23]
	v_lshl_add_u64 v[4:5], v[4:5], 0, v[2:3]
	global_load_dwordx4 v[4:7], v[4:5], off offset:1536
	v_add_u32_e32 v8, 32, v2
	v_mad_u64_u32 v[14:15], s[0:1], v1, s4, v[8:9]
	v_add_u32_e32 v1, 0x100, v0
	v_ashrrev_i32_e32 v1, 3, v1
	v_mad_u64_u32 v[8:9], s[0:1], v1, s4, v[8:9]
	s_or_b32 s4, s11, 1
	s_mulk_i32 s4, 0x44
	s_waitcnt vmcnt(0)
	ds_write_b128 v14, v[4:7] offset:30720
	v_mad_i64_i32 v[4:5], s[0:1], v1, s48, v[12:13]
	v_lshl_add_u64 v[4:5], v[4:5], 0, s[22:23]
	v_lshl_add_u64 v[4:5], v[4:5], 0, v[2:3]
	global_load_dwordx4 v[4:7], v[4:5], off offset:1536
	s_waitcnt vmcnt(0)
	ds_write_b128 v8, v[4:7] offset:30720
	s_waitcnt lgkmcnt(0)
	s_barrier
	s_and_saveexec_b64 s[0:1], vcc
	s_xor_b64 s[0:1], exec, s[0:1]
	s_add_i32 s5, s4, s7
	s_or_saveexec_b64 s[0:1], s[0:1]
	v_mov_b32_e32 v1, s5
	s_xor_b64 exec, exec, s[0:1]
	s_cbranch_execz .LBB0_560
	ds_read2st64_b32 v[4:5], v11 offset0:160 offset1:161
	s_add_i32 s7, s4, s7
	s_lshl_b32 s4, s7, 8
	v_readlane_b32 s5, v252, 9
	s_add_u32 s4, s5, s4
	s_waitcnt lgkmcnt(0)
	v_mul_f32_e32 v2, v4, v5
	ds_read2st64_b32 v[4:5], v11 offset0:162 offset1:163
	v_readlane_b32 s5, v252, 10
	v_ashrrev_i32_e32 v1, 31, v0
	s_addc_u32 s5, s5, 0
	s_waitcnt lgkmcnt(0)
	v_mul_f32_e32 v2, v2, v4
	v_mul_f32_e32 v2, v2, v5
	v_lshl_add_u64 v[4:5], v[0:1], 2, s[4:5]
	v_mov_b32_e32 v1, s7
	global_store_dword v[4:5], v2, off

.Lat_noload_a:
	s_waitcnt vmcnt(8) lgkmcnt(0)
	v_mfma_f32_32x32x16_bf16 v[68:83], v[186:189], v[120:123], v[224:239]
	ds_read_b64_tr_b16 v[186:187], v241 offset:18432
	ds_read_b64_tr_b16 v[188:189], v241 offset:19584
	v_mfma_f32_32x32x16_bf16 v[84:99], v[190:193], v[120:123], v[224:239]
	ds_read_b64_tr_b16 v[190:191], v241 offset:18496
	ds_read_b64_tr_b16 v[192:193], v241 offset:19648
	v_mfma_f32_32x32x16_bf16 v[68:83], v[194:197], v[108:111], v[68:83]
	ds_read_b64_tr_b16 v[194:195], v241 offset:20736
	ds_read_b64_tr_b16 v[196:197], v241 offset:21888
	v_mfma_f32_32x32x16_bf16 v[84:99], v[198:201], v[108:111], v[84:99]
	ds_read_b64_tr_b16 v[198:199], v241 offset:20800
	ds_read_b64_tr_b16 v[200:201], v241 offset:21952
	v_mfma_f32_32x32x16_bf16 v[154:169], v[202:205], v[116:119], v[224:239]
	ds_read_b64_tr_b16 v[202:203], v242 offset:23040
	ds_read_b64_tr_b16 v[204:205], v242 offset:24192
	v_mfma_f32_32x32x16_bf16 v[170:185], v[206:209], v[116:119], v[224:239]
	ds_read_b64_tr_b16 v[206:207], v242 offset:23104
	ds_read_b64_tr_b16 v[208:209], v242 offset:24256
	s_nop 0
	v_exp_f32_e32 v68, v68
	v_exp_f32_e32 v69, v69
	v_exp_f32_e32 v70, v70
	v_exp_f32_e32 v71, v71
	v_exp_f32_e32 v72, v72
	v_exp_f32_e32 v73, v73
	v_exp_f32_e32 v74, v74
	v_exp_f32_e32 v75, v75
	v_mfma_f32_32x32x16_bf16 v[154:169], v[210:213], v[124:127], v[154:169]
	ds_read_b64_tr_b16 v[210:211], v242 offset:25344
	ds_read_b64_tr_b16 v[212:213], v242 offset:26496
	v_pk_add_f32 v[220:221], v[68:69], v[220:221]
	v_pk_add_f32 v[220:221], v[70:71], v[220:221]
	v_pk_add_f32 v[220:221], v[72:73], v[220:221]
	v_pk_add_f32 v[220:221], v[74:75], v[220:221]
	v_cvt_pk_bf16_f32 v68, v68, v69
	v_cvt_pk_bf16_f32 v69, v70, v71
	v_cvt_pk_bf16_f32 v70, v72, v73
	v_cvt_pk_bf16_f32 v71, v74, v75
	v_mfma_f32_32x32x16_bf16 v[170:185], v[214:217], v[124:127], v[170:185]
	ds_read_b64_tr_b16 v[214:215], v242 offset:25408
	ds_read_b64_tr_b16 v[216:217], v242 offset:26560
	v_exp_f32_e32 v154, v154
	v_exp_f32_e32 v155, v155
	v_exp_f32_e32 v156, v156
	v_exp_f32_e32 v157, v157
	v_exp_f32_e32 v158, v158
	v_exp_f32_e32 v159, v159
	v_exp_f32_e32 v160, v160
	v_exp_f32_e32 v161, v161
	s_waitcnt lgkmcnt(12)
	v_mfma_f32_32x32x16_bf16 v[4:19], v[186:189], v[68:71], v[4:19]
	v_pk_add_f32 v[246:247], v[154:155], v[246:247]
	v_pk_add_f32 v[246:247], v[156:157], v[246:247]
	v_pk_add_f32 v[246:247], v[158:159], v[246:247]
	v_pk_add_f32 v[246:247], v[160:161], v[246:247]
	v_cvt_pk_bf16_f32 v154, v154, v155
	v_cvt_pk_bf16_f32 v155, v156, v157
	v_cvt_pk_bf16_f32 v156, v158, v159
	v_cvt_pk_bf16_f32 v157, v160, v161
	v_mfma_f32_32x32x16_bf16 v[20:35], v[190:193], v[68:71], v[20:35]
	v_exp_f32_e32 v76, v76
	v_exp_f32_e32 v77, v77
	v_exp_f32_e32 v78, v78
	v_exp_f32_e32 v79, v79
	v_exp_f32_e32 v80, v80
	v_exp_f32_e32 v81, v81
	v_exp_f32_e32 v82, v82
	v_exp_f32_e32 v83, v83
	v_mfma_f32_32x32x16_bf16 v[36:51], v[186:189], v[154:157], v[36:51]
	v_pk_add_f32 v[220:221], v[76:77], v[220:221]
	v_pk_add_f32 v[220:221], v[78:79], v[220:221]
	v_pk_add_f32 v[220:221], v[80:81], v[220:221]
	v_pk_add_f32 v[220:221], v[82:83], v[220:221]
	v_cvt_pk_bf16_f32 v76, v76, v77
	v_cvt_pk_bf16_f32 v77, v78, v79
	v_cvt_pk_bf16_f32 v78, v80, v81
	v_cvt_pk_bf16_f32 v79, v82, v83
	v_mfma_f32_32x32x16_bf16 v[52:67], v[190:193], v[154:157], v[52:67]
	v_exp_f32_e32 v162, v162
	v_exp_f32_e32 v163, v163
	v_exp_f32_e32 v164, v164
	v_exp_f32_e32 v165, v165
	v_exp_f32_e32 v166, v166
	v_exp_f32_e32 v167, v167
	v_exp_f32_e32 v168, v168
	v_exp_f32_e32 v169, v169
	s_waitcnt lgkmcnt(8)
	v_mfma_f32_32x32x16_bf16 v[4:19], v[194:197], v[76:79], v[4:19]
	v_pk_add_f32 v[246:247], v[162:163], v[246:247]
	v_pk_add_f32 v[246:247], v[164:165], v[246:247]
	v_pk_add_f32 v[246:247], v[166:167], v[246:247]
	v_pk_add_f32 v[246:247], v[168:169], v[246:247]
	v_cvt_pk_bf16_f32 v162, v162, v163
	v_cvt_pk_bf16_f32 v163, v164, v165
	v_cvt_pk_bf16_f32 v164, v166, v167
	v_cvt_pk_bf16_f32 v165, v168, v169
	v_mfma_f32_32x32x16_bf16 v[20:35], v[198:201], v[76:79], v[20:35]
	v_exp_f32_e32 v84, v84
	v_exp_f32_e32 v85, v85
	v_exp_f32_e32 v86, v86
	v_exp_f32_e32 v87, v87
	v_exp_f32_e32 v88, v88
	v_exp_f32_e32 v89, v89
	v_exp_f32_e32 v90, v90
	v_exp_f32_e32 v91, v91
	v_mfma_f32_32x32x16_bf16 v[36:51], v[194:197], v[162:165], v[36:51]
	v_pk_add_f32 v[220:221], v[84:85], v[220:221]
	v_pk_add_f32 v[220:221], v[86:87], v[220:221]
	v_pk_add_f32 v[220:221], v[88:89], v[220:221]
	v_pk_add_f32 v[220:221], v[90:91], v[220:221]
	v_cvt_pk_bf16_f32 v84, v84, v85
	v_cvt_pk_bf16_f32 v85, v86, v87
	v_cvt_pk_bf16_f32 v86, v88, v89
	v_cvt_pk_bf16_f32 v87, v90, v91
	v_mfma_f32_32x32x16_bf16 v[52:67], v[198:201], v[162:165], v[52:67]
	v_exp_f32_e32 v170, v170
	v_exp_f32_e32 v171, v171
	v_exp_f32_e32 v172, v172
	v_exp_f32_e32 v173, v173
	v_exp_f32_e32 v174, v174
	v_exp_f32_e32 v175, v175
	v_exp_f32_e32 v176, v176
	v_exp_f32_e32 v177, v177
	s_waitcnt lgkmcnt(4)
	v_mfma_f32_32x32x16_bf16 v[4:19], v[202:205], v[84:87], v[4:19]
	v_pk_add_f32 v[246:247], v[170:171], v[246:247]
	v_pk_add_f32 v[246:247], v[172:173], v[246:247]
	v_pk_add_f32 v[246:247], v[174:175], v[246:247]
	v_pk_add_f32 v[246:247], v[176:177], v[246:247]
	v_cvt_pk_bf16_f32 v170, v170, v171
	v_cvt_pk_bf16_f32 v171, v172, v173
	v_cvt_pk_bf16_f32 v172, v174, v175
	v_cvt_pk_bf16_f32 v173, v176, v177
	v_mfma_f32_32x32x16_bf16 v[20:35], v[206:209], v[84:87], v[20:35]
	v_exp_f32_e32 v92, v92
	v_exp_f32_e32 v93, v93
	v_exp_f32_e32 v94, v94
	v_exp_f32_e32 v95, v95
	v_exp_f32_e32 v96, v96
	v_exp_f32_e32 v97, v97
	v_exp_f32_e32 v98, v98
	v_exp_f32_e32 v99, v99
	v_mfma_f32_32x32x16_bf16 v[36:51], v[202:205], v[170:173], v[36:51]
	v_pk_add_f32 v[220:221], v[92:93], v[220:221]
	v_pk_add_f32 v[220:221], v[94:95], v[220:221]
	v_pk_add_f32 v[220:221], v[96:97], v[220:221]
	v_pk_add_f32 v[220:221], v[98:99], v[220:221]
	v_cvt_pk_bf16_f32 v92, v92, v93
	v_cvt_pk_bf16_f32 v93, v94, v95
	v_cvt_pk_bf16_f32 v94, v96, v97
	v_cvt_pk_bf16_f32 v95, v98, v99
	v_mfma_f32_32x32x16_bf16 v[52:67], v[206:209], v[170:173], v[52:67]
	v_exp_f32_e32 v178, v178
	v_exp_f32_e32 v179, v179
	v_exp_f32_e32 v180, v180
	v_exp_f32_e32 v181, v181
	v_exp_f32_e32 v182, v182
	v_exp_f32_e32 v183, v183
	v_exp_f32_e32 v184, v184
	v_exp_f32_e32 v185, v185
	s_waitcnt lgkmcnt(0)
	v_mfma_f32_32x32x16_bf16 v[4:19], v[210:213], v[92:95], v[4:19]
	v_pk_add_f32 v[246:247], v[178:179], v[246:247]
	v_pk_add_f32 v[246:247], v[180:181], v[246:247]
	v_pk_add_f32 v[246:247], v[182:183], v[246:247]
	v_pk_add_f32 v[246:247], v[184:185], v[246:247]
	v_cvt_pk_bf16_f32 v178, v178, v179
	v_cvt_pk_bf16_f32 v179, v180, v181
	v_cvt_pk_bf16_f32 v180, v182, v183
	v_cvt_pk_bf16_f32 v181, v184, v185
	v_mfma_f32_32x32x16_bf16 v[20:35], v[214:217], v[92:95], v[20:35]
	s_nop 1
	v_mfma_f32_32x32x16_bf16 v[36:51], v[210:213], v[178:181], v[36:51]
	v_mfma_f32_32x32x16_bf16 v[52:67], v[214:217], v[178:181], v[52:67]
	v_max3_f32 v248, v220, v221, v246
	v_max_f32_e32 v248, v248, v247
	v_cmp_lt_f32_e32 vcc, 0x49800000, v248
	s_cbranch_vccz .Lat_norescale_a
	v_add_f32_e32 v250, v220, v221
	v_add_f32_e32 v251, v246, v247
	v_lshlrev_b32_e32 v249, 2, v222
	v_xor_b32_e32 v249, 0x80, v249
	v_and_b32_e32 v249, 0xfc, v249
	ds_bpermute_b32 v68, v249, v250
	ds_bpermute_b32 v69, v249, v251
	s_waitcnt lgkmcnt(0)
	v_add_f32_e32 v250, v250, v68
	v_add_f32_e32 v251, v251, v69
	v_max_f32_e32 v250, v250, v251
	v_log_f32_e32 v250, v250
	s_nop 0
	v_max_f32_e32 v250, 0, v250
	v_add_f32_e32 v244, v244, v250
	v_exp_f32_e64 v248, -v250
	v_xor_b32_e32 v224, 0x80000000, v244
	v_mov_b32_e32 v225, v224
	v_mov_b32_e32 v226, v224
	v_mov_b32_e32 v227, v224
	v_mov_b32_e32 v228, v224
	v_mov_b32_e32 v229, v224
	v_mov_b32_e32 v230, v224
	v_mov_b32_e32 v231, v224
	v_mov_b32_e32 v232, v224
	v_mov_b32_e32 v233, v224
	v_mov_b32_e32 v234, v224
	v_mov_b32_e32 v235, v224
	v_mov_b32_e32 v236, v224
	v_mov_b32_e32 v237, v224
	v_mov_b32_e32 v238, v224
	v_mov_b32_e32 v239, v224
	v_mul_f32_e32 v220, v220, v248
	v_mul_f32_e32 v221, v221, v248
	v_mul_f32_e32 v246, v246, v248
	v_mul_f32_e32 v247, v247, v248
	v_pk_mul_f32 v[4:5], v[4:5], v[248:249] op_sel_hi:[1,0]
	v_pk_mul_f32 v[6:7], v[6:7], v[248:249] op_sel_hi:[1,0]
	v_pk_mul_f32 v[8:9], v[8:9], v[248:249] op_sel_hi:[1,0]
	v_pk_mul_f32 v[10:11], v[10:11], v[248:249] op_sel_hi:[1,0]
	v_pk_mul_f32 v[12:13], v[12:13], v[248:249] op_sel_hi:[1,0]
	v_pk_mul_f32 v[14:15], v[14:15], v[248:249] op_sel_hi:[1,0]
	v_pk_mul_f32 v[16:17], v[16:17], v[248:249] op_sel_hi:[1,0]
	v_pk_mul_f32 v[18:19], v[18:19], v[248:249] op_sel_hi:[1,0]
	v_pk_mul_f32 v[20:21], v[20:21], v[248:249] op_sel_hi:[1,0]
	v_pk_mul_f32 v[22:23], v[22:23], v[248:249] op_sel_hi:[1,0]
	v_pk_mul_f32 v[24:25], v[24:25], v[248:249] op_sel_hi:[1,0]
	v_pk_mul_f32 v[26:27], v[26:27], v[248:249] op_sel_hi:[1,0]
	v_pk_mul_f32 v[28:29], v[28:29], v[248:249] op_sel_hi:[1,0]
	v_pk_mul_f32 v[30:31], v[30:31], v[248:249] op_sel_hi:[1,0]
	v_pk_mul_f32 v[32:33], v[32:33], v[248:249] op_sel_hi:[1,0]
	v_pk_mul_f32 v[34:35], v[34:35], v[248:249] op_sel_hi:[1,0]
	v_pk_mul_f32 v[36:37], v[36:37], v[248:249] op_sel_hi:[1,0]
	v_pk_mul_f32 v[38:39], v[38:39], v[248:249] op_sel_hi:[1,0]
	v_pk_mul_f32 v[40:41], v[40:41], v[248:249] op_sel_hi:[1,0]
	v_pk_mul_f32 v[42:43], v[42:43], v[248:249] op_sel_hi:[1,0]
	v_pk_mul_f32 v[44:45], v[44:45], v[248:249] op_sel_hi:[1,0]
	v_pk_mul_f32 v[46:47], v[46:47], v[248:249] op_sel_hi:[1,0]
	v_pk_mul_f32 v[48:49], v[48:49], v[248:249] op_sel_hi:[1,0]
	v_pk_mul_f32 v[50:51], v[50:51], v[248:249] op_sel_hi:[1,0]
	v_pk_mul_f32 v[52:53], v[52:53], v[248:249] op_sel_hi:[1,0]
	v_pk_mul_f32 v[54:55], v[54:55], v[248:249] op_sel_hi:[1,0]
	v_pk_mul_f32 v[56:57], v[56:57], v[248:249] op_sel_hi:[1,0]
	v_pk_mul_f32 v[58:59], v[58:59], v[248:249] op_sel_hi:[1,0]
	v_pk_mul_f32 v[60:61], v[60:61], v[248:249] op_sel_hi:[1,0]
	v_pk_mul_f32 v[62:63], v[62:63], v[248:249] op_sel_hi:[1,0]
	v_pk_mul_f32 v[64:65], v[64:65], v[248:249] op_sel_hi:[1,0]
	v_pk_mul_f32 v[66:67], v[66:67], v[248:249] op_sel_hi:[1,0]

.Lat_noload_b:
	s_waitcnt vmcnt(8) lgkmcnt(0)
	v_mfma_f32_32x32x16_bf16 v[68:83], v[186:189], v[120:123], v[224:239]
	ds_read_b64_tr_b16 v[186:187], v241 offset:27648
	ds_read_b64_tr_b16 v[188:189], v241 offset:28800
	v_mfma_f32_32x32x16_bf16 v[84:99], v[190:193], v[120:123], v[224:239]
	ds_read_b64_tr_b16 v[190:191], v241 offset:27712
	ds_read_b64_tr_b16 v[192:193], v241 offset:28864
	v_mfma_f32_32x32x16_bf16 v[68:83], v[194:197], v[108:111], v[68:83]
	ds_read_b64_tr_b16 v[194:195], v241 offset:29952
	ds_read_b64_tr_b16 v[196:197], v241 offset:31104
	v_mfma_f32_32x32x16_bf16 v[84:99], v[198:201], v[108:111], v[84:99]
	ds_read_b64_tr_b16 v[198:199], v241 offset:30016
	ds_read_b64_tr_b16 v[200:201], v241 offset:31168
	v_mfma_f32_32x32x16_bf16 v[154:169], v[202:205], v[116:119], v[224:239]
	ds_read_b64_tr_b16 v[202:203], v242 offset:32256
	ds_read_b64_tr_b16 v[204:205], v242 offset:33408
	v_mfma_f32_32x32x16_bf16 v[170:185], v[206:209], v[116:119], v[224:239]
	ds_read_b64_tr_b16 v[206:207], v242 offset:32320
	ds_read_b64_tr_b16 v[208:209], v242 offset:33472
	s_nop 0
	v_exp_f32_e32 v68, v68
	v_exp_f32_e32 v69, v69
	v_exp_f32_e32 v70, v70
	v_exp_f32_e32 v71, v71
	v_exp_f32_e32 v72, v72
	v_exp_f32_e32 v73, v73
	v_exp_f32_e32 v74, v74
	v_exp_f32_e32 v75, v75
	v_mfma_f32_32x32x16_bf16 v[154:169], v[210:213], v[124:127], v[154:169]
	ds_read_b64_tr_b16 v[210:211], v242 offset:34560
	ds_read_b64_tr_b16 v[212:213], v242 offset:35712
	v_pk_add_f32 v[220:221], v[68:69], v[220:221]
	v_pk_add_f32 v[220:221], v[70:71], v[220:221]
	v_pk_add_f32 v[220:221], v[72:73], v[220:221]
	v_pk_add_f32 v[220:221], v[74:75], v[220:221]
	v_cvt_pk_bf16_f32 v68, v68, v69
	v_cvt_pk_bf16_f32 v69, v70, v71
	v_cvt_pk_bf16_f32 v70, v72, v73
	v_cvt_pk_bf16_f32 v71, v74, v75
	v_mfma_f32_32x32x16_bf16 v[170:185], v[214:217], v[124:127], v[170:185]
	ds_read_b64_tr_b16 v[214:215], v242 offset:34624
	ds_read_b64_tr_b16 v[216:217], v242 offset:35776
	v_exp_f32_e32 v154, v154
	v_exp_f32_e32 v155, v155
	v_exp_f32_e32 v156, v156
	v_exp_f32_e32 v157, v157
	v_exp_f32_e32 v158, v158
	v_exp_f32_e32 v159, v159
	v_exp_f32_e32 v160, v160
	v_exp_f32_e32 v161, v161
	s_waitcnt lgkmcnt(12)
	v_mfma_f32_32x32x16_bf16 v[4:19], v[186:189], v[68:71], v[4:19]
	v_pk_add_f32 v[246:247], v[154:155], v[246:247]
	v_pk_add_f32 v[246:247], v[156:157], v[246:247]
	v_pk_add_f32 v[246:247], v[158:159], v[246:247]
	v_pk_add_f32 v[246:247], v[160:161], v[246:247]
	v_cvt_pk_bf16_f32 v154, v154, v155
	v_cvt_pk_bf16_f32 v155, v156, v157
	v_cvt_pk_bf16_f32 v156, v158, v159
	v_cvt_pk_bf16_f32 v157, v160, v161
	v_mfma_f32_32x32x16_bf16 v[20:35], v[190:193], v[68:71], v[20:35]
	v_exp_f32_e32 v76, v76
	v_exp_f32_e32 v77, v77
	v_exp_f32_e32 v78, v78
	v_exp_f32_e32 v79, v79
	v_exp_f32_e32 v80, v80
	v_exp_f32_e32 v81, v81
	v_exp_f32_e32 v82, v82
	v_exp_f32_e32 v83, v83
	v_mfma_f32_32x32x16_bf16 v[36:51], v[186:189], v[154:157], v[36:51]
	v_pk_add_f32 v[220:221], v[76:77], v[220:221]
	v_pk_add_f32 v[220:221], v[78:79], v[220:221]
	v_pk_add_f32 v[220:221], v[80:81], v[220:221]
	v_pk_add_f32 v[220:221], v[82:83], v[220:221]
	v_cvt_pk_bf16_f32 v76, v76, v77
	v_cvt_pk_bf16_f32 v77, v78, v79
	v_cvt_pk_bf16_f32 v78, v80, v81
	v_cvt_pk_bf16_f32 v79, v82, v83
	v_mfma_f32_32x32x16_bf16 v[52:67], v[190:193], v[154:157], v[52:67]
	v_exp_f32_e32 v162, v162
	v_exp_f32_e32 v163, v163
	v_exp_f32_e32 v164, v164
	v_exp_f32_e32 v165, v165
	v_exp_f32_e32 v166, v166
	v_exp_f32_e32 v167, v167
	v_exp_f32_e32 v168, v168
	v_exp_f32_e32 v169, v169
	s_waitcnt lgkmcnt(8)
	v_mfma_f32_32x32x16_bf16 v[4:19], v[194:197], v[76:79], v[4:19]
	v_pk_add_f32 v[246:247], v[162:163], v[246:247]
	v_pk_add_f32 v[246:247], v[164:165], v[246:247]
	v_pk_add_f32 v[246:247], v[166:167], v[246:247]
	v_pk_add_f32 v[246:247], v[168:169], v[246:247]
	v_cvt_pk_bf16_f32 v162, v162, v163
	v_cvt_pk_bf16_f32 v163, v164, v165
	v_cvt_pk_bf16_f32 v164, v166, v167
	v_cvt_pk_bf16_f32 v165, v168, v169
	v_mfma_f32_32x32x16_bf16 v[20:35], v[198:201], v[76:79], v[20:35]
	v_exp_f32_e32 v84, v84
	v_exp_f32_e32 v85, v85
	v_exp_f32_e32 v86, v86
	v_exp_f32_e32 v87, v87
	v_exp_f32_e32 v88, v88
	v_exp_f32_e32 v89, v89
	v_exp_f32_e32 v90, v90
	v_exp_f32_e32 v91, v91
	v_mfma_f32_32x32x16_bf16 v[36:51], v[194:197], v[162:165], v[36:51]
	v_pk_add_f32 v[220:221], v[84:85], v[220:221]
	v_pk_add_f32 v[220:221], v[86:87], v[220:221]
	v_pk_add_f32 v[220:221], v[88:89], v[220:221]
	v_pk_add_f32 v[220:221], v[90:91], v[220:221]
	v_cvt_pk_bf16_f32 v84, v84, v85
	v_cvt_pk_bf16_f32 v85, v86, v87
	v_cvt_pk_bf16_f32 v86, v88, v89
	v_cvt_pk_bf16_f32 v87, v90, v91
	v_mfma_f32_32x32x16_bf16 v[52:67], v[198:201], v[162:165], v[52:67]
	v_exp_f32_e32 v170, v170
	v_exp_f32_e32 v171, v171
	v_exp_f32_e32 v172, v172
	v_exp_f32_e32 v173, v173
	v_exp_f32_e32 v174, v174
	v_exp_f32_e32 v175, v175
	v_exp_f32_e32 v176, v176
	v_exp_f32_e32 v177, v177
	s_waitcnt lgkmcnt(4)
	v_mfma_f32_32x32x16_bf16 v[4:19], v[202:205], v[84:87], v[4:19]
	v_pk_add_f32 v[246:247], v[170:171], v[246:247]
	v_pk_add_f32 v[246:247], v[172:173], v[246:247]
	v_pk_add_f32 v[246:247], v[174:175], v[246:247]
	v_pk_add_f32 v[246:247], v[176:177], v[246:247]
	v_cvt_pk_bf16_f32 v170, v170, v171
	v_cvt_pk_bf16_f32 v171, v172, v173
	v_cvt_pk_bf16_f32 v172, v174, v175
	v_cvt_pk_bf16_f32 v173, v176, v177
	v_mfma_f32_32x32x16_bf16 v[20:35], v[206:209], v[84:87], v[20:35]
	v_exp_f32_e32 v92, v92
	v_exp_f32_e32 v93, v93
	v_exp_f32_e32 v94, v94
	v_exp_f32_e32 v95, v95
	v_exp_f32_e32 v96, v96
	v_exp_f32_e32 v97, v97
	v_exp_f32_e32 v98, v98
	v_exp_f32_e32 v99, v99
	v_mfma_f32_32x32x16_bf16 v[36:51], v[202:205], v[170:173], v[36:51]
	v_pk_add_f32 v[220:221], v[92:93], v[220:221]
	v_pk_add_f32 v[220:221], v[94:95], v[220:221]
	v_pk_add_f32 v[220:221], v[96:97], v[220:221]
	v_pk_add_f32 v[220:221], v[98:99], v[220:221]
	v_cvt_pk_bf16_f32 v92, v92, v93
	v_cvt_pk_bf16_f32 v93, v94, v95
	v_cvt_pk_bf16_f32 v94, v96, v97
	v_cvt_pk_bf16_f32 v95, v98, v99
	v_mfma_f32_32x32x16_bf16 v[52:67], v[206:209], v[170:173], v[52:67]
	v_exp_f32_e32 v178, v178
	v_exp_f32_e32 v179, v179
	v_exp_f32_e32 v180, v180
	v_exp_f32_e32 v181, v181
	v_exp_f32_e32 v182, v182
	v_exp_f32_e32 v183, v183
	v_exp_f32_e32 v184, v184
	v_exp_f32_e32 v185, v185
	s_waitcnt lgkmcnt(0)
	v_mfma_f32_32x32x16_bf16 v[4:19], v[210:213], v[92:95], v[4:19]
	v_pk_add_f32 v[246:247], v[178:179], v[246:247]
	v_pk_add_f32 v[246:247], v[180:181], v[246:247]
	v_pk_add_f32 v[246:247], v[182:183], v[246:247]
	v_pk_add_f32 v[246:247], v[184:185], v[246:247]
	v_cvt_pk_bf16_f32 v178, v178, v179
	v_cvt_pk_bf16_f32 v179, v180, v181
	v_cvt_pk_bf16_f32 v180, v182, v183
	v_cvt_pk_bf16_f32 v181, v184, v185
	v_mfma_f32_32x32x16_bf16 v[20:35], v[214:217], v[92:95], v[20:35]
	s_nop 1
	v_mfma_f32_32x32x16_bf16 v[36:51], v[210:213], v[178:181], v[36:51]
	v_mfma_f32_32x32x16_bf16 v[52:67], v[214:217], v[178:181], v[52:67]
	v_max3_f32 v248, v220, v221, v246
	v_max_f32_e32 v248, v248, v247
	v_cmp_lt_f32_e32 vcc, 0x49800000, v248
	s_cbranch_vccz .Lat_norescale_b
	v_add_f32_e32 v250, v220, v221
	v_add_f32_e32 v251, v246, v247
	v_lshlrev_b32_e32 v249, 2, v222
	v_xor_b32_e32 v249, 0x80, v249
	v_and_b32_e32 v249, 0xfc, v249
	ds_bpermute_b32 v68, v249, v250
	ds_bpermute_b32 v69, v249, v251
	s_waitcnt lgkmcnt(0)
	v_add_f32_e32 v250, v250, v68
	v_add_f32_e32 v251, v251, v69
	v_max_f32_e32 v250, v250, v251
	v_log_f32_e32 v250, v250
	s_nop 0
	v_max_f32_e32 v250, 0, v250
	v_add_f32_e32 v244, v244, v250
	v_exp_f32_e64 v248, -v250
	v_xor_b32_e32 v224, 0x80000000, v244
	v_mov_b32_e32 v225, v224
	v_mov_b32_e32 v226, v224
	v_mov_b32_e32 v227, v224
	v_mov_b32_e32 v228, v224
	v_mov_b32_e32 v229, v224
	v_mov_b32_e32 v230, v224
	v_mov_b32_e32 v231, v224
	v_mov_b32_e32 v232, v224
	v_mov_b32_e32 v233, v224
	v_mov_b32_e32 v234, v224
	v_mov_b32_e32 v235, v224
	v_mov_b32_e32 v236, v224
	v_mov_b32_e32 v237, v224
	v_mov_b32_e32 v238, v224
	v_mov_b32_e32 v239, v224
	v_mul_f32_e32 v220, v220, v248
	v_mul_f32_e32 v221, v221, v248
	v_mul_f32_e32 v246, v246, v248
	v_mul_f32_e32 v247, v247, v248
	v_pk_mul_f32 v[4:5], v[4:5], v[248:249] op_sel_hi:[1,0]
	v_pk_mul_f32 v[6:7], v[6:7], v[248:249] op_sel_hi:[1,0]
	v_pk_mul_f32 v[8:9], v[8:9], v[248:249] op_sel_hi:[1,0]
	v_pk_mul_f32 v[10:11], v[10:11], v[248:249] op_sel_hi:[1,0]
	v_pk_mul_f32 v[12:13], v[12:13], v[248:249] op_sel_hi:[1,0]
	v_pk_mul_f32 v[14:15], v[14:15], v[248:249] op_sel_hi:[1,0]
	v_pk_mul_f32 v[16:17], v[16:17], v[248:249] op_sel_hi:[1,0]
	v_pk_mul_f32 v[18:19], v[18:19], v[248:249] op_sel_hi:[1,0]
	v_pk_mul_f32 v[20:21], v[20:21], v[248:249] op_sel_hi:[1,0]
	v_pk_mul_f32 v[22:23], v[22:23], v[248:249] op_sel_hi:[1,0]
	v_pk_mul_f32 v[24:25], v[24:25], v[248:249] op_sel_hi:[1,0]
	v_pk_mul_f32 v[26:27], v[26:27], v[248:249] op_sel_hi:[1,0]
	v_pk_mul_f32 v[28:29], v[28:29], v[248:249] op_sel_hi:[1,0]
	v_pk_mul_f32 v[30:31], v[30:31], v[248:249] op_sel_hi:[1,0]
	v_pk_mul_f32 v[32:33], v[32:33], v[248:249] op_sel_hi:[1,0]
	v_pk_mul_f32 v[34:35], v[34:35], v[248:249] op_sel_hi:[1,0]
	v_pk_mul_f32 v[36:37], v[36:37], v[248:249] op_sel_hi:[1,0]
	v_pk_mul_f32 v[38:39], v[38:39], v[248:249] op_sel_hi:[1,0]
	v_pk_mul_f32 v[40:41], v[40:41], v[248:249] op_sel_hi:[1,0]
	v_pk_mul_f32 v[42:43], v[42:43], v[248:249] op_sel_hi:[1,0]
	v_pk_mul_f32 v[44:45], v[44:45], v[248:249] op_sel_hi:[1,0]
	v_pk_mul_f32 v[46:47], v[46:47], v[248:249] op_sel_hi:[1,0]
	v_pk_mul_f32 v[48:49], v[48:49], v[248:249] op_sel_hi:[1,0]
	v_pk_mul_f32 v[50:51], v[50:51], v[248:249] op_sel_hi:[1,0]
	v_pk_mul_f32 v[52:53], v[52:53], v[248:249] op_sel_hi:[1,0]
	v_pk_mul_f32 v[54:55], v[54:55], v[248:249] op_sel_hi:[1,0]
	v_pk_mul_f32 v[56:57], v[56:57], v[248:249] op_sel_hi:[1,0]
	v_pk_mul_f32 v[58:59], v[58:59], v[248:249] op_sel_hi:[1,0]
	v_pk_mul_f32 v[60:61], v[60:61], v[248:249] op_sel_hi:[1,0]
	v_pk_mul_f32 v[62:63], v[62:63], v[248:249] op_sel_hi:[1,0]
	v_pk_mul_f32 v[64:65], v[64:65], v[248:249] op_sel_hi:[1,0]
	v_pk_mul_f32 v[66:67], v[66:67], v[248:249] op_sel_hi:[1,0]

.LBB0_902:
	s_or_b64 exec, exec, s[0:1]
	s_waitcnt lgkmcnt(0)
	s_barrier
	ds_read_b32 v0, v3 offset:16
	s_movk_i32 s0, 0xa9f
	s_waitcnt lgkmcnt(0)
	v_cmp_lt_i32_e32 vcc, s0, v0
	v_readfirstlane_b32 s10, v0
	s_mov_b64 s[0:1], -1
	s_cbranch_vccnz .LBB0_897
	s_cmpk_gt_i32 s10, 0x21f
	s_cbranch_scc0 .LBB0_913
	s_add_i32 s0, s10, 0xfde0
	s_and_b32 s1, s0, 0xffff
	s_mul_i32 s1, s1, 0xf0f1
	s_lshr_b32 s4, s1, 22
	s_mulk_i32 s4, 0x44
	s_sub_i32 s0, s0, s4
	s_and_b32 s4, s0, 0xffff
	s_lshr_b32 s5, s1, 24
	s_mul_i32 s11, s5, 0x1100
	s_lshl_b32 s0, s4, 6
	s_add_i32 s11, s11, s0
	s_mul_i32 s0, s11, 0x1c00
	s_bfe_u32 s6, s1, 0x20016
	s_waitcnt vmcnt(10)
	v_mov_b32_e32 v58, v222
	s_add_u32 s0, s24, s0
	v_mov_b32_e32 v8, v222
	s_addc_u32 s1, s25, 0
	s_lshl_b32 s33, s6, 6
	v_and_b32_e32 v0, 63, v8
	v_or_b32_e32 v1, s33, v0
	v_ashrrev_i32_e32 v9, 6, v8
	v_lshlrev_b32_e32 v2, 1, v1
	v_lshlrev_b32_e32 v11, 4, v9
	v_lshl_add_u64 v[4:5], s[0:1], 0, v[2:3]
	v_mad_i64_i32 v[6:7], s[8:9], v11, s48, v[4:5]
	v_mad_i64_i32 v[128:129], s[8:9], v11, s48, v[4:5]
	global_load_ushort v96, v[128:129], off offset:1024
	global_load_ushort v80, v[128:129], off offset:2048
	global_load_ushort v112, v[128:129], off offset:2560
	v_or_b32_e32 v137, 1, v11
	v_mad_i64_i32 v[130:131], s[8:9], v137, s48, v[4:5]
	global_load_ushort v97, v[130:131], off offset:1024
	global_load_ushort v81, v[130:131], off offset:2048
	global_load_ushort v113, v[130:131], off offset:2560
	v_or_b32_e32 v138, 2, v11
	v_mad_i64_i32 v[132:133], s[8:9], v138, s48, v[4:5]
	global_load_ushort v98, v[132:133], off offset:1024
	global_load_ushort v82, v[132:133], off offset:2048
	global_load_ushort v114, v[132:133], off offset:2560
	v_or_b32_e32 v139, 3, v11
	v_mad_i64_i32 v[134:135], s[8:9], v139, s48, v[4:5]
	global_load_ushort v99, v[134:135], off offset:1024
	global_load_ushort v83, v[134:135], off offset:2048
	global_load_ushort v115, v[134:135], off offset:2560
	v_or_b32_e32 v136, 4, v11
	v_mad_i64_i32 v[128:129], s[8:9], v136, s48, v[4:5]
	global_load_ushort v100, v[128:129], off offset:1024
	global_load_ushort v84, v[128:129], off offset:2048
	global_load_ushort v116, v[128:129], off offset:2560
	v_or_b32_e32 v137, 5, v11
	v_mad_i64_i32 v[130:131], s[8:9], v137, s48, v[4:5]
	global_load_ushort v101, v[130:131], off offset:1024
	global_load_ushort v85, v[130:131], off offset:2048
	global_load_ushort v117, v[130:131], off offset:2560
	v_or_b32_e32 v138, 6, v11
	v_mad_i64_i32 v[132:133], s[8:9], v138, s48, v[4:5]
	global_load_ushort v102, v[132:133], off offset:1024
	global_load_ushort v86, v[132:133], off offset:2048
	global_load_ushort v118, v[132:133], off offset:2560
	v_or_b32_e32 v139, 7, v11
	v_mad_i64_i32 v[134:135], s[8:9], v139, s48, v[4:5]
	global_load_ushort v103, v[134:135], off offset:1024
	global_load_ushort v87, v[134:135], off offset:2048
	global_load_ushort v119, v[134:135], off offset:2560
	v_or_b32_e32 v136, 8, v11
	v_mad_i64_i32 v[128:129], s[8:9], v136, s48, v[4:5]
	global_load_ushort v104, v[128:129], off offset:1024
	global_load_ushort v88, v[128:129], off offset:2048
	global_load_ushort v120, v[128:129], off offset:2560
	v_or_b32_e32 v137, 9, v11
	v_mad_i64_i32 v[130:131], s[8:9], v137, s48, v[4:5]
	global_load_ushort v105, v[130:131], off offset:1024
	global_load_ushort v89, v[130:131], off offset:2048
	global_load_ushort v121, v[130:131], off offset:2560
	v_or_b32_e32 v138, 10, v11
	v_mad_i64_i32 v[132:133], s[8:9], v138, s48, v[4:5]
	global_load_ushort v106, v[132:133], off offset:1024
	global_load_ushort v90, v[132:133], off offset:2048
	global_load_ushort v122, v[132:133], off offset:2560
	v_or_b32_e32 v139, 11, v11
	v_mad_i64_i32 v[134:135], s[8:9], v139, s48, v[4:5]
	global_load_ushort v107, v[134:135], off offset:1024
	global_load_ushort v91, v[134:135], off offset:2048
	global_load_ushort v123, v[134:135], off offset:2560
	v_or_b32_e32 v136, 12, v11
	v_mad_i64_i32 v[128:129], s[8:9], v136, s48, v[4:5]
	global_load_ushort v108, v[128:129], off offset:1024
	global_load_ushort v92, v[128:129], off offset:2048
	global_load_ushort v124, v[128:129], off offset:2560
	v_or_b32_e32 v137, 13, v11
	v_mad_i64_i32 v[130:131], s[8:9], v137, s48, v[4:5]
	global_load_ushort v109, v[130:131], off offset:1024
	global_load_ushort v93, v[130:131], off offset:2048
	global_load_ushort v125, v[130:131], off offset:2560
	v_or_b32_e32 v138, 14, v11
	v_mad_i64_i32 v[132:133], s[8:9], v138, s48, v[4:5]
	global_load_ushort v110, v[132:133], off offset:1024
	global_load_ushort v94, v[132:133], off offset:2048
	global_load_ushort v126, v[132:133], off offset:2560
	v_or_b32_e32 v139, 15, v11
	v_mad_i64_i32 v[134:135], s[8:9], v139, s48, v[4:5]
	global_load_ushort v111, v[134:135], off offset:1024
	global_load_ushort v95, v[134:135], off offset:2048
	global_load_ushort v127, v[134:135], off offset:2560
	s_barrier
	s_waitcnt vmcnt(0)
	v_mov_b32_e32 v1, v80
	v_or_b32_e32 v2, 13, v11
	v_or_b32_e32 v43, 1, v11
	v_mad_i64_i32 v[24:25], s[8:9], v2, s48, v[4:5]
	v_or_b32_e32 v20, 15, v11
	s_movk_i32 s38, 0x500
	v_mul_lo_u32 v55, v9, s38
	v_or_b32_e32 v55, v55, v0
	v_lshl_add_u32 v55, v55, 1, 32
	s_movk_i32 s39, 0x50
	s_lshl_b32 s22, s6, 7
	s_movk_i32 s42, 0xa0
	s_lshl_b32 s5, s5, 3
	s_lshl_b32 s6, s6, 1
	s_or_b32 s5, s6, s5
	s_mulk_i32 s5, 0x44
	s_add_i32 s5, s5, s4
	s_lshl_b32 s4, s5, 12
	s_mov_b32 s5, s23
	v_bfe_u32 v10, v8, 4, 2
	s_lshl_b64 s[4:5], s[4:5], 2
	s_add_u32 s12, s2, s4
	s_addc_u32 s13, s3, s5
	v_and_b32_e32 v56, 15, v58
	v_bfe_u32 v57, v58, 4, 2
	v_mov_b32_e32 v2, v93
	s_waitcnt vmcnt(1)
	v_lshlrev_b32_e32 v47, 16, v1
	v_mov_b32_e32 v1, v96
	v_mad_i64_i32 v[6:7], s[8:9], v43, s48, v[4:5]
	v_add_f32_e32 v48, 0, v47
	v_mul_f32_e32 v59, 0x3fb8aa3b, v48
	v_exp_f32_e32 v59, v59
	v_mul_f32_e32 v47, 0x3fb8aa3b, v47
	v_exp_f32_e32 v47, v47
	s_waitcnt vmcnt(0)
	v_lshlrev_b32_e32 v46, 16, v1
	v_mov_b32_e32 v1, v81
	v_mul_f32_e32 v46, v59, v46
	v_cvt_pk_bf16_f32 v46, v46, s0
	ds_write_b16 v55, v46
	v_min_f32_e64 v46, -v48, s40
	v_mul_f32_e32 v46, 0x3fb8aa3b, v46
	v_exp_f32_e32 v46, v46
	v_sub_f32_e32 v47, 1.0, v47
	v_mul_f32_e32 v46, v47, v46
	v_cvt_pk_bf16_f32 v46, v46, s0
	ds_write_b16 v55, v46 offset:10240
	s_waitcnt vmcnt(0)
	v_lshlrev_b32_e32 v44, 16, v1
	v_mov_b32_e32 v1, v97
	v_add_f32_e32 v49, v48, v44
	v_mul_f32_e32 v44, 0x3fb8aa3b, v44
	v_exp_f32_e32 v44, v44
	s_waitcnt vmcnt(0)
	v_lshlrev_b32_e32 v42, 16, v1
	v_or_b32_e32 v1, 2, v11
	v_mad_i64_i32 v[6:7], s[8:9], v1, s48, v[4:5]
	v_mov_b32_e32 v1, v82
	v_sub_f32_e32 v44, 1.0, v44
	s_waitcnt vmcnt(0)
	v_lshlrev_b32_e32 v40, 16, v1
	v_mov_b32_e32 v1, v98
	v_add_f32_e32 v50, v49, v40
	v_mul_f32_e32 v40, 0x3fb8aa3b, v40
	v_exp_f32_e32 v40, v40
	s_waitcnt vmcnt(0)
	v_lshlrev_b32_e32 v39, 16, v1
	v_or_b32_e32 v1, 3, v11
	v_mad_i64_i32 v[6:7], s[8:9], v1, s48, v[4:5]
	v_mov_b32_e32 v1, v83
	v_sub_f32_e32 v40, 1.0, v40
	s_waitcnt vmcnt(0)
	v_lshlrev_b32_e32 v38, 16, v1
	v_mov_b32_e32 v1, v99
	v_add_f32_e32 v51, v50, v38
	v_mul_f32_e32 v38, 0x3fb8aa3b, v38
	v_exp_f32_e32 v38, v38
	s_waitcnt vmcnt(0)
	v_lshlrev_b32_e32 v36, 16, v1
	v_or_b32_e32 v1, 4, v11
	v_mad_i64_i32 v[6:7], s[8:9], v1, s48, v[4:5]
	v_mov_b32_e32 v1, v84
	v_sub_f32_e32 v38, 1.0, v38
	s_waitcnt vmcnt(0)
	v_lshlrev_b32_e32 v35, 16, v1
	v_mov_b32_e32 v1, v100
	v_add_f32_e32 v52, v51, v35
	v_mul_f32_e32 v35, 0x3fb8aa3b, v35
	v_exp_f32_e32 v35, v35
	s_waitcnt vmcnt(0)
	v_lshlrev_b32_e32 v34, 16, v1
	v_or_b32_e32 v1, 5, v11
	v_mad_i64_i32 v[6:7], s[8:9], v1, s48, v[4:5]
	v_mov_b32_e32 v1, v85
	v_sub_f32_e32 v35, 1.0, v35
	s_waitcnt vmcnt(0)
	v_lshlrev_b32_e32 v32, 16, v1
	v_mov_b32_e32 v1, v101
	v_add_f32_e32 v53, v52, v32
	v_mul_f32_e32 v32, 0x3fb8aa3b, v32
	v_exp_f32_e32 v32, v32
	s_waitcnt vmcnt(0)
	v_lshlrev_b32_e32 v31, 16, v1
	v_or_b32_e32 v1, 6, v11
	v_mad_i64_i32 v[6:7], s[8:9], v1, s48, v[4:5]
	v_mov_b32_e32 v1, v86
	v_sub_f32_e32 v32, 1.0, v32
	s_waitcnt vmcnt(0)
	v_lshlrev_b32_e32 v30, 16, v1
	v_mov_b32_e32 v1, v102
	v_add_f32_e32 v54, v53, v30
	v_mul_f32_e32 v30, 0x3fb8aa3b, v30
	v_exp_f32_e32 v30, v30
	s_waitcnt vmcnt(0)
	v_lshlrev_b32_e32 v28, 16, v1
	v_or_b32_e32 v1, 7, v11
	v_mad_i64_i32 v[6:7], s[8:9], v1, s48, v[4:5]
	v_mov_b32_e32 v1, v87
	v_sub_f32_e32 v30, 1.0, v30
	s_waitcnt vmcnt(0)
	v_lshlrev_b32_e32 v27, 16, v1
	v_mov_b32_e32 v1, v103
	v_add_f32_e32 v45, v54, v27
	v_mul_f32_e32 v27, 0x3fb8aa3b, v27
	v_exp_f32_e32 v27, v27
	s_waitcnt vmcnt(0)
	v_lshlrev_b32_e32 v26, 16, v1
	v_or_b32_e32 v1, 8, v11
	v_mad_i64_i32 v[6:7], s[8:9], v1, s48, v[4:5]
	v_mov_b32_e32 v1, v88
	v_sub_f32_e32 v27, 1.0, v27
	s_waitcnt vmcnt(0)
	v_lshlrev_b32_e32 v23, 16, v1
	v_mov_b32_e32 v1, v104
	v_add_f32_e32 v41, v45, v23
	v_mul_f32_e32 v23, 0x3fb8aa3b, v23
	v_exp_f32_e32 v23, v23
	s_waitcnt vmcnt(0)
	v_lshlrev_b32_e32 v21, 16, v1
	v_or_b32_e32 v1, 9, v11
	v_mad_i64_i32 v[6:7], s[8:9], v1, s48, v[4:5]
	v_mov_b32_e32 v1, v89
	v_sub_f32_e32 v23, 1.0, v23
	s_waitcnt vmcnt(0)
	v_lshlrev_b32_e32 v19, 16, v1
	v_mov_b32_e32 v1, v105
	v_add_f32_e32 v37, v41, v19
	v_mul_f32_e32 v19, 0x3fb8aa3b, v19
	v_exp_f32_e32 v19, v19
	s_waitcnt vmcnt(0)
	v_lshlrev_b32_e32 v18, 16, v1
	v_or_b32_e32 v1, 10, v11
	v_mad_i64_i32 v[6:7], s[8:9], v1, s48, v[4:5]
	v_mov_b32_e32 v1, v90
	v_sub_f32_e32 v19, 1.0, v19
	s_waitcnt vmcnt(0)
	v_lshlrev_b32_e32 v17, 16, v1
	v_mov_b32_e32 v1, v106
	v_add_f32_e32 v33, v37, v17
	v_mul_f32_e32 v17, 0x3fb8aa3b, v17
	v_exp_f32_e32 v17, v17
	s_waitcnt vmcnt(0)
	v_lshlrev_b32_e32 v16, 16, v1
	v_or_b32_e32 v1, 11, v11
	v_mad_i64_i32 v[6:7], s[8:9], v1, s48, v[4:5]
	v_mov_b32_e32 v1, v91
	v_sub_f32_e32 v17, 1.0, v17
	s_waitcnt vmcnt(0)
	v_lshlrev_b32_e32 v15, 16, v1
	v_mov_b32_e32 v1, v107
	v_add_f32_e32 v29, v33, v15
	v_mul_f32_e32 v15, 0x3fb8aa3b, v15
	v_exp_f32_e32 v15, v15
	s_waitcnt vmcnt(0)
	v_lshlrev_b32_e32 v14, 16, v1
	v_or_b32_e32 v1, 12, v11
	v_mad_i64_i32 v[6:7], s[8:9], v1, s48, v[4:5]
	v_mov_b32_e32 v1, v92
	v_sub_f32_e32 v15, 1.0, v15
	s_waitcnt vmcnt(0)
	v_lshlrev_b32_e32 v13, 16, v1
	v_mov_b32_e32 v1, v108
	v_or_b32_e32 v6, 14, v11
	v_lshlrev_b32_e32 v7, 16, v2
	v_mov_b32_e32 v2, v109
	v_mad_i64_i32 v[24:25], s[8:9], v6, s48, v[4:5]
	v_mov_b32_e32 v6, v94
	s_waitcnt vmcnt(2)
	v_lshlrev_b32_e32 v1, 16, v1
	s_waitcnt vmcnt(1)
	v_lshlrev_b32_e32 v2, 16, v2
	s_waitcnt vmcnt(0)
	v_lshlrev_b32_e32 v12, 16, v6
	v_mov_b32_e32 v6, v110
	v_mad_i64_i32 v[24:25], s[8:9], v20, s48, v[4:5]
	v_mov_b32_e32 v4, v95
	v_mov_b32_e32 v5, v111
	v_add_f32_e32 v25, v29, v13
	v_add_f32_e32 v24, v25, v7
	v_add_f32_e32 v22, v24, v12
	v_mul_f32_e32 v13, 0x3fb8aa3b, v13
	v_exp_f32_e32 v13, v13
	s_waitcnt vmcnt(2)
	v_lshlrev_b32_e32 v6, 16, v6
	v_sub_f32_e32 v13, 1.0, v13
	s_waitcnt vmcnt(1)
	v_lshlrev_b32_e32 v4, 16, v4
	v_add_f32_e32 v20, v22, v4
	v_sub_f32_e32 v46, v20, v48
	v_mul_f32_e32 v46, 0x3fb8aa3b, v46
	v_exp_f32_e32 v46, v46
	s_waitcnt vmcnt(0)
	v_lshlrev_b32_e32 v5, 16, v5
	v_mul_f32_e32 v46, v47, v46
	v_cvt_pk_bf16_f32 v46, v46, s0
	ds_write_b16 v55, v46 offset:20480
	v_mad_u64_u32 v[46:47], s[8:9], v43, s39, v[0:1]
	v_mul_f32_e32 v0, 0x3fb8aa3b, v49
	v_exp_f32_e32 v0, v0
	s_nop 0
	v_mul_f32_e32 v0, v0, v42
	v_cvt_pk_bf16_f32 v42, v0, s0
	v_lshl_add_u32 v0, v46, 1, 32
	ds_write_b16 v0, v42
	v_min_f32_e64 v42, -v49, s40
	v_mul_f32_e32 v42, 0x3fb8aa3b, v42
	v_exp_f32_e32 v42, v42
	s_nop 0
	v_mul_f32_e32 v42, v44, v42
	v_cvt_pk_bf16_f32 v42, v42, s0
	ds_write_b16 v0, v42 offset:10240
	v_sub_f32_e32 v42, v20, v49
	v_mul_f32_e32 v42, 0x3fb8aa3b, v42
	v_exp_f32_e32 v42, v42
	s_nop 0
	v_mul_f32_e32 v42, v44, v42
	v_cvt_pk_bf16_f32 v42, v42, s0
	ds_write_b16 v0, v42 offset:20480
	v_mul_f32_e32 v42, 0x3fb8aa3b, v50
	v_exp_f32_e32 v42, v42
	s_nop 0
	v_mul_f32_e32 v39, v42, v39
	v_cvt_pk_bf16_f32 v39, v39, s0
	ds_write_b16 v0, v39 offset:160
	v_min_f32_e64 v39, -v50, s40
	v_mul_f32_e32 v39, 0x3fb8aa3b, v39
	v_exp_f32_e32 v39, v39
	s_nop 0
	v_mul_f32_e32 v39, v40, v39
	v_cvt_pk_bf16_f32 v39, v39, s0
	ds_write_b16 v0, v39 offset:10400
	v_sub_f32_e32 v39, v20, v50
	v_mul_f32_e32 v39, 0x3fb8aa3b, v39
	v_exp_f32_e32 v39, v39
	s_nop 0
	v_mul_f32_e32 v39, v40, v39
	v_cvt_pk_bf16_f32 v39, v39, s0
	ds_write_b16 v0, v39 offset:20640
	v_mul_f32_e32 v39, 0x3fb8aa3b, v51
	v_exp_f32_e32 v39, v39
	s_nop 0
	v_mul_f32_e32 v36, v39, v36
	v_cvt_pk_bf16_f32 v36, v36, s0
	ds_write_b16 v0, v36 offset:320
	v_min_f32_e64 v36, -v51, s40
	v_mul_f32_e32 v36, 0x3fb8aa3b, v36
	v_exp_f32_e32 v36, v36
	s_nop 0
	v_mul_f32_e32 v36, v38, v36
	v_cvt_pk_bf16_f32 v36, v36, s0
	ds_write_b16 v0, v36 offset:10560
	v_sub_f32_e32 v36, v20, v51
	v_mul_f32_e32 v36, 0x3fb8aa3b, v36
	v_exp_f32_e32 v36, v36
	s_nop 0
	v_mul_f32_e32 v36, v38, v36
	v_cvt_pk_bf16_f32 v36, v36, s0
	ds_write_b16 v0, v36 offset:20800
	v_mul_f32_e32 v36, 0x3fb8aa3b, v52
	v_exp_f32_e32 v36, v36
	v_lshlrev_b32_e32 v38, 3, v10
	v_mul_f32_e32 v34, v36, v34
	v_cvt_pk_bf16_f32 v34, v34, s0
	ds_write_b16 v0, v34 offset:480
	v_min_f32_e64 v34, -v52, s40
	v_mul_f32_e32 v34, 0x3fb8aa3b, v34
	v_exp_f32_e32 v34, v34
	s_nop 0
	v_mul_f32_e32 v34, v35, v34
	v_cvt_pk_bf16_f32 v34, v34, s0
	ds_write_b16 v0, v34 offset:10720
	v_sub_f32_e32 v34, v20, v52
	v_mul_f32_e32 v34, 0x3fb8aa3b, v34
	v_exp_f32_e32 v34, v34
	s_nop 0
	v_mul_f32_e32 v34, v35, v34
	v_cvt_pk_bf16_f32 v34, v34, s0
	ds_write_b16 v0, v34 offset:20960
	v_mul_f32_e32 v34, 0x3fb8aa3b, v53
	v_exp_f32_e32 v34, v34
	s_nop 0
	v_mul_f32_e32 v31, v34, v31
	v_cvt_pk_bf16_f32 v31, v31, s0
	ds_write_b16 v0, v31 offset:640
	v_min_f32_e64 v31, -v53, s40
	v_mul_f32_e32 v31, 0x3fb8aa3b, v31
	v_exp_f32_e32 v31, v31
	s_nop 0
	v_mul_f32_e32 v31, v32, v31
	v_cvt_pk_bf16_f32 v31, v31, s0
	ds_write_b16 v0, v31 offset:10880
	v_sub_f32_e32 v31, v20, v53
	v_mul_f32_e32 v31, 0x3fb8aa3b, v31
	v_exp_f32_e32 v31, v31
	s_nop 0
	v_mul_f32_e32 v31, v32, v31
	v_cvt_pk_bf16_f32 v31, v31, s0
	ds_write_b16 v0, v31 offset:21120
	v_mul_f32_e32 v31, 0x3fb8aa3b, v54
	v_exp_f32_e32 v31, v31
	s_nop 0
	v_mul_f32_e32 v28, v31, v28
	v_cvt_pk_bf16_f32 v28, v28, s0
	ds_write_b16 v0, v28 offset:800
	v_min_f32_e64 v28, -v54, s40
	v_mul_f32_e32 v28, 0x3fb8aa3b, v28
	v_exp_f32_e32 v28, v28
	s_nop 0
	v_mul_f32_e32 v28, v30, v28
	v_cvt_pk_bf16_f32 v28, v28, s0
	ds_write_b16 v0, v28 offset:11040
	v_sub_f32_e32 v28, v20, v54
	v_mul_f32_e32 v28, 0x3fb8aa3b, v28
	v_exp_f32_e32 v28, v28
	s_nop 0
	v_mul_f32_e32 v28, v30, v28
	v_cvt_pk_bf16_f32 v28, v28, s0
	ds_write_b16 v0, v28 offset:21280
	v_mul_f32_e32 v28, 0x3fb8aa3b, v45
	v_exp_f32_e32 v28, v28
	s_nop 0
	v_mul_f32_e32 v26, v28, v26
	v_cvt_pk_bf16_f32 v26, v26, s0
	ds_write_b16 v0, v26 offset:960
	v_min_f32_e64 v26, -v45, s40
	v_mul_f32_e32 v26, 0x3fb8aa3b, v26
	v_exp_f32_e32 v26, v26
	s_nop 0
	v_mul_f32_e32 v26, v27, v26
	v_cvt_pk_bf16_f32 v26, v26, s0
	ds_write_b16 v0, v26 offset:11200
	v_sub_f32_e32 v26, v20, v45
	v_mul_f32_e32 v26, 0x3fb8aa3b, v26
	v_exp_f32_e32 v26, v26
	s_nop 0
	v_mul_f32_e32 v26, v27, v26
	v_cvt_pk_bf16_f32 v26, v26, s0
	ds_write_b16 v0, v26 offset:21440
	v_mul_f32_e32 v26, 0x3fb8aa3b, v41
	v_exp_f32_e32 v26, v26
	s_nop 0
	v_mul_f32_e32 v21, v26, v21
	v_cvt_pk_bf16_f32 v21, v21, s0
	ds_write_b16 v0, v21 offset:1120
	v_min_f32_e64 v21, -v41, s40
	v_mul_f32_e32 v21, 0x3fb8aa3b, v21
	v_exp_f32_e32 v21, v21
	s_nop 0
	v_mul_f32_e32 v21, v23, v21
	v_cvt_pk_bf16_f32 v21, v21, s0
	ds_write_b16 v0, v21 offset:11360
	v_sub_f32_e32 v21, v20, v41
	v_mul_f32_e32 v21, 0x3fb8aa3b, v21
	v_exp_f32_e32 v21, v21
	v_mov_b64_e32 v[40:41], s[0:1]
	v_mul_f32_e32 v21, v23, v21
	v_cvt_pk_bf16_f32 v21, v21, s0
	ds_write_b16 v0, v21 offset:21600
	v_mul_f32_e32 v21, 0x3fb8aa3b, v37
	v_exp_f32_e32 v21, v21
	s_nop 0
	v_mul_f32_e32 v18, v21, v18
	v_cvt_pk_bf16_f32 v18, v18, s0
	ds_write_b16 v0, v18 offset:1280
	v_min_f32_e64 v18, -v37, s40
	v_mul_f32_e32 v18, 0x3fb8aa3b, v18
	v_exp_f32_e32 v18, v18
	s_nop 0
	v_mul_f32_e32 v18, v19, v18
	v_cvt_pk_bf16_f32 v18, v18, s0
	ds_write_b16 v0, v18 offset:11520
	v_sub_f32_e32 v18, v20, v37
	v_mul_f32_e32 v18, 0x3fb8aa3b, v18
	v_exp_f32_e32 v18, v18
	v_lshl_add_u32 v37, v9, 5, 32
	v_mul_f32_e32 v18, v19, v18
	v_cvt_pk_bf16_f32 v18, v18, s0
	ds_write_b16 v0, v18 offset:21760
	v_mul_f32_e32 v18, 0x3fb8aa3b, v33
	v_exp_f32_e32 v18, v18
	s_nop 0
	v_mul_f32_e32 v16, v18, v16
	v_cvt_pk_bf16_f32 v16, v16, s0
	ds_write_b16 v0, v16 offset:1440
	v_min_f32_e64 v16, -v33, s40
	v_mul_f32_e32 v16, 0x3fb8aa3b, v16
	v_exp_f32_e32 v16, v16
	s_nop 0
	v_mul_f32_e32 v16, v17, v16
	v_cvt_pk_bf16_f32 v16, v16, s0
	ds_write_b16 v0, v16 offset:11680
	v_sub_f32_e32 v16, v20, v33
	v_mul_f32_e32 v16, 0x3fb8aa3b, v16
	v_exp_f32_e32 v16, v16
	v_lshlrev_b32_e32 v33, 2, v10
	v_mul_f32_e32 v16, v17, v16
	v_cvt_pk_bf16_f32 v16, v16, s0
	ds_write_b16 v0, v16 offset:21920
	v_mul_f32_e32 v16, 0x3fb8aa3b, v29
	v_exp_f32_e32 v16, v16
	s_nop 0
	v_mul_f32_e32 v14, v16, v14
	v_cvt_pk_bf16_f32 v14, v14, s0
	ds_write_b16 v0, v14 offset:1600
	v_min_f32_e64 v14, -v29, s40
	v_mul_f32_e32 v14, 0x3fb8aa3b, v14
	v_exp_f32_e32 v14, v14
	s_nop 0
	v_mul_f32_e32 v14, v15, v14
	v_cvt_pk_bf16_f32 v14, v14, s0
	ds_write_b16 v0, v14 offset:11840
	v_sub_f32_e32 v14, v20, v29
	v_mul_f32_e32 v14, 0x3fb8aa3b, v14
	v_exp_f32_e32 v14, v14
	s_nop 0
	v_mul_f32_e32 v14, v15, v14
	v_cvt_pk_bf16_f32 v14, v14, s0
	ds_write_b16 v0, v14 offset:22080
	v_mul_f32_e32 v14, 0x3fb8aa3b, v25
	v_exp_f32_e32 v14, v14
	s_nop 0
	v_mul_f32_e32 v1, v14, v1
	v_cvt_pk_bf16_f32 v1, v1, s0
	ds_write_b16 v0, v1 offset:1760
	v_min_f32_e64 v1, -v25, s40
	v_mul_f32_e32 v1, 0x3fb8aa3b, v1
	v_exp_f32_e32 v1, v1
	s_nop 0
	v_mul_f32_e32 v1, v13, v1
	v_cvt_pk_bf16_f32 v1, v1, s0
	ds_write_b16 v0, v1 offset:12000
	v_sub_f32_e32 v1, v20, v25
	v_mul_f32_e32 v1, 0x3fb8aa3b, v1
	v_exp_f32_e32 v1, v1
	s_nop 0
	v_mul_f32_e32 v1, v13, v1
	v_cvt_pk_bf16_f32 v1, v1, s0
	ds_write_b16 v0, v1 offset:22240
	v_mul_f32_e32 v1, 0x3fb8aa3b, v7
	v_mul_f32_e32 v7, 0x3fb8aa3b, v24
	v_exp_f32_e32 v7, v7
	v_exp_f32_e32 v1, v1
	v_mul_f32_e32 v2, v7, v2
	v_cvt_pk_bf16_f32 v2, v2, s0
	ds_write_b16 v0, v2 offset:1920
	v_min_f32_e64 v2, -v24, s40
	v_mul_f32_e32 v2, 0x3fb8aa3b, v2
	v_exp_f32_e32 v2, v2
	v_sub_f32_e32 v1, 1.0, v1
	v_mul_f32_e32 v2, v1, v2
	v_cvt_pk_bf16_f32 v2, v2, s0
	ds_write_b16 v0, v2 offset:12160
	v_sub_f32_e32 v2, v20, v24
	v_mul_f32_e32 v2, 0x3fb8aa3b, v2
	v_exp_f32_e32 v2, v2
	s_nop 0
	v_mul_f32_e32 v1, v1, v2
	v_mul_f32_e32 v2, 0x3fb8aa3b, v22
	v_exp_f32_e32 v2, v2
	v_cvt_pk_bf16_f32 v1, v1, s0
	ds_write_b16 v0, v1 offset:22400
	v_mul_f32_e32 v1, 0x3fb8aa3b, v12
	v_mul_f32_e32 v2, v2, v6
	v_cvt_pk_bf16_f32 v2, v2, s0
	ds_write_b16 v0, v2 offset:2080
	v_min_f32_e64 v2, -v22, s40
	v_exp_f32_e32 v1, v1
	v_mul_f32_e32 v2, 0x3fb8aa3b, v2
	v_exp_f32_e32 v2, v2
	v_lshlrev_b32_e32 v12, 2, v8
	v_sub_f32_e32 v1, 1.0, v1
	v_and_b32_e32 v35, 12, v12
	v_mul_f32_e32 v2, v1, v2
	v_cvt_pk_bf16_f32 v2, v2, s0
	ds_write_b16 v0, v2 offset:12320
	v_sub_f32_e32 v2, v20, v22
	v_mul_f32_e32 v2, 0x3fb8aa3b, v2
	v_exp_f32_e32 v2, v2
	s_nop 0
	v_mul_f32_e32 v1, v1, v2
	v_mul_f32_e32 v2, 0x3fb8aa3b, v20
	v_exp_f32_e32 v2, v2
	v_cvt_pk_bf16_f32 v1, v1, s0
	ds_write_b16 v0, v1 offset:22560
	v_mul_f32_e32 v1, 0x3fb8aa3b, v4
	v_mul_f32_e32 v4, v2, v5
	v_cvt_pk_bf16_f32 v4, v4, s0
	ds_write_b16 v0, v4 offset:2240
	v_min_f32_e64 v4, -v20, s40
	v_exp_f32_e32 v1, v1
	v_mul_f32_e32 v4, 0x3fb8aa3b, v4
	v_exp_f32_e32 v4, v4
	v_sub_f32_e32 v1, 1.0, v1
	v_mul_f32_e32 v4, v1, v4
	v_cvt_pk_bf16_f32 v4, v4, s0
	ds_write_b16 v0, v4 offset:12480
	v_sub_f32_e32 v4, v20, v20
	v_mul_f32_e32 v4, 0x3fb8aa3b, v4
	v_exp_f32_e32 v4, v4
	s_nop 0
	v_mul_f32_e32 v1, v1, v4
	v_cvt_pk_bf16_f32 v1, v1, s0
	ds_write_b16 v0, v1 offset:22720
	v_add_u32_e32 v0, 32, v12
	v_ashrrev_i32_e32 v1, 3, v8
	ds_write_b32 v0, v2 offset:40960
	v_lshlrev_b32_e32 v0, 4, v8
	v_mad_i64_i32 v[4:5], s[8:9], v1, s48, v[40:41]
	v_and_b32_e32 v2, 0x70, v0
	v_lshl_add_u64 v[4:5], v[4:5], 0, s[22:23]
	v_lshl_add_u64 v[4:5], v[4:5], 0, v[2:3]
	global_load_dwordx4 v[4:7], v[4:5], off offset:1536
	v_add_u32_e32 v0, 32, v2
	v_mad_u64_u32 v[14:15], s[8:9], v1, s42, v[0:1]
	v_add_u32_e32 v1, 0x100, v8
	v_ashrrev_i32_e32 v1, 3, v1
	s_waitcnt vmcnt(0)
	ds_write_b128 v14, v[4:7] offset:30720
	v_mad_i64_i32 v[4:5], s[8:9], v1, s48, v[40:41]
	v_lshl_add_u64 v[4:5], v[4:5], 0, s[22:23]
	v_lshl_add_u64 v[4:5], v[4:5], 0, v[2:3]
	global_load_dwordx4 v[4:7], v[4:5], off offset:1536
	v_mad_u64_u32 v[0:1], s[8:9], v1, s42, v[0:1]
	v_and_b32_e32 v2, 15, v8
	v_cmp_gt_u32_e32 vcc, v33, v2
	v_cmp_lt_u32_e64 s[4:5], v33, v2
	s_waitcnt vmcnt(0)
	ds_write_b128 v0, v[4:7] offset:30720
	v_or_b32_e32 v0, v11, v2
	v_lshl_add_u32 v0, v10, 8, v0
	v_ashrrev_i32_e32 v1, 31, v0
	v_lshl_add_u64 v[4:5], v[0:1], 2, s[12:13]
	s_waitcnt lgkmcnt(0)
	s_barrier
	global_load_dword v16, v[4:5], off
	global_load_dword v17, v[4:5], off offset:256
	global_load_dword v18, v[4:5], off offset:512
	global_load_dword v19, v[4:5], off offset:768
	v_add_u32_e32 v4, 0x400, v0
	v_ashrrev_i32_e32 v5, 31, v4
	v_lshl_add_u64 v[4:5], v[4:5], 2, s[12:13]
	global_load_dword v20, v[4:5], off
	v_add_u32_e32 v4, 0x440, v0
	v_ashrrev_i32_e32 v5, 31, v4
	v_lshl_add_u64 v[4:5], v[4:5], 2, s[12:13]
	global_load_dword v21, v[4:5], off
	v_add_u32_e32 v4, 0x480, v0
	v_ashrrev_i32_e32 v5, 31, v4
	v_lshl_add_u64 v[4:5], v[4:5], 2, s[12:13]
	global_load_dword v22, v[4:5], off
	v_add_u32_e32 v4, 0x4c0, v0
	v_ashrrev_i32_e32 v5, 31, v4
	v_lshl_add_u64 v[4:5], v[4:5], 2, s[12:13]
	global_load_dword v23, v[4:5], off
	v_add_u32_e32 v4, 0x800, v0
	v_ashrrev_i32_e32 v5, 31, v4
	v_lshl_add_u64 v[4:5], v[4:5], 2, s[12:13]
	global_load_dword v24, v[4:5], off
	v_add_u32_e32 v4, 0x840, v0
	v_ashrrev_i32_e32 v5, 31, v4
	v_lshl_add_u64 v[4:5], v[4:5], 2, s[12:13]
	global_load_dword v25, v[4:5], off
	v_add_u32_e32 v4, 0x880, v0
	v_ashrrev_i32_e32 v5, 31, v4
	v_lshl_add_u64 v[4:5], v[4:5], 2, s[12:13]
	global_load_dword v26, v[4:5], off
	v_add_u32_e32 v4, 0x8c0, v0
	v_ashrrev_i32_e32 v5, 31, v4
	v_lshl_add_u64 v[4:5], v[4:5], 2, s[12:13]
	global_load_dword v27, v[4:5], off
	v_add_u32_e32 v4, 0xc00, v0
	v_ashrrev_i32_e32 v5, 31, v4
	v_lshl_add_u64 v[4:5], v[4:5], 2, s[12:13]
	global_load_dword v28, v[4:5], off
	v_add_u32_e32 v4, 0xc40, v0
	v_ashrrev_i32_e32 v5, 31, v4
	v_lshl_add_u64 v[4:5], v[4:5], 2, s[12:13]
	global_load_dword v29, v[4:5], off
	v_add_u32_e32 v4, 0xc80, v0
	v_add_u32_e32 v0, 0xcc0, v0
	v_ashrrev_i32_e32 v5, 31, v4
	v_ashrrev_i32_e32 v1, 31, v0
	v_lshl_add_u64 v[4:5], v[4:5], 2, s[12:13]
	v_lshl_add_u64 v[0:1], v[0:1], 2, s[12:13]
	global_load_dword v30, v[4:5], off
	global_load_dword v31, v[0:1], off
	v_bfe_u32 v0, v8, 2, 2
	v_and_b32_e32 v8, 48, v8
	v_mul_u32_u24_e32 v4, 0x50, v2
	v_add_u32_e32 v39, 32, v8
	v_lshlrev_b32_e32 v9, 1, v4
	v_add_u32_e32 v32, v39, v9
	ds_read_b128 v[4:7], v32 offset:10240
	v_add3_u32 v36, 32, v9, v8
	v_or_b32_e32 v34, v33, v0
	ds_read_b128 v[8:11], v36
	v_mul_u32_u24_e32 v0, 0x50, v34
	v_or_b32_e32 v0, v0, v35
	v_lshlrev_b32_e32 v43, 1, v0
	v_add_u32_e32 v44, v37, v43
	ds_read_b64_tr_b16 v[0:1], v44 offset:30720
	s_waitcnt lgkmcnt(1)
	v_mfma_f32_16x16x32_bf16 v[4:7], v[4:7], v[8:11], 0
	ds_read_b128 v[8:11], v32 offset:10304
	ds_read_b128 v[12:15], v36 offset:64
	v_sub_u32_e32 v42, v36, v38
	v_add_u32_e32 v38, 0x800, v42
	s_waitcnt lgkmcnt(0)
	v_mfma_f32_16x16x32_bf16 v[4:7], v[8:11], v[12:15], v[4:7]
	v_or_b32_e32 v8, 2, v33
	v_cmp_gt_u32_e64 s[6:7], v8, v2
	v_or_b32_e32 v8, 3, v33
	v_cmp_gt_u32_e64 s[8:9], v8, v2
	s_nop 3
	v_cndmask_b32_e64 v4, v4, 0, vcc
	v_cndmask_b32_e64 v5, 0, v5, s[4:5]
	v_cndmask_b32_e64 v6, v6, 0, s[6:7]
	v_cndmask_b32_e64 v2, v7, 0, s[8:9]
	v_cvt_pk_bf16_f32 v4, v4, v5
	v_cvt_pk_bf16_f32 v5, v6, v2
	v_mov_b32_e32 v2, v3
	v_mov_b32_e32 v6, v3
	v_mov_b32_e32 v7, v3
	s_waitcnt vmcnt(14)
	v_cvt_pk_bf16_f32 v8, v16, v17
	s_waitcnt vmcnt(12)
	v_cvt_pk_bf16_f32 v9, v18, v19
	ds_read2_b64 v[12:15], v42 offset1:4
	v_mfma_f32_16x16x32_bf16 v[4:7], v[0:3], v[4:7], 0
	s_waitcnt vmcnt(10)
	v_cvt_pk_bf16_f32 v10, v20, v21
	v_add_u32_e32 v33, 32, v43
	s_waitcnt vmcnt(8)
	v_cvt_pk_bf16_f32 v11, v22, v23
	s_waitcnt lgkmcnt(0)
	s_nop 0
	v_mfma_f32_16x16x32_bf16 v[4:7], v[8:11], v[12:15], v[4:7]
	ds_read2_b64 v[12:15], v42 offset0:8 offset1:12
	s_waitcnt vmcnt(6)
	v_cvt_pk_bf16_f32 v8, v24, v25
	s_waitcnt vmcnt(4)
	v_cvt_pk_bf16_f32 v9, v26, v27
	s_waitcnt vmcnt(2)
	v_cvt_pk_bf16_f32 v10, v28, v29
	s_waitcnt vmcnt(0)
	v_cvt_pk_bf16_f32 v11, v30, v31
	s_waitcnt lgkmcnt(0)
	s_nop 0
	v_mfma_f32_16x16x32_bf16 v[4:7], v[8:11], v[12:15], v[4:7]
	v_mov_b32_e32 v10, v3
	v_mov_b32_e32 v11, v3
	v_mov_b32_e32 v14, v3
	s_nop 4
	v_pk_add_f32 v[52:53], v[6:7], 0 op_sel_hi:[1,0]
	v_pk_add_f32 v[54:55], v[4:5], 0 op_sel_hi:[1,0]
	ds_read_b128 v[4:7], v39 offset:40960
	ds_read_b64_tr_b16 v[8:9], v33 offset:20480
	ds_read_b64_tr_b16 v[12:13], v33 offset:20512
	v_mov_b32_e32 v15, v3
	s_waitcnt lgkmcnt(2)
	v_pk_mul_f32 v[4:5], v[16:17], v[4:5]
	v_pk_mul_f32 v[6:7], v[18:19], v[6:7]
	ds_read_b64_tr_b16 v[16:17], v33 offset:20544
	v_mov_b32_e32 v18, v3
	s_waitcnt lgkmcnt(2)
	v_mfma_f32_16x16x32_bf16 v[8:11], v[8:11], v[0:3], v[4:7]
	v_mov_b32_e32 v19, v3
	s_nop 1
	ds_read_b128 v[4:7], v39 offset:41024
	s_waitcnt lgkmcnt(0)
	v_pk_mul_f32 v[4:5], v[20:21], v[4:5]
	v_pk_mul_f32 v[6:7], v[22:23], v[6:7]
	ds_read_b64_tr_b16 v[20:21], v33 offset:20576
	v_mov_b32_e32 v22, v3
	v_mfma_f32_16x16x32_bf16 v[12:15], v[12:15], v[0:3], v[4:7]
	v_mov_b32_e32 v23, v3
	s_nop 1
	ds_read_b128 v[4:7], v39 offset:41088
	s_waitcnt lgkmcnt(0)
	v_pk_mul_f32 v[4:5], v[24:25], v[4:5]
	v_pk_mul_f32 v[6:7], v[26:27], v[6:7]
	s_nop 1
	v_mfma_f32_16x16x32_bf16 v[16:19], v[16:19], v[0:3], v[4:7]
	s_nop 2
	ds_read_b128 v[4:7], v39 offset:41152
	s_waitcnt lgkmcnt(0)
	v_pk_mul_f32 v[4:5], v[28:29], v[4:5]
	v_pk_mul_f32 v[6:7], v[30:31], v[6:7]
	s_nop 1
	v_mfma_f32_16x16x32_bf16 v[20:23], v[20:23], v[0:3], v[4:7]
	ds_read_b64_tr_b16 v[0:1], v44 offset:33280
	s_nop 1
	ds_read_b128 v[4:7], v32 offset:12800
	ds_read_b128 v[24:27], v36 offset:2560
	s_waitcnt lgkmcnt(0)
	v_mfma_f32_16x16x32_bf16 v[4:7], v[4:7], v[24:27], 0
	ds_read_b128 v[24:27], v32 offset:12864
	ds_read_b128 v[28:31], v36 offset:2624
	s_waitcnt lgkmcnt(0)
	v_mfma_f32_16x16x32_bf16 v[4:7], v[24:27], v[28:31], v[4:7]
	v_cvt_pk_bf16_f32 v24, v8, v9
	v_cvt_pk_bf16_f32 v25, v10, v11
	v_cvt_pk_bf16_f32 v26, v12, v13
	s_nop 4
	v_cndmask_b32_e64 v2, v4, 0, vcc
	v_cndmask_b32_e64 v4, 0, v5, s[4:5]
	v_cvt_pk_bf16_f32 v4, v2, v4
	v_mov_b32_e32 v2, v3
	v_cndmask_b32_e64 v5, v6, 0, s[6:7]
	v_cndmask_b32_e64 v6, v7, 0, s[8:9]
	v_cvt_pk_bf16_f32 v5, v5, v6
	v_mov_b32_e32 v6, v3
	v_mov_b32_e32 v7, v3
	v_cvt_pk_bf16_f32 v27, v14, v15
	ds_read2_b64 v[28:31], v38 offset0:64 offset1:68
	v_mfma_f32_16x16x32_bf16 v[4:7], v[0:3], v[4:7], 0
	s_waitcnt lgkmcnt(0)
	v_mfma_f32_16x16x32_bf16 v[4:7], v[24:27], v[28:31], v[4:7]
	v_cvt_pk_bf16_f32 v24, v16, v17
	v_cvt_pk_bf16_f32 v25, v18, v19
	v_cvt_pk_bf16_f32 v26, v20, v21
	v_cvt_pk_bf16_f32 v27, v22, v23
	ds_read2_b64 v[28:31], v38 offset0:72 offset1:76
	v_add_u32_e32 v38, 0x1000, v42
	s_waitcnt lgkmcnt(0)
	v_mfma_f32_16x16x32_bf16 v[4:7], v[24:27], v[28:31], v[4:7]
	ds_read_b128 v[24:27], v39 offset:41216
	s_waitcnt lgkmcnt(0)
	v_pk_mul_f32 v[8:9], v[8:9], v[24:25]
	ds_read_b64_tr_b16 v[24:25], v33 offset:23040
	v_pk_mul_f32 v[10:11], v[10:11], v[26:27]
	v_mov_b32_e32 v26, v3
	v_mov_b32_e32 v27, v3
	s_waitcnt lgkmcnt(0)
	s_nop 0
	v_mfma_f32_16x16x32_bf16 v[24:27], v[24:27], v[0:3], v[8:11]
	s_nop 2
	ds_read_b128 v[8:11], v39 offset:41280
	s_waitcnt lgkmcnt(0)
	v_pk_mul_f32 v[8:9], v[12:13], v[8:9]
	ds_read_b64_tr_b16 v[12:13], v33 offset:23072
	v_pk_mul_f32 v[10:11], v[14:15], v[10:11]
	v_mov_b32_e32 v14, v3
	v_mov_b32_e32 v15, v3
	s_waitcnt lgkmcnt(0)
	s_nop 0
	v_mfma_f32_16x16x32_bf16 v[12:15], v[12:15], v[0:3], v[8:11]
	s_nop 2
	ds_read_b128 v[8:11], v39 offset:41344
	s_waitcnt lgkmcnt(0)
	v_pk_mul_f32 v[8:9], v[16:17], v[8:9]
	ds_read_b64_tr_b16 v[16:17], v33 offset:23104
	v_pk_mul_f32 v[10:11], v[18:19], v[10:11]
	v_mov_b32_e32 v18, v3
	v_mov_b32_e32 v19, v3
	s_waitcnt lgkmcnt(0)
	s_nop 0
	v_mfma_f32_16x16x32_bf16 v[16:19], v[16:19], v[0:3], v[8:11]
	s_nop 2
	ds_read_b128 v[8:11], v39 offset:41408
	s_waitcnt lgkmcnt(0)
	v_pk_mul_f32 v[8:9], v[20:21], v[8:9]
	ds_read_b64_tr_b16 v[20:21], v33 offset:23136
	v_pk_mul_f32 v[10:11], v[22:23], v[10:11]
	v_mov_b32_e32 v22, v3
	v_mov_b32_e32 v23, v3
	s_waitcnt lgkmcnt(0)
	s_nop 0
	v_mfma_f32_16x16x32_bf16 v[28:31], v[20:23], v[0:3], v[8:11]
	ds_read_b64_tr_b16 v[0:1], v44 offset:35840
	s_nop 1
	ds_read_b128 v[8:11], v32 offset:15360
	ds_read_b128 v[20:23], v36 offset:5120
	s_waitcnt lgkmcnt(0)
	v_mfma_f32_16x16x32_bf16 v[8:11], v[8:11], v[20:23], 0
	ds_read_b128 v[20:23], v32 offset:15424
	ds_read_b128 v[44:47], v36 offset:5184
	s_waitcnt lgkmcnt(0)
	v_mfma_f32_16x16x32_bf16 v[8:11], v[20:23], v[44:47], v[8:11]
	v_cvt_pk_bf16_f32 v20, v24, v25
	v_cvt_pk_bf16_f32 v21, v26, v27
	v_cvt_pk_bf16_f32 v22, v12, v13
	s_nop 4
	v_cndmask_b32_e64 v2, v8, 0, vcc
	v_cndmask_b32_e64 v8, 0, v9, s[4:5]
	v_cvt_pk_bf16_f32 v8, v2, v8
	v_mov_b32_e32 v2, v3
	v_cndmask_b32_e64 v9, v10, 0, s[6:7]
	v_cndmask_b32_e64 v10, v11, 0, s[8:9]
	v_cvt_pk_bf16_f32 v9, v9, v10
	v_mov_b32_e32 v10, v3
	v_mov_b32_e32 v11, v3
	v_cvt_pk_bf16_f32 v23, v14, v15
	ds_read2_b64 v[44:47], v38 offset0:128 offset1:132
	v_mfma_f32_16x16x32_bf16 v[8:11], v[0:3], v[8:11], 0
	s_waitcnt lgkmcnt(0)
	v_mfma_f32_16x16x32_bf16 v[8:11], v[20:23], v[44:47], v[8:11]
	v_cvt_pk_bf16_f32 v20, v16, v17
	v_cvt_pk_bf16_f32 v21, v18, v19
	v_cvt_pk_bf16_f32 v22, v28, v29
	v_cvt_pk_bf16_f32 v23, v30, v31
	ds_read2_b64 v[44:47], v38 offset0:136 offset1:140
	s_waitcnt lgkmcnt(0)
	v_mfma_f32_16x16x32_bf16 v[8:11], v[20:23], v[44:47], v[8:11]
	ds_read_b128 v[20:23], v39 offset:41472
	s_waitcnt lgkmcnt(0)
	v_pk_mul_f32 v[20:21], v[24:25], v[20:21]
	ds_read_b64_tr_b16 v[24:25], v33 offset:25600
	v_pk_mul_f32 v[22:23], v[26:27], v[22:23]
	v_mov_b32_e32 v26, v3
	v_mov_b32_e32 v27, v3
	s_waitcnt lgkmcnt(0)
	s_nop 0
	v_mfma_f32_16x16x32_bf16 v[20:23], v[24:27], v[0:3], v[20:23]
	ds_read_b128 v[24:27], v39 offset:41536
	s_waitcnt lgkmcnt(0)
	v_pk_mul_f32 v[12:13], v[12:13], v[24:25]
	ds_read_b64_tr_b16 v[24:25], v33 offset:25632
	v_pk_mul_f32 v[14:15], v[14:15], v[26:27]
	v_mov_b32_e32 v26, v3
	v_mov_b32_e32 v27, v3
	s_nop 0
	v_cvt_pk_bf16_f32 v20, v20, v21
	v_cvt_pk_bf16_f32 v21, v22, v23
	s_waitcnt lgkmcnt(0)
	v_mfma_f32_16x16x32_bf16 v[24:27], v[24:27], v[0:3], v[12:15]
	s_nop 2
	ds_read_b128 v[12:15], v39 offset:41600
	s_waitcnt lgkmcnt(0)
	v_pk_mul_f32 v[12:13], v[16:17], v[12:13]
	ds_read_b64_tr_b16 v[16:17], v33 offset:25664
	v_pk_mul_f32 v[14:15], v[18:19], v[14:15]
	v_mov_b32_e32 v18, v3
	v_mov_b32_e32 v19, v3
	v_cvt_pk_bf16_f32 v22, v24, v25
	v_cvt_pk_bf16_f32 v23, v26, v27
	s_waitcnt lgkmcnt(0)
	v_mfma_f32_16x16x32_bf16 v[12:15], v[16:19], v[0:3], v[12:15]
	ds_read_b128 v[16:19], v39 offset:41664
	s_waitcnt lgkmcnt(0)
	v_pk_mul_f32 v[16:17], v[28:29], v[16:17]
	ds_read_b64_tr_b16 v[28:29], v33 offset:25696
	v_pk_mul_f32 v[18:19], v[30:31], v[18:19]
	v_mov_b32_e32 v30, v3
	v_mov_b32_e32 v31, v3
	s_nop 0
	v_cvt_pk_bf16_f32 v12, v12, v13
	v_cvt_pk_bf16_f32 v13, v14, v15
	s_waitcnt lgkmcnt(0)
	v_mfma_f32_16x16x32_bf16 v[16:19], v[28:31], v[0:3], v[16:19]
	v_mul_u32_u24_e32 v0, 0xa0, v34
	v_lshlrev_b32_e32 v1, 1, v35
	v_add3_u32 v0, v37, v0, v1
	ds_read_b64_tr_b16 v[0:1], v0 offset:38400
	ds_read_b128 v[28:31], v32 offset:17920
	ds_read_b128 v[44:47], v36 offset:7680
	ds_read_b128 v[32:35], v32 offset:17984
	ds_read_b128 v[36:39], v36 offset:7744
	s_waitcnt lgkmcnt(2)
	v_mfma_f32_16x16x32_bf16 v[28:31], v[28:31], v[44:47], 0
	v_cvt_pk_bf16_f32 v14, v16, v17
	v_cvt_pk_bf16_f32 v15, v18, v19
	s_waitcnt lgkmcnt(0)
	v_mfma_f32_16x16x32_bf16 v[28:31], v[32:35], v[36:39], v[28:31]
	s_nop 7
	v_cndmask_b32_e64 v2, v28, 0, vcc
	v_cndmask_b32_e64 v28, 0, v29, s[4:5]
	v_cvt_pk_bf16_f32 v28, v2, v28
	v_mov_b32_e32 v2, v3
	v_cndmask_b32_e64 v29, v30, 0, s[6:7]
	v_cndmask_b32_e64 v30, v31, 0, s[8:9]
	v_cvt_pk_bf16_f32 v29, v29, v30
	v_mov_b32_e32 v30, v3
	v_mov_b32_e32 v31, v3
	s_nop 1
	v_mfma_f32_16x16x32_bf16 v[28:31], v[0:3], v[28:31], 0
	v_add_u32_e32 v0, 0x1800, v42
	ds_read2_b64 v[24:27], v0 offset0:192 offset1:196
	ds_read2_b64 v[16:19], v0 offset0:200 offset1:204
	s_waitcnt lgkmcnt(1)
	v_mfma_f32_16x16x32_bf16 v[20:23], v[20:23], v[24:27], v[28:31]
	v_mov_b32_e32 v24, v222
	s_waitcnt lgkmcnt(0)
	v_and_b32_e32 v0, 63, v24
	v_or_b32_e32 v1, s33, v0
	v_ashrrev_i32_e32 v25, 6, v24
	v_lshlrev_b32_e32 v2, 1, v1
	v_mfma_f32_16x16x32_bf16 v[12:15], v[12:15], v[16:19], v[20:23]
	v_lshl_add_u64 v[16:17], s[0:1], 0, v[2:3]
	s_barrier
	s_nop 0
	v_lshlrev_b32_e32 v20, 4, v25
	v_mad_i64_i32 v[18:19], s[4:5], v20, s48, v[16:17]
	v_mov_b32_e32 v1, v112
	v_or_b32_e32 v2, 13, v20
	v_or_b32_e32 v64, 1, v20
	v_mad_i64_i32 v[38:39], s[4:5], v2, s48, v[16:17]
	v_mov_b32_e32 v2, v125
	v_or_b32_e32 v37, 15, v20
	v_bfe_u32 v26, v24, 4, 2
	s_waitcnt vmcnt(1)
	v_lshlrev_b32_e32 v43, 16, v1
	v_mov_b32_e32 v1, v96
	v_mad_i64_i32 v[18:19], s[4:5], v64, s48, v[16:17]
	s_waitcnt vmcnt(0)
	v_lshlrev_b32_e32 v67, 16, v1
	v_mov_b32_e32 v1, v113
	s_waitcnt vmcnt(0)
	v_lshlrev_b32_e32 v66, 16, v1
	v_mov_b32_e32 v1, v97
	s_waitcnt vmcnt(0)
	v_lshlrev_b32_e32 v63, 16, v1
	v_or_b32_e32 v1, 2, v20
	v_mad_i64_i32 v[18:19], s[4:5], v1, s48, v[16:17]
	v_mov_b32_e32 v1, v114
	s_waitcnt vmcnt(0)
	v_lshlrev_b32_e32 v62, 16, v1
	v_mov_b32_e32 v1, v98
	s_waitcnt vmcnt(0)
	v_lshlrev_b32_e32 v60, 16, v1
	v_or_b32_e32 v1, 3, v20
	v_mad_i64_i32 v[18:19], s[4:5], v1, s48, v[16:17]
	v_mov_b32_e32 v1, v115
	s_waitcnt vmcnt(0)
	v_lshlrev_b32_e32 v59, 16, v1
	v_mov_b32_e32 v1, v99
	s_waitcnt vmcnt(0)
	v_lshlrev_b32_e32 v51, 16, v1
	v_or_b32_e32 v1, 4, v20
	v_mad_i64_i32 v[18:19], s[4:5], v1, s48, v[16:17]
	v_mov_b32_e32 v1, v116
	s_waitcnt vmcnt(0)
	v_lshlrev_b32_e32 v49, 16, v1
	v_mov_b32_e32 v1, v100
	s_waitcnt vmcnt(0)
	v_lshlrev_b32_e32 v48, 16, v1
	v_or_b32_e32 v1, 5, v20
	v_mad_i64_i32 v[18:19], s[4:5], v1, s48, v[16:17]
	v_mov_b32_e32 v1, v117
	s_waitcnt vmcnt(0)
	v_lshlrev_b32_e32 v47, 16, v1
	v_mov_b32_e32 v1, v101
	s_waitcnt vmcnt(0)
	v_lshlrev_b32_e32 v45, 16, v1
	v_or_b32_e32 v1, 6, v20
	v_mad_i64_i32 v[18:19], s[4:5], v1, s48, v[16:17]
	v_mov_b32_e32 v1, v118
	s_waitcnt vmcnt(0)
	v_lshlrev_b32_e32 v42, 16, v1
	v_mov_b32_e32 v1, v102
	s_waitcnt vmcnt(0)
	v_lshlrev_b32_e32 v36, 16, v1
	v_or_b32_e32 v1, 7, v20
	v_mad_i64_i32 v[18:19], s[4:5], v1, s48, v[16:17]
	v_mov_b32_e32 v1, v119
	s_waitcnt vmcnt(0)
	v_lshlrev_b32_e32 v35, 16, v1
	v_mov_b32_e32 v1, v103
	s_waitcnt vmcnt(0)
	v_lshlrev_b32_e32 v34, 16, v1
	v_or_b32_e32 v1, 8, v20
	v_mad_i64_i32 v[18:19], s[4:5], v1, s48, v[16:17]
	v_mov_b32_e32 v1, v120
	s_waitcnt vmcnt(0)
	v_lshlrev_b32_e32 v33, 16, v1
	v_mov_b32_e32 v1, v104
	s_waitcnt vmcnt(0)
	v_lshlrev_b32_e32 v32, 16, v1
	v_or_b32_e32 v1, 9, v20
	v_mad_i64_i32 v[18:19], s[4:5], v1, s48, v[16:17]
	v_mov_b32_e32 v1, v121
	s_waitcnt vmcnt(0)
	v_lshlrev_b32_e32 v31, 16, v1
	v_mov_b32_e32 v1, v105
	s_waitcnt vmcnt(0)
	v_lshlrev_b32_e32 v30, 16, v1
	v_or_b32_e32 v1, 10, v20
	v_mad_i64_i32 v[18:19], s[4:5], v1, s48, v[16:17]
	v_mov_b32_e32 v1, v122
	s_waitcnt vmcnt(0)
	v_lshlrev_b32_e32 v29, 16, v1
	v_mov_b32_e32 v1, v106
	s_waitcnt vmcnt(0)
	v_lshlrev_b32_e32 v28, 16, v1
	v_or_b32_e32 v1, 11, v20
	v_mad_i64_i32 v[18:19], s[4:5], v1, s48, v[16:17]
	v_mov_b32_e32 v1, v123
	s_waitcnt vmcnt(0)
	v_lshlrev_b32_e32 v27, 16, v1
	v_mov_b32_e32 v1, v107
	s_waitcnt vmcnt(0)
	v_lshlrev_b32_e32 v23, 16, v1
	v_or_b32_e32 v1, 12, v20
	v_mad_i64_i32 v[18:19], s[4:5], v1, s48, v[16:17]
	v_mov_b32_e32 v1, v124
	s_waitcnt vmcnt(0)
	v_lshlrev_b32_e32 v22, 16, v1
	v_mov_b32_e32 v1, v108
	v_or_b32_e32 v18, 14, v20
	v_lshlrev_b32_e32 v19, 16, v2
	v_mov_b32_e32 v2, v109
	v_mad_i64_i32 v[38:39], s[4:5], v18, s48, v[16:17]
	v_mov_b32_e32 v18, v126
	s_waitcnt vmcnt(2)
	v_lshlrev_b32_e32 v1, 16, v1
	s_waitcnt vmcnt(1)
	v_lshlrev_b32_e32 v2, 16, v2
	s_waitcnt vmcnt(0)
	v_lshlrev_b32_e32 v21, 16, v18
	v_mov_b32_e32 v18, v110
	v_mad_i64_i32 v[38:39], s[4:5], v37, s48, v[16:17]
	v_mov_b32_e32 v16, v127
	v_mov_b32_e32 v17, v111
	s_waitcnt vmcnt(2)
	v_lshlrev_b32_e32 v18, 16, v18
	s_waitcnt vmcnt(1)
	v_lshlrev_b32_e32 v16, 16, v16
	s_waitcnt vmcnt(0)
	v_lshlrev_b32_e32 v37, 16, v17
	v_add_f32_e32 v17, 0, v16
	v_add_f32_e32 v39, v17, v21
	v_add_f32_e32 v44, v39, v19
	v_add_f32_e32 v46, v44, v22
	v_add_f32_e32 v50, v46, v27
	v_add_f32_e32 v61, v50, v29
	v_add_f32_e32 v65, v61, v31
	v_add_f32_e32 v68, v65, v33
	v_add_f32_e32 v69, v68, v35
	v_add_f32_e32 v70, v69, v42
	v_add_f32_e32 v71, v70, v47
	v_add_f32_e32 v72, v71, v49
	v_add_f32_e32 v73, v72, v59
	v_add_f32_e32 v74, v73, v62
	v_add_f32_e32 v75, v74, v66
	v_add_f32_e32 v38, v75, v43
	v_mul_f32_e32 v43, 0x3fb8aa3b, v43
	v_exp_f32_e32 v43, v43
	v_mul_f32_e32 v66, 0x3fb8aa3b, v66
	v_exp_f32_e32 v66, v66
	v_mul_f32_e32 v62, 0x3fb8aa3b, v62
	v_sub_f32_e32 v76, 1.0, v43
	v_mul_lo_u32 v43, v25, s38
	v_or_b32_e32 v77, v43, v0
	v_mul_f32_e32 v43, 0x3fb8aa3b, v38
	v_exp_f32_e32 v43, v43
	v_lshl_add_u32 v77, v77, 1, 32
	v_exp_f32_e32 v62, v62
	v_mul_f32_e32 v59, 0x3fb8aa3b, v59
	v_mul_f32_e32 v67, v43, v67
	v_cvt_pk_bf16_f32 v67, v67, s0
	ds_write_b16 v77, v67
	v_min_f32_e64 v67, -v38, s40
	v_mul_f32_e32 v67, 0x3fb8aa3b, v67
	v_exp_f32_e32 v67, v67
	v_sub_f32_e32 v62, 1.0, v62
	v_exp_f32_e32 v59, v59
	v_mul_f32_e32 v49, 0x3fb8aa3b, v49
	v_mul_f32_e32 v67, v76, v67
	v_cvt_pk_bf16_f32 v67, v67, s0
	ds_write_b16 v77, v67 offset:10240
	v_sub_f32_e32 v67, v38, v38
	v_mul_f32_e32 v67, 0x3fb8aa3b, v67
	v_exp_f32_e32 v67, v67
	v_sub_f32_e32 v59, 1.0, v59
	v_exp_f32_e32 v49, v49
	v_mul_f32_e32 v47, 0x3fb8aa3b, v47
	v_mul_f32_e32 v67, v76, v67
	v_cvt_pk_bf16_f32 v67, v67, s0
	ds_write_b16 v77, v67 offset:20480
	v_sub_f32_e32 v76, 1.0, v66
	v_mad_u64_u32 v[66:67], s[4:5], v64, s39, v[0:1]
	v_mul_f32_e32 v0, 0x3fb8aa3b, v75
	v_exp_f32_e32 v0, v0
	v_sub_f32_e32 v49, 1.0, v49
	v_exp_f32_e32 v47, v47
	v_mul_f32_e32 v42, 0x3fb8aa3b, v42
	v_mul_f32_e32 v0, v0, v63
	v_cvt_pk_bf16_f32 v63, v0, s0
	v_lshl_add_u32 v0, v66, 1, 32
	ds_write_b16 v0, v63
	v_min_f32_e64 v63, -v75, s40
	v_mul_f32_e32 v63, 0x3fb8aa3b, v63
	v_exp_f32_e32 v63, v63
	v_sub_f32_e32 v47, 1.0, v47
	v_exp_f32_e32 v42, v42
	v_mul_f32_e32 v35, 0x3fb8aa3b, v35
	v_mul_f32_e32 v63, v76, v63
	v_cvt_pk_bf16_f32 v63, v63, s0
	ds_write_b16 v0, v63 offset:10240
	v_sub_f32_e32 v63, v38, v75
	v_mul_f32_e32 v63, 0x3fb8aa3b, v63
	v_exp_f32_e32 v63, v63
	v_sub_f32_e32 v42, 1.0, v42
	v_exp_f32_e32 v35, v35
	v_mul_f32_e32 v33, 0x3fb8aa3b, v33
	v_mul_f32_e32 v63, v76, v63
	v_cvt_pk_bf16_f32 v63, v63, s0
	ds_write_b16 v0, v63 offset:20480
	v_mul_f32_e32 v63, 0x3fb8aa3b, v74
	v_exp_f32_e32 v63, v63
	v_sub_f32_e32 v35, 1.0, v35
	v_exp_f32_e32 v33, v33
	v_mul_f32_e32 v31, 0x3fb8aa3b, v31
	v_mul_f32_e32 v60, v63, v60
	v_cvt_pk_bf16_f32 v60, v60, s0
	ds_write_b16 v0, v60 offset:160
	v_min_f32_e64 v60, -v74, s40
	v_mul_f32_e32 v60, 0x3fb8aa3b, v60
	v_exp_f32_e32 v60, v60
	v_sub_f32_e32 v33, 1.0, v33
	v_exp_f32_e32 v31, v31
	v_mul_f32_e32 v29, 0x3fb8aa3b, v29
	v_mul_f32_e32 v60, v62, v60
	v_cvt_pk_bf16_f32 v60, v60, s0
	ds_write_b16 v0, v60 offset:10400
	v_sub_f32_e32 v60, v38, v74
	v_mul_f32_e32 v60, 0x3fb8aa3b, v60
	v_exp_f32_e32 v60, v60
	v_sub_f32_e32 v31, 1.0, v31
	v_exp_f32_e32 v29, v29
	v_mul_f32_e32 v27, 0x3fb8aa3b, v27
	v_mul_f32_e32 v60, v62, v60
	v_cvt_pk_bf16_f32 v60, v60, s0
	ds_write_b16 v0, v60 offset:20640
	v_mul_f32_e32 v60, 0x3fb8aa3b, v73
	v_exp_f32_e32 v60, v60
	v_sub_f32_e32 v29, 1.0, v29
	v_exp_f32_e32 v27, v27
	v_mul_f32_e32 v22, 0x3fb8aa3b, v22
	v_mul_f32_e32 v51, v60, v51
	v_cvt_pk_bf16_f32 v51, v51, s0
	ds_write_b16 v0, v51 offset:320
	v_min_f32_e64 v51, -v73, s40
	v_mul_f32_e32 v51, 0x3fb8aa3b, v51
	v_exp_f32_e32 v51, v51
	v_sub_f32_e32 v27, 1.0, v27
	v_exp_f32_e32 v22, v22
	v_mul_f32_e32 v51, v59, v51
	v_cvt_pk_bf16_f32 v51, v51, s0
	ds_write_b16 v0, v51 offset:10560
	v_sub_f32_e32 v51, v38, v73
	v_mul_f32_e32 v51, 0x3fb8aa3b, v51
	v_exp_f32_e32 v51, v51
	v_sub_f32_e32 v22, 1.0, v22
	v_mul_f32_e32 v51, v59, v51
	v_cvt_pk_bf16_f32 v51, v51, s0
	ds_write_b16 v0, v51 offset:20800
	v_mul_f32_e32 v51, 0x3fb8aa3b, v72
	v_exp_f32_e32 v51, v51
	s_nop 0
	v_mul_f32_e32 v48, v51, v48
	v_cvt_pk_bf16_f32 v48, v48, s0
	ds_write_b16 v0, v48 offset:480
	v_min_f32_e64 v48, -v72, s40
	v_mul_f32_e32 v48, 0x3fb8aa3b, v48
	v_exp_f32_e32 v48, v48
	v_lshl_add_u32 v51, v25, 5, 32
	v_mul_f32_e32 v48, v49, v48
	v_cvt_pk_bf16_f32 v48, v48, s0
	ds_write_b16 v0, v48 offset:10720
	v_sub_f32_e32 v48, v38, v72
	v_mul_f32_e32 v48, 0x3fb8aa3b, v48
	v_exp_f32_e32 v48, v48
	s_nop 0
	v_mul_f32_e32 v48, v49, v48
	v_cvt_pk_bf16_f32 v48, v48, s0
	ds_write_b16 v0, v48 offset:20960
	v_mul_f32_e32 v48, 0x3fb8aa3b, v71
	v_exp_f32_e32 v48, v48
	s_nop 0
	v_mul_f32_e32 v45, v48, v45
	v_cvt_pk_bf16_f32 v45, v45, s0
	ds_write_b16 v0, v45 offset:640
	v_min_f32_e64 v45, -v71, s40
	v_mul_f32_e32 v45, 0x3fb8aa3b, v45
	v_exp_f32_e32 v45, v45
	s_nop 0
	v_mul_f32_e32 v45, v47, v45
	v_cvt_pk_bf16_f32 v45, v45, s0
	ds_write_b16 v0, v45 offset:10880
	v_sub_f32_e32 v45, v38, v71
	v_mul_f32_e32 v45, 0x3fb8aa3b, v45
	v_exp_f32_e32 v45, v45
	s_nop 0
	v_mul_f32_e32 v45, v47, v45
	v_cvt_pk_bf16_f32 v45, v45, s0
	ds_write_b16 v0, v45 offset:21120
	v_mul_f32_e32 v45, 0x3fb8aa3b, v70
	v_exp_f32_e32 v45, v45
	s_nop 0
	v_mul_f32_e32 v36, v45, v36
	v_cvt_pk_bf16_f32 v36, v36, s0
	ds_write_b16 v0, v36 offset:800
	v_min_f32_e64 v36, -v70, s40
	v_mul_f32_e32 v36, 0x3fb8aa3b, v36
	v_exp_f32_e32 v36, v36
	v_lshlrev_b32_e32 v45, 3, v26
	v_mul_f32_e32 v36, v42, v36
	v_cvt_pk_bf16_f32 v36, v36, s0
	ds_write_b16 v0, v36 offset:11040
	v_sub_f32_e32 v36, v38, v70
	v_mul_f32_e32 v36, 0x3fb8aa3b, v36
	v_exp_f32_e32 v36, v36
	s_nop 0
	v_mul_f32_e32 v36, v42, v36
	v_cvt_pk_bf16_f32 v36, v36, s0
	ds_write_b16 v0, v36 offset:21280
	v_mul_f32_e32 v36, 0x3fb8aa3b, v69
	v_exp_f32_e32 v36, v36
	s_nop 0
	v_mul_f32_e32 v34, v36, v34
	v_cvt_pk_bf16_f32 v34, v34, s0
	ds_write_b16 v0, v34 offset:960
	v_min_f32_e64 v34, -v69, s40
	v_mul_f32_e32 v34, 0x3fb8aa3b, v34
	v_exp_f32_e32 v34, v34
	s_nop 0
	v_mul_f32_e32 v34, v35, v34
	v_cvt_pk_bf16_f32 v34, v34, s0
	ds_write_b16 v0, v34 offset:11200
	v_sub_f32_e32 v34, v38, v69
	v_mul_f32_e32 v34, 0x3fb8aa3b, v34
	v_exp_f32_e32 v34, v34
	s_nop 0
	v_mul_f32_e32 v34, v35, v34
	v_cvt_pk_bf16_f32 v34, v34, s0
	ds_write_b16 v0, v34 offset:21440
	v_mul_f32_e32 v34, 0x3fb8aa3b, v68
	v_exp_f32_e32 v34, v34
	s_nop 0
	v_mul_f32_e32 v32, v34, v32
	v_cvt_pk_bf16_f32 v32, v32, s0
	ds_write_b16 v0, v32 offset:1120
	v_min_f32_e64 v32, -v68, s40
	v_mul_f32_e32 v32, 0x3fb8aa3b, v32
	v_exp_f32_e32 v32, v32
	s_nop 0
	v_mul_f32_e32 v32, v33, v32
	v_cvt_pk_bf16_f32 v32, v32, s0
	ds_write_b16 v0, v32 offset:11360
	v_sub_f32_e32 v32, v38, v68
	v_mul_f32_e32 v32, 0x3fb8aa3b, v32
	v_exp_f32_e32 v32, v32
	s_nop 0
	v_mul_f32_e32 v32, v33, v32
	v_cvt_pk_bf16_f32 v32, v32, s0
	ds_write_b16 v0, v32 offset:21600
	v_mul_f32_e32 v32, 0x3fb8aa3b, v65
	v_exp_f32_e32 v32, v32
	s_nop 0
	v_mul_f32_e32 v30, v32, v30
	v_cvt_pk_bf16_f32 v30, v30, s0
	ds_write_b16 v0, v30 offset:1280
	v_min_f32_e64 v30, -v65, s40
	v_mul_f32_e32 v30, 0x3fb8aa3b, v30
	v_exp_f32_e32 v30, v30
	s_nop 0
	v_mul_f32_e32 v30, v31, v30
	v_cvt_pk_bf16_f32 v30, v30, s0
	ds_write_b16 v0, v30 offset:11520
	v_sub_f32_e32 v30, v38, v65
	v_mul_f32_e32 v30, 0x3fb8aa3b, v30
	v_exp_f32_e32 v30, v30
	s_nop 0
	v_mul_f32_e32 v30, v31, v30
	v_cvt_pk_bf16_f32 v30, v30, s0
	ds_write_b16 v0, v30 offset:21760
	v_mul_f32_e32 v30, 0x3fb8aa3b, v61
	v_exp_f32_e32 v30, v30
	s_nop 0
	v_mul_f32_e32 v28, v30, v28
	v_cvt_pk_bf16_f32 v28, v28, s0
	ds_write_b16 v0, v28 offset:1440
	v_min_f32_e64 v28, -v61, s40
	v_mul_f32_e32 v28, 0x3fb8aa3b, v28
	v_exp_f32_e32 v28, v28
	s_nop 0
	v_mul_f32_e32 v28, v29, v28
	v_cvt_pk_bf16_f32 v28, v28, s0
	ds_write_b16 v0, v28 offset:11680
	v_sub_f32_e32 v28, v38, v61
	v_mul_f32_e32 v28, 0x3fb8aa3b, v28
	v_exp_f32_e32 v28, v28
	s_nop 0
	v_mul_f32_e32 v28, v29, v28
	v_cvt_pk_bf16_f32 v28, v28, s0
	ds_write_b16 v0, v28 offset:21920
	v_mul_f32_e32 v28, 0x3fb8aa3b, v50
	v_exp_f32_e32 v28, v28
	s_nop 0
	v_mul_f32_e32 v23, v28, v23
	v_cvt_pk_bf16_f32 v23, v23, s0
	ds_write_b16 v0, v23 offset:1600
	v_min_f32_e64 v23, -v50, s40
	v_mul_f32_e32 v23, 0x3fb8aa3b, v23
	v_exp_f32_e32 v23, v23
	s_nop 0
	v_mul_f32_e32 v23, v27, v23
	v_cvt_pk_bf16_f32 v23, v23, s0
	ds_write_b16 v0, v23 offset:11840
	v_sub_f32_e32 v23, v38, v50
	v_mul_f32_e32 v23, 0x3fb8aa3b, v23
	v_exp_f32_e32 v23, v23
	s_nop 0
	v_mul_f32_e32 v23, v27, v23
	v_cvt_pk_bf16_f32 v23, v23, s0
	ds_write_b16 v0, v23 offset:22080
	v_mul_f32_e32 v23, 0x3fb8aa3b, v46
	v_exp_f32_e32 v23, v23
	v_lshlrev_b32_e32 v27, 2, v24
	v_and_b32_e32 v50, 12, v27
	v_mul_f32_e32 v1, v23, v1
	v_cvt_pk_bf16_f32 v1, v1, s0
	ds_write_b16 v0, v1 offset:1760
	v_min_f32_e64 v1, -v46, s40
	v_mul_f32_e32 v1, 0x3fb8aa3b, v1
	v_exp_f32_e32 v1, v1
	s_nop 0
	v_mul_f32_e32 v1, v22, v1
	v_cvt_pk_bf16_f32 v1, v1, s0
	ds_write_b16 v0, v1 offset:12000
	v_sub_f32_e32 v1, v38, v46
	v_mul_f32_e32 v1, 0x3fb8aa3b, v1
	v_exp_f32_e32 v1, v1
	s_nop 0
	v_mul_f32_e32 v1, v22, v1
	v_cvt_pk_bf16_f32 v1, v1, s0
	ds_write_b16 v0, v1 offset:22240
	v_mul_f32_e32 v1, 0x3fb8aa3b, v19
	v_mul_f32_e32 v19, 0x3fb8aa3b, v44
	v_exp_f32_e32 v19, v19
	v_exp_f32_e32 v1, v1
	v_mul_f32_e32 v2, v19, v2
	v_cvt_pk_bf16_f32 v2, v2, s0
	ds_write_b16 v0, v2 offset:1920
	v_min_f32_e64 v2, -v44, s40
	v_mul_f32_e32 v2, 0x3fb8aa3b, v2
	v_exp_f32_e32 v2, v2
	v_sub_f32_e32 v1, 1.0, v1
	v_mul_f32_e32 v2, v1, v2
	v_cvt_pk_bf16_f32 v2, v2, s0
	ds_write_b16 v0, v2 offset:12160
	v_sub_f32_e32 v2, v38, v44
	v_mul_f32_e32 v2, 0x3fb8aa3b, v2
	v_exp_f32_e32 v2, v2
	v_lshlrev_b32_e32 v44, 2, v26
	v_mul_f32_e32 v1, v1, v2
	v_mul_f32_e32 v2, 0x3fb8aa3b, v39
	v_exp_f32_e32 v2, v2
	v_cvt_pk_bf16_f32 v1, v1, s0
	ds_write_b16 v0, v1 offset:22400
	v_mul_f32_e32 v1, 0x3fb8aa3b, v21
	v_mul_f32_e32 v2, v2, v18
	v_cvt_pk_bf16_f32 v2, v2, s0
	ds_write_b16 v0, v2 offset:2080
	v_min_f32_e64 v2, -v39, s40
	v_exp_f32_e32 v1, v1
	v_mul_f32_e32 v2, 0x3fb8aa3b, v2
	v_exp_f32_e32 v2, v2
	v_sub_f32_e32 v1, 1.0, v1
	v_mul_f32_e32 v2, v1, v2
	v_cvt_pk_bf16_f32 v2, v2, s0
	ds_write_b16 v0, v2 offset:12320
	v_sub_f32_e32 v2, v38, v39
	v_mul_f32_e32 v2, 0x3fb8aa3b, v2
	v_exp_f32_e32 v2, v2
	s_nop 0
	v_mul_f32_e32 v1, v1, v2
	v_mul_f32_e32 v2, 0x3fb8aa3b, v17
	v_exp_f32_e32 v2, v2
	v_cvt_pk_bf16_f32 v1, v1, s0
	ds_write_b16 v0, v1 offset:22560
	v_mul_f32_e32 v1, 0x3fb8aa3b, v16
	v_mul_f32_e32 v2, v2, v37
	v_cvt_pk_bf16_f32 v2, v2, s0
	ds_write_b16 v0, v2 offset:2240
	v_min_f32_e64 v2, -v17, s40
	v_exp_f32_e32 v1, v1
	v_mul_f32_e32 v2, 0x3fb8aa3b, v2
	v_exp_f32_e32 v2, v2
	v_sub_f32_e32 v1, 1.0, v1
	v_mul_f32_e32 v2, v1, v2
	v_cvt_pk_bf16_f32 v2, v2, s0
	ds_write_b16 v0, v2 offset:12480
	v_sub_f32_e32 v2, v38, v17
	v_mul_f32_e32 v2, 0x3fb8aa3b, v2
	v_exp_f32_e32 v2, v2
	s_nop 0
	v_mul_f32_e32 v1, v1, v2
	v_cvt_pk_bf16_f32 v1, v1, s0
	ds_write_b16 v0, v1 offset:22720
	v_add_u32_e32 v0, 32, v27
	v_ashrrev_i32_e32 v1, 3, v24
	ds_write_b32 v0, v43 offset:40960
	v_lshlrev_b32_e32 v0, 4, v24
	v_mad_i64_i32 v[16:17], s[4:5], v1, s48, v[40:41]
	v_and_b32_e32 v2, 0x70, v0
	v_lshl_add_u64 v[16:17], v[16:17], 0, s[22:23]
	v_lshl_add_u64 v[16:17], v[16:17], 0, v[2:3]
	global_load_dwordx4 v[16:19], v[16:17], off offset:1536
	v_add_u32_e32 v0, 32, v2
	v_mad_u64_u32 v[22:23], s[4:5], v1, s42, v[0:1]
	v_add_u32_e32 v1, 0x100, v24
	v_ashrrev_i32_e32 v1, 3, v1
	s_waitcnt vmcnt(0)
	ds_write_b128 v22, v[16:19] offset:30720
	v_mad_i64_i32 v[16:17], s[4:5], v1, s48, v[40:41]
	v_lshl_add_u64 v[16:17], v[16:17], 0, s[22:23]
	v_lshl_add_u64 v[16:17], v[16:17], 0, v[2:3]
	global_load_dwordx4 v[16:19], v[16:17], off offset:1536
	v_mad_u64_u32 v[0:1], s[4:5], v1, s42, v[0:1]
	v_and_b32_e32 v2, 15, v24
	s_add_u32 s4, s12, 0x110000
	s_addc_u32 s5, s13, 0
	v_cmp_lt_u32_e32 vcc, v44, v2
	s_waitcnt vmcnt(0)
	ds_write_b128 v0, v[16:19] offset:30720
	v_or_b32_e32 v0, v20, v2
	v_lshl_add_u32 v0, v26, 8, v0
	v_ashrrev_i32_e32 v1, 31, v0
	v_lshl_add_u64 v[16:17], v[0:1], 2, s[4:5]
	s_waitcnt lgkmcnt(0)
	s_barrier
	global_load_dword v20, v[16:17], off
	v_add_u32_e32 v16, 64, v0
	v_ashrrev_i32_e32 v17, 31, v16
	v_lshl_add_u64 v[16:17], v[16:17], 2, s[4:5]
	global_load_dword v21, v[16:17], off
	v_add_u32_e32 v16, 0x80, v0
	v_ashrrev_i32_e32 v17, 31, v16
	v_lshl_add_u64 v[16:17], v[16:17], 2, s[4:5]
	global_load_dword v22, v[16:17], off
	v_add_u32_e32 v16, 0xc0, v0
	v_ashrrev_i32_e32 v17, 31, v16
	v_lshl_add_u64 v[16:17], v[16:17], 2, s[4:5]
	global_load_dword v23, v[16:17], off
	v_add_u32_e32 v16, 0x400, v0
	v_ashrrev_i32_e32 v17, 31, v16
	v_lshl_add_u64 v[16:17], v[16:17], 2, s[4:5]
	global_load_dword v28, v[16:17], off
	v_add_u32_e32 v16, 0x440, v0
	v_ashrrev_i32_e32 v17, 31, v16
	v_lshl_add_u64 v[16:17], v[16:17], 2, s[4:5]
	global_load_dword v29, v[16:17], off
	v_add_u32_e32 v16, 0x480, v0
	v_ashrrev_i32_e32 v17, 31, v16
	v_lshl_add_u64 v[16:17], v[16:17], 2, s[4:5]
	global_load_dword v34, v[16:17], off
	v_add_u32_e32 v16, 0x4c0, v0
	v_ashrrev_i32_e32 v17, 31, v16
	v_lshl_add_u64 v[16:17], v[16:17], 2, s[4:5]
	global_load_dword v35, v[16:17], off
	v_add_u32_e32 v16, 0x800, v0
	v_ashrrev_i32_e32 v17, 31, v16
	v_lshl_add_u64 v[16:17], v[16:17], 2, s[4:5]
	global_load_dword v36, v[16:17], off
	v_add_u32_e32 v16, 0x840, v0
	v_ashrrev_i32_e32 v17, 31, v16
	v_lshl_add_u64 v[16:17], v[16:17], 2, s[4:5]
	global_load_dword v37, v[16:17], off
	v_add_u32_e32 v16, 0x880, v0
	v_ashrrev_i32_e32 v17, 31, v16
	v_lshl_add_u64 v[16:17], v[16:17], 2, s[4:5]
	global_load_dword v38, v[16:17], off
	v_add_u32_e32 v16, 0x8c0, v0
	v_ashrrev_i32_e32 v17, 31, v16
	v_lshl_add_u64 v[16:17], v[16:17], 2, s[4:5]
	global_load_dword v39, v[16:17], off
	v_add_u32_e32 v16, 0xc00, v0
	v_ashrrev_i32_e32 v17, 31, v16
	v_lshl_add_u64 v[16:17], v[16:17], 2, s[4:5]
	global_load_dword v40, v[16:17], off
	v_add_u32_e32 v16, 0xc40, v0
	v_ashrrev_i32_e32 v17, 31, v16
	v_lshl_add_u64 v[16:17], v[16:17], 2, s[4:5]
	global_load_dword v41, v[16:17], off
	v_add_u32_e32 v16, 0xc80, v0
	v_add_u32_e32 v0, 0xcc0, v0
	v_ashrrev_i32_e32 v17, 31, v16
	v_ashrrev_i32_e32 v1, 31, v0
	v_lshl_add_u64 v[16:17], v[16:17], 2, s[4:5]
	v_lshl_add_u64 v[0:1], v[0:1], 2, s[4:5]
	global_load_dword v42, v[16:17], off
	global_load_dword v43, v[0:1], off
	v_bfe_u32 v0, v24, 2, 2
	v_and_b32_e32 v24, 48, v24
	v_mul_u32_u24_e32 v16, 0x50, v2
	v_add_u32_e32 v61, 32, v24
	v_lshlrev_b32_e32 v25, 1, v16
	v_add_u32_e32 v48, v61, v25
	ds_read_b128 v[16:19], v48 offset:17920
	v_add3_u32 v60, 32, v25, v24
	v_or_b32_e32 v49, v44, v0
	ds_read_b128 v[24:27], v60 offset:7680
	v_mul_u32_u24_e32 v0, 0x50, v49
	v_or_b32_e32 v0, v0, v50
	v_lshlrev_b32_e32 v46, 1, v0
	v_add_u32_e32 v63, v51, v46
	ds_read_b64_tr_b16 v[0:1], v63 offset:38400
	s_waitcnt lgkmcnt(1)
	v_mfma_f32_16x16x32_bf16 v[16:19], v[16:19], v[24:27], 0
	ds_read_b128 v[24:27], v48 offset:17984
	ds_read_b128 v[30:33], v60 offset:7744
	v_sub_u32_e32 v59, v60, v45
	v_add_u32_e32 v62, 32, v46
	s_waitcnt lgkmcnt(0)
	v_mfma_f32_16x16x32_bf16 v[16:19], v[24:27], v[30:33], v[16:19]
	v_or_b32_e32 v24, 1, v44
	v_cmp_lt_u32_e64 s[4:5], v24, v2
	v_or_b32_e32 v24, 2, v44
	v_cmp_lt_u32_e64 s[6:7], v24, v2
	v_or_b32_e32 v24, 3, v44
	v_cmp_lt_u32_e64 s[8:9], v24, v2
	s_nop 1
	v_cndmask_b32_e64 v16, v16, 0, vcc
	v_cndmask_b32_e64 v17, v17, 0, s[4:5]
	v_cndmask_b32_e64 v18, v18, 0, s[6:7]
	v_cndmask_b32_e64 v2, v19, 0, s[8:9]
	v_cvt_pk_bf16_f32 v16, v16, v17
	v_cvt_pk_bf16_f32 v17, v18, v2
	v_mov_b32_e32 v2, v3
	v_add_u32_e32 v44, 0x1800, v59
	v_mov_b32_e32 v18, v3
	v_mov_b32_e32 v19, v3
	s_waitcnt vmcnt(14)
	v_cvt_pk_bf16_f32 v24, v20, v21
	s_waitcnt vmcnt(12)
	v_cvt_pk_bf16_f32 v25, v22, v23
	s_waitcnt vmcnt(10)
	v_cvt_pk_bf16_f32 v26, v28, v29
	ds_read2_b64 v[30:33], v44 offset0:192 offset1:196
	v_mfma_f32_16x16x32_bf16 v[16:19], v[0:3], v[16:19], 0
	v_add_u32_e32 v64, 0x1000, v59
	s_waitcnt vmcnt(8)
	v_cvt_pk_bf16_f32 v27, v34, v35
	s_waitcnt lgkmcnt(0)
	s_nop 0
	v_mfma_f32_16x16x32_bf16 v[16:19], v[24:27], v[30:33], v[16:19]
	ds_read2_b64 v[30:33], v44 offset0:200 offset1:204
	s_waitcnt vmcnt(6)
	v_cvt_pk_bf16_f32 v24, v36, v37
	s_waitcnt vmcnt(4)
	v_cvt_pk_bf16_f32 v25, v38, v39
	s_waitcnt vmcnt(2)
	v_cvt_pk_bf16_f32 v26, v40, v41
	s_waitcnt vmcnt(0)
	v_cvt_pk_bf16_f32 v27, v42, v43
	s_waitcnt lgkmcnt(0)
	s_nop 0
	v_mfma_f32_16x16x32_bf16 v[16:19], v[24:27], v[30:33], v[16:19]
	ds_read_b128 v[24:27], v61 offset:41728
	ds_read_b64_tr_b16 v[32:33], v62 offset:28224
	v_mov_b32_e32 v30, v3
	v_mov_b32_e32 v31, v3
	s_waitcnt lgkmcnt(1)
	v_pk_mul_f32 v[20:21], v[20:21], v[24:25]
	ds_read_b64_tr_b16 v[24:25], v62 offset:28160
	v_pk_mul_f32 v[22:23], v[22:23], v[26:27]
	v_mov_b32_e32 v26, v3
	v_mov_b32_e32 v27, v3
	s_waitcnt lgkmcnt(0)
	s_nop 0
	v_mfma_f32_16x16x32_bf16 v[24:27], v[24:27], v[0:3], v[20:23]
	s_nop 2
	ds_read_b128 v[20:23], v61 offset:41792
	s_waitcnt lgkmcnt(0)
	v_pk_mul_f32 v[20:21], v[28:29], v[20:21]
	ds_read_b64_tr_b16 v[28:29], v62 offset:28192
	v_pk_mul_f32 v[22:23], v[34:35], v[22:23]
	v_mov_b32_e32 v34, v3
	v_mov_b32_e32 v35, v3
	s_waitcnt lgkmcnt(0)
	v_mfma_f32_16x16x32_bf16 v[28:31], v[28:31], v[0:3], v[20:23]
	s_nop 2
	ds_read_b128 v[20:23], v61 offset:41856
	s_waitcnt lgkmcnt(0)
	v_pk_mul_f32 v[20:21], v[36:37], v[20:21]
	v_pk_mul_f32 v[22:23], v[38:39], v[22:23]
	ds_read_b64_tr_b16 v[36:37], v62 offset:28256
	v_mov_b32_e32 v38, v3
	v_mfma_f32_16x16x32_bf16 v[32:35], v[32:35], v[0:3], v[20:23]
	v_mov_b32_e32 v39, v3
	s_nop 1
	ds_read_b128 v[20:23], v61 offset:41920
	s_waitcnt lgkmcnt(0)
	v_pk_mul_f32 v[20:21], v[40:41], v[20:21]
	v_pk_mul_f32 v[22:23], v[42:43], v[22:23]
	s_nop 1
	v_mfma_f32_16x16x32_bf16 v[36:39], v[36:39], v[0:3], v[20:23]
	ds_read_b64_tr_b16 v[0:1], v63 offset:35840
	s_nop 1
	ds_read_b128 v[20:23], v48 offset:15360
	ds_read_b128 v[40:43], v60 offset:5120
	s_waitcnt lgkmcnt(0)
	v_mfma_f32_16x16x32_bf16 v[20:23], v[20:23], v[40:43], 0
	ds_read_b128 v[40:43], v48 offset:15424
	ds_read_b128 v[44:47], v60 offset:5184
	s_waitcnt lgkmcnt(0)
	v_mfma_f32_16x16x32_bf16 v[20:23], v[40:43], v[44:47], v[20:23]
	v_cvt_pk_bf16_f32 v40, v24, v25
	v_cvt_pk_bf16_f32 v41, v26, v27
	v_cvt_pk_bf16_f32 v42, v28, v29
	s_nop 4
	v_cndmask_b32_e64 v2, v20, 0, vcc
	v_cndmask_b32_e64 v20, v21, 0, s[4:5]
	v_cvt_pk_bf16_f32 v20, v2, v20
	v_mov_b32_e32 v2, v3
	v_cndmask_b32_e64 v21, v22, 0, s[6:7]
	v_cndmask_b32_e64 v22, v23, 0, s[8:9]
	v_cvt_pk_bf16_f32 v21, v21, v22
	v_mov_b32_e32 v22, v3
	v_mov_b32_e32 v23, v3
	v_cvt_pk_bf16_f32 v43, v30, v31
	ds_read2_b64 v[44:47], v64 offset0:128 offset1:132
	v_mfma_f32_16x16x32_bf16 v[20:23], v[0:3], v[20:23], 0
	s_waitcnt lgkmcnt(0)
	v_mfma_f32_16x16x32_bf16 v[20:23], v[40:43], v[44:47], v[20:23]
	v_cvt_pk_bf16_f32 v40, v32, v33
	v_cvt_pk_bf16_f32 v41, v34, v35
	v_cvt_pk_bf16_f32 v42, v36, v37
	v_cvt_pk_bf16_f32 v43, v38, v39
	ds_read2_b64 v[44:47], v64 offset0:136 offset1:140
	s_waitcnt lgkmcnt(0)
	v_mfma_f32_16x16x32_bf16 v[20:23], v[40:43], v[44:47], v[20:23]
	ds_read_b128 v[40:43], v61 offset:41472
	s_waitcnt lgkmcnt(0)
	v_pk_mul_f32 v[24:25], v[24:25], v[40:41]
	ds_read_b64_tr_b16 v[40:41], v62 offset:25600
	v_pk_mul_f32 v[26:27], v[26:27], v[42:43]
	v_mov_b32_e32 v42, v3
	v_mov_b32_e32 v43, v3
	s_waitcnt lgkmcnt(0)
	s_nop 0
	v_mfma_f32_16x16x32_bf16 v[40:43], v[40:43], v[0:3], v[24:27]
	s_nop 2
	ds_read_b128 v[24:27], v61 offset:41536
	s_waitcnt lgkmcnt(0)
	v_pk_mul_f32 v[24:25], v[28:29], v[24:25]
	ds_read_b64_tr_b16 v[28:29], v62 offset:25632
	v_pk_mul_f32 v[26:27], v[30:31], v[26:27]
	v_mov_b32_e32 v30, v3
	v_mov_b32_e32 v31, v3
	s_waitcnt lgkmcnt(0)
	s_nop 0
	v_mfma_f32_16x16x32_bf16 v[28:31], v[28:31], v[0:3], v[24:27]
	s_nop 2
	ds_read_b128 v[24:27], v61 offset:41600
	s_waitcnt lgkmcnt(0)
	v_pk_mul_f32 v[24:25], v[32:33], v[24:25]
	ds_read_b64_tr_b16 v[32:33], v62 offset:25664
	v_pk_mul_f32 v[26:27], v[34:35], v[26:27]
	v_mov_b32_e32 v34, v3
	v_mov_b32_e32 v35, v3
	s_waitcnt lgkmcnt(0)
	s_nop 0
	v_mfma_f32_16x16x32_bf16 v[32:35], v[32:35], v[0:3], v[24:27]
	s_nop 2
	ds_read_b128 v[24:27], v61 offset:41664
	s_waitcnt lgkmcnt(0)
	v_pk_mul_f32 v[24:25], v[36:37], v[24:25]
	ds_read_b64_tr_b16 v[36:37], v62 offset:25696
	v_pk_mul_f32 v[26:27], v[38:39], v[26:27]
	v_mov_b32_e32 v38, v3
	v_mov_b32_e32 v39, v3
	s_waitcnt lgkmcnt(0)
	s_nop 0
	v_mfma_f32_16x16x32_bf16 v[44:47], v[36:39], v[0:3], v[24:27]
	ds_read_b64_tr_b16 v[0:1], v63 offset:33280
	s_nop 1
	ds_read_b128 v[24:27], v48 offset:12800
	ds_read_b128 v[36:39], v60 offset:2560
	v_add_u32_e32 v63, 0x800, v59
	s_waitcnt lgkmcnt(0)
	v_mfma_f32_16x16x32_bf16 v[24:27], v[24:27], v[36:39], 0
	ds_read_b128 v[36:39], v48 offset:12864
	ds_read_b128 v[64:67], v60 offset:2624
	s_waitcnt lgkmcnt(0)
	v_mfma_f32_16x16x32_bf16 v[24:27], v[36:39], v[64:67], v[24:27]
	v_cvt_pk_bf16_f32 v36, v40, v41
	v_cvt_pk_bf16_f32 v37, v42, v43
	v_cvt_pk_bf16_f32 v38, v28, v29
	s_nop 4
	v_cndmask_b32_e64 v2, v24, 0, vcc
	v_cndmask_b32_e64 v24, v25, 0, s[4:5]
	v_cvt_pk_bf16_f32 v24, v2, v24
	v_mov_b32_e32 v2, v3
	v_cndmask_b32_e64 v25, v26, 0, s[6:7]
	v_cndmask_b32_e64 v26, v27, 0, s[8:9]
	v_cvt_pk_bf16_f32 v25, v25, v26
	v_mov_b32_e32 v26, v3
	v_mov_b32_e32 v27, v3
	v_cvt_pk_bf16_f32 v39, v30, v31
	ds_read2_b64 v[64:67], v63 offset0:64 offset1:68
	v_mfma_f32_16x16x32_bf16 v[24:27], v[0:3], v[24:27], 0
	s_waitcnt lgkmcnt(0)
	v_mfma_f32_16x16x32_bf16 v[24:27], v[36:39], v[64:67], v[24:27]
	v_cvt_pk_bf16_f32 v36, v32, v33
	v_cvt_pk_bf16_f32 v37, v34, v35
	v_cvt_pk_bf16_f32 v38, v44, v45
	v_cvt_pk_bf16_f32 v39, v46, v47
	ds_read2_b64 v[64:67], v63 offset0:72 offset1:76
	s_waitcnt lgkmcnt(0)
	v_mfma_f32_16x16x32_bf16 v[24:27], v[36:39], v[64:67], v[24:27]
	ds_read_b128 v[36:39], v61 offset:41216
	v_mov_b32_e32 v66, v3
	v_mov_b32_e32 v67, v3
	s_waitcnt lgkmcnt(0)
	v_pk_mul_f32 v[38:39], v[42:43], v[38:39]
	v_mov_b32_e32 v42, v3
	v_mov_b32_e32 v43, v3
	v_pk_mul_f32 v[36:37], v[40:41], v[36:37]
	ds_read_b64_tr_b16 v[40:41], v62 offset:23040
	ds_read_b64_tr_b16 v[64:65], v62 offset:23072
	s_waitcnt lgkmcnt(1)
	v_mfma_f32_16x16x32_bf16 v[36:39], v[40:43], v[0:3], v[36:39]
	ds_read_b128 v[40:43], v61 offset:41280
	s_waitcnt lgkmcnt(0)
	v_pk_mul_f32 v[30:31], v[30:31], v[42:43]
	v_pk_mul_f32 v[28:29], v[28:29], v[40:41]
	s_nop 3
	v_cvt_pk_bf16_f32 v36, v36, v37
	v_cvt_pk_bf16_f32 v37, v38, v39
	v_mfma_f32_16x16x32_bf16 v[40:43], v[64:67], v[0:3], v[28:31]
	s_nop 2
	ds_read_b128 v[28:31], v61 offset:41344
	s_waitcnt lgkmcnt(0)
	v_pk_mul_f32 v[28:29], v[32:33], v[28:29]
	ds_read_b64_tr_b16 v[32:33], v62 offset:23104
	v_pk_mul_f32 v[30:31], v[34:35], v[30:31]
	v_mov_b32_e32 v34, v3
	v_mov_b32_e32 v35, v3
	v_cvt_pk_bf16_f32 v38, v40, v41
	v_cvt_pk_bf16_f32 v39, v42, v43
	s_waitcnt lgkmcnt(0)
	v_mfma_f32_16x16x32_bf16 v[28:31], v[32:35], v[0:3], v[28:31]
	ds_read_b128 v[32:35], v61 offset:41408
	s_waitcnt lgkmcnt(0)
	v_pk_mul_f32 v[32:33], v[44:45], v[32:33]
	ds_read_b64_tr_b16 v[44:45], v62 offset:23136
	v_pk_mul_f32 v[34:35], v[46:47], v[34:35]
	v_mov_b32_e32 v46, v3
	v_mov_b32_e32 v47, v3
	s_nop 0
	v_cvt_pk_bf16_f32 v28, v28, v29
	v_cvt_pk_bf16_f32 v29, v30, v31
	s_waitcnt lgkmcnt(0)
	v_mfma_f32_16x16x32_bf16 v[32:35], v[44:47], v[0:3], v[32:35]
	v_mul_u32_u24_e32 v0, 0xa0, v49
	v_lshlrev_b32_e32 v1, 1, v50
	v_add3_u32 v0, v51, v0, v1
	ds_read_b64_tr_b16 v[0:1], v0 offset:30720
	ds_read_b128 v[44:47], v48 offset:10240
	ds_read_b128 v[62:65], v60
	s_waitcnt lgkmcnt(0)
	v_mfma_f32_16x16x32_bf16 v[44:47], v[44:47], v[62:65], 0
	ds_read_b128 v[48:51], v48 offset:10304
	ds_read_b128 v[60:63], v60 offset:64
	ds_read2_b64 v[40:43], v59 offset1:4
	v_cvt_pk_bf16_f32 v30, v32, v33
	s_waitcnt lgkmcnt(1)
	v_mfma_f32_16x16x32_bf16 v[44:47], v[48:51], v[60:63], v[44:47]
	v_cvt_pk_bf16_f32 v31, v34, v35
	ds_read2_b64 v[32:35], v59 offset0:8 offset1:12
	s_nop 5
	v_cndmask_b32_e64 v2, v44, 0, vcc
	v_cndmask_b32_e64 v44, v45, 0, s[4:5]
	v_cvt_pk_bf16_f32 v44, v2, v44
	v_mov_b32_e32 v2, v3
	v_cndmask_b32_e64 v45, v46, 0, s[6:7]
	v_cndmask_b32_e64 v46, v47, 0, s[8:9]
	v_cvt_pk_bf16_f32 v45, v45, v46
	v_mov_b32_e32 v46, v3
	v_mov_b32_e32 v47, v3
	v_cmp_eq_u32_e32 vcc, 0, v57
	s_nop 0
	v_mfma_f32_16x16x32_bf16 v[44:47], v[0:3], v[44:47], 0
	v_and_b32_e32 v0, 0x3fffffc0, v58
	v_lshlrev_b32_e32 v0, 2, v0
	v_lshlrev_b32_e32 v1, 2, v56
	s_waitcnt lgkmcnt(1)
	v_mfma_f32_16x16x32_bf16 v[36:39], v[36:39], v[40:43], v[44:47]
	v_add3_u32 v2, 32, v0, v1
	v_mov_b32_e32 v1, v222
	s_waitcnt lgkmcnt(0)
	v_mfma_f32_16x16x32_bf16 v[30:33], v[28:31], v[32:35], v[36:39]
	v_lshlrev_b32_e32 v1, 2, v1
	v_bitop3_b32 v1, v1, 64, v229 bitop3:0x6c
	s_nop 5
	v_pk_add_f32 v[30:31], v[54:55], v[30:31]
	v_pk_add_f32 v[28:29], v[52:53], v[32:33]
	v_mul_f32_e32 v0, v31, v31
	v_fmac_f32_e32 v0, v30, v30
	v_fmac_f32_e32 v0, v28, v28
	v_fmac_f32_e32 v0, v29, v29
	ds_bpermute_b32 v1, v1, v0
	s_waitcnt lgkmcnt(0)
	v_add_f32_e32 v0, v0, v1
	v_mov_b32_e32 v1, v222
	s_nop 0
	v_lshlrev_b32_e32 v1, 2, v1
	v_bitop3_b32 v1, v1, s18, v229 bitop3:0x6c
	ds_bpermute_b32 v1, v1, v0
	s_and_saveexec_b64 s[4:5], vcc
	s_cbranch_execz .LBB0_906
	s_waitcnt lgkmcnt(0)
	v_add_f32_e32 v0, v0, v1
	ds_write_b32 v2, v0 offset:41984
